# v5: flat->global, ss loads hoisted in 6 epilogues, GQA partial-softmax exps moved into the PV MFMA shadow, residual-epilogue row loads issued together
# speedup vs baseline: 1.0037x; 1.0037x over previous
; __device__ __forceinline__ unsigned cvt_pk_bf16(float lo, float hi) { f32x2 v = {lo, hi}; bf16x2_t_ b = __builtin_convertvector(v, bf16x2_t_); return __builtin_bit_cast(unsigned, b); }
;     __device__ __forceinline__ void operator()(const Acc& acc, const Unit& u, int wr, int wc, int fr, int fq) const {
;     ...
;         const float* const R = Rp_ ? (u.pm * BM < MP ? Rp_ : Rs_ - (size_t)MP * DM) : X;
;         const int row0 = u.pm * BM + wr * 64 + fr, col0 = u.pn * BM + wc * 32 + 8 * fq; const int lane = fr + 16 * fq;
;         f32x4 gv[2][2];
;         if (gnext) {
; #pragma unroll
;             for (int bj = 0; bj < 2; ++bj)
; #pragma unroll
;                 for (int n = 0; n < 2; ++n) gv[bj][n] = *(const f32x4*)(gnext + col0 + bj * HALF + 4 * n); }
; #pragma unroll
;         for (int ai = 0; ai < 2; ++ai)
; #pragma unroll
;             for (int m = 0; m < 4; ++m) { const int row = row0 + ai * HALF + m * 16; float* rowp = X + (size_t)row * DM + col0; float sq = 0.f;
; #pragma unroll
;                 for (int bj = 0; bj < 2; ++bj) { f32x4* p0 = (f32x4*)(rowp + bj * HALF); const f32x4* r0 = (const f32x4*)(R + (size_t)row * DM + col0 + bj * HALF); const f32x4 o0 = r0[0] + acc[ai][bj][m][0] * alpha, o1 = r0[1] + acc[ai][bj][m][1] * alpha; p0[0] = o0; p0[1] = o1;
;                     if (gnext) { sq += (o0[0] * o0[0] + o0[1] * o0[1]) + (o0[2] * o0[2] + o0[3] * o0[3]) + (o1[0] * o1[0] + o1[1] * o1[1]) + (o1[2] * o1[2] + o1[3] * o1[3]);
;                         const f32x4 y0 = o0 * gv[bj][0], y1 = o1 * gv[bj][1];
;                         u32x4 w; w.x = cvt_pk_bf16(y0[0], y0[1]); w.y = cvt_pk_bf16(y0[2], y0[3]); w.z = cvt_pk_bf16(y1[0], y1[1]); w.w = cvt_pk_bf16(y1[2], y1[3]);
;                         *(u32x4*)(XNo + (size_t)row * DM + col0 + bj * HALF) = w; } }
.LBB0_317:
	s_cmpk_lt_i32 s38, 0x100
	v_readlane_b32 s12, v255, 12
	s_cselect_b32 s10, s56, s80
	s_cselect_b32 s11, s57, s90
	s_and_b64 s[6:7], s[82:83], exec
	v_readlane_b32 s13, v255, 13
	s_cselect_b32 s7, s13, s11
	s_cselect_b32 s6, s12, s10
	s_lshl_b32 s88, s38, 8
	v_readlane_b32 s8, v254, 1
	v_and_b32_e32 v166, 15, v165
	s_add_i32 s10, s88, s8
	v_or_b32_e32 v144, s10, v166
	v_lshlrev_b64 v[150:151], 2, v[146:147]
	v_ashrrev_i32_e32 v145, 31, v144
	v_lshl_add_u64 v[148:149], s[12:13], 0, v[150:151]
	v_lshl_add_u64 v[150:151], s[6:7], 0, v[150:151]
	v_lshlrev_b64 v[152:153], 12, v[144:145]
	v_lshl_add_u64 v[156:157], v[150:151], 0, v[152:153]
	global_load_dwordx4 v[202:205], v[156:157], off
	global_load_dwordx4 v[206:209], v[156:157], off offset:16
	global_load_dwordx4 v[210:213], v[156:157], off offset:512
	global_load_dwordx4 v[214:217], v[156:157], off offset:528
	v_lshl_add_u64 v[146:147], v[146:147], 1, s[62:63]
	v_lshl_add_u64 v[154:155], v[148:149], 0, v[152:153]
	v_lshlrev_b64 v[152:153], 11, v[144:145]
	v_lshl_add_u64 v[152:153], v[146:147], 0, v[152:153]
	s_and_b64 vcc, exec, s[42:43]
	s_waitcnt vmcnt(0) lgkmcnt(0)
	s_nop 1
	v_mov_b64_e32 v[168:169], v[202:203]
	v_mov_b64_e32 v[170:171], v[204:205]
	v_pk_fma_f32 v[142:143], v[142:143], 0.5, v[170:171] op_sel_hi:[1,0,1]
	v_pk_fma_f32 v[140:141], v[140:141], 0.5, v[168:169] op_sel_hi:[1,0,1]
	s_nop 1
	v_mov_b64_e32 v[168:169], v[206:207]
	v_mov_b64_e32 v[170:171], v[208:209]
	s_waitcnt lgkmcnt(0)
	v_pk_fma_f32 v[138:139], v[138:139], 0.5, v[170:171] op_sel_hi:[1,0,1]
	v_pk_fma_f32 v[136:137], v[136:137], 0.5, v[168:169] op_sel_hi:[1,0,1]
	global_store_dwordx4 v[154:155], v[140:143], off
	global_store_dwordx4 v[154:155], v[136:139], off offset:16
	s_cbranch_vccnz .LBB0_319
	v_pk_mul_f32 v[168:169], v[142:143], v[142:143]
	v_pk_mul_f32 v[170:171], v[140:141], v[140:141]
	v_pk_mul_f32 v[142:143], v[66:67], v[142:143]
	v_pk_mov_b32 v[172:173], v[170:171], v[168:169] op_sel:[1,0]
	v_mov_b32_e32 v171, v169
	v_pk_add_f32 v[168:169], v[172:173], v[170:171]
	v_pk_mul_f32 v[170:171], v[138:139], v[138:139]
	v_pk_mul_f32 v[172:173], v[136:137], v[136:137]
	v_mov_b32_e32 v174, v170
	v_mov_b32_e32 v175, v172
	v_mov_b32_e32 v172, v171
	v_pk_add_f32 v[170:171], v[174:175], v[172:173]
	v_add_f32_e32 v145, v168, v169
	v_add_f32_e32 v145, v145, v171
	v_pk_mul_f32 v[140:141], v[64:65], v[140:141]
	v_pk_mul_f32 v[168:169], v[58:59], v[138:139]
	v_pk_mul_f32 v[138:139], v[56:57], v[136:137]
	v_add_f32_e32 v145, v170, v145
	v_cvt_pk_bf16_f32 v136, v140, v141
	v_cvt_pk_bf16_f32 v137, v142, v143
	v_cvt_pk_bf16_f32 v138, v138, v139
	v_cvt_pk_bf16_f32 v139, v168, v169
	global_store_dwordx4 v[152:153], v[136:139], off
	s_branch .LBB0_320

; __device__ __forceinline__ unsigned cvt_pk_bf16(float lo, float hi) { f32x2 v = {lo, hi}; bf16x2_t_ b = __builtin_convertvector(v, bf16x2_t_); return __builtin_bit_cast(unsigned, b); }
; __device__ __forceinline__ float shfl_xor_l(float v, int o, int lane) { return __int_as_float(__builtin_amdgcn_ds_bpermute((lane ^ o) << 2, __float_as_int(v))); }
;     __device__ __forceinline__ void operator()(const Acc& acc, const Unit& u, int wr, int wc, int fr, int fq) const {
;     ...
;                 for (int bj = 0; bj < 2; ++bj) { f32x4* p0 = (f32x4*)(rowp + bj * HALF); const f32x4* r0 = (const f32x4*)(R + (size_t)row * DM + col0 + bj * HALF); const f32x4 o0 = r0[0] + acc[ai][bj][m][0] * alpha, o1 = r0[1] + acc[ai][bj][m][1] * alpha; p0[0] = o0; p0[1] = o1;
;                     if (gnext) { sq += (o0[0] * o0[0] + o0[1] * o0[1]) + (o0[2] * o0[2] + o0[3] * o0[3]) + (o1[0] * o1[0] + o1[1] * o1[1]) + (o1[2] * o1[2] + o1[3] * o1[3]);
;                         const f32x4 y0 = o0 * gv[bj][0], y1 = o1 * gv[bj][1];
;                         u32x4 w; w.x = cvt_pk_bf16(y0[0], y0[1]); w.y = cvt_pk_bf16(y0[2], y0[3]); w.z = cvt_pk_bf16(y1[0], y1[1]); w.w = cvt_pk_bf16(y1[2], y1[3]);
;                         *(u32x4*)(XNo + (size_t)row * DM + col0 + bj * HALF) = w; } }
;                 if (gnext) { sq += shfl_xor_l(sq, 16, lane); sq += shfl_xor_l(sq, 32, lane); if (fq == 0) part[wc * 256 + ai * HALF + wr * 64 + m * 16 + fr] = sq; }
.LBB0_320:
	s_nop 1
	v_mov_b64_e32 v[140:141], v[210:211]
	v_mov_b64_e32 v[142:143], v[212:213]
	v_lshlrev_b32_e32 v136, 2, v165
	v_xor_b32_e32 v138, 64, v136
	v_xor_b32_e32 v137, 0x80, v136
	v_cmp_gt_u32_e64 s[44:45], 16, v165
	v_lshl_add_u32 v136, v166, 2, s94
	s_and_b64 vcc, exec, s[42:43]
	s_waitcnt lgkmcnt(0)
	v_pk_fma_f32 v[134:135], v[134:135], 0.5, v[142:143] op_sel_hi:[1,0,1]
	v_pk_fma_f32 v[132:133], v[132:133], 0.5, v[140:141] op_sel_hi:[1,0,1]
	s_nop 1
	v_mov_b64_e32 v[140:141], v[214:215]
	v_mov_b64_e32 v[142:143], v[216:217]
	s_waitcnt lgkmcnt(0)
	v_pk_fma_f32 v[130:131], v[130:131], 0.5, v[142:143] op_sel_hi:[1,0,1]
	v_pk_fma_f32 v[128:129], v[128:129], 0.5, v[140:141] op_sel_hi:[1,0,1]
	global_store_dwordx4 v[154:155], v[132:135], off offset:512
	global_store_dwordx4 v[154:155], v[128:131], off offset:528
	s_cbranch_vccnz .LBB0_324
	v_mul_f32_e32 v139, v133, v133
	v_mul_f32_e32 v140, v135, v135
	v_fmac_f32_e32 v139, v132, v132
	v_fmac_f32_e32 v140, v134, v134
	v_add_f32_e32 v139, v139, v140
	v_mul_f32_e32 v140, v129, v129
	v_fmac_f32_e32 v140, v128, v128
	v_add_f32_e32 v139, v139, v140
	v_mul_f32_e32 v140, v131, v131
	v_fmac_f32_e32 v140, v130, v130
	v_add_f32_e32 v139, v140, v139
	v_add_f32_e32 v139, v145, v139
	ds_bpermute_b32 v145, v138, v139
	v_pk_mul_f32 v[142:143], v[44:45], v[128:129]
	v_pk_mul_f32 v[134:135], v[50:51], v[134:135]
	v_pk_mul_f32 v[132:133], v[48:49], v[132:133]
	v_pk_mul_f32 v[140:141], v[46:47], v[130:131]
	s_waitcnt lgkmcnt(0)
	v_add_f32_e32 v128, v139, v145
	ds_bpermute_b32 v129, v137, v128
	v_cvt_pk_bf16_f32 v130, v132, v133
	v_cvt_pk_bf16_f32 v131, v134, v135
	v_cvt_pk_bf16_f32 v132, v142, v143
	v_cvt_pk_bf16_f32 v133, v140, v141
	global_store_dwordx4 v[152:153], v[130:133], off offset:256
	s_and_saveexec_b64 s[6:7], s[44:45]
	s_cbranch_execz .LBB0_323
	s_waitcnt lgkmcnt(0)
	v_add_f32_e32 v128, v128, v129
	ds_write_b32 v136, v128

; __device__ __forceinline__ unsigned cvt_pk_bf16(float lo, float hi) { f32x2 v = {lo, hi}; bf16x2_t_ b = __builtin_convertvector(v, bf16x2_t_); return __builtin_bit_cast(unsigned, b); }
;     __device__ __forceinline__ void operator()(const Acc& acc, const Unit& u, int wr, int wc, int fr, int fq) const {
;     ...
;             for (int m = 0; m < 4; ++m) { const int row = row0 + ai * HALF + m * 16; float* rowp = X + (size_t)row * DM + col0; float sq = 0.f;
; #pragma unroll
;                 for (int bj = 0; bj < 2; ++bj) { f32x4* p0 = (f32x4*)(rowp + bj * HALF); const f32x4* r0 = (const f32x4*)(R + (size_t)row * DM + col0 + bj * HALF); const f32x4 o0 = r0[0] + acc[ai][bj][m][0] * alpha, o1 = r0[1] + acc[ai][bj][m][1] * alpha; p0[0] = o0; p0[1] = o1;
;                     if (gnext) { sq += (o0[0] * o0[0] + o0[1] * o0[1]) + (o0[2] * o0[2] + o0[3] * o0[3]) + (o1[0] * o1[0] + o1[1] * o1[1]) + (o1[2] * o1[2] + o1[3] * o1[3]);
;                         const f32x4 y0 = o0 * gv[bj][0], y1 = o1 * gv[bj][1];
;                         u32x4 w; w.x = cvt_pk_bf16(y0[0], y0[1]); w.y = cvt_pk_bf16(y0[2], y0[3]); w.z = cvt_pk_bf16(y1[0], y1[1]); w.w = cvt_pk_bf16(y1[2], y1[3]);
;                         *(u32x4*)(XNo + (size_t)row * DM + col0 + bj * HALF) = w; } }
.LBB0_324:
	s_nop 0
	v_or_b32_e32 v128, 16, v144
	s_waitcnt lgkmcnt(0)
	v_ashrrev_i32_e32 v129, 31, v128
	v_lshlrev_b64 v[132:133], 12, v[128:129]
	v_lshl_add_u64 v[130:131], v[148:149], 0, v[132:133]
	v_lshl_add_u64 v[132:133], v[150:151], 0, v[132:133]
	global_load_dwordx4 v[202:205], v[132:133], off
	global_load_dwordx4 v[206:209], v[132:133], off offset:16
	global_load_dwordx4 v[210:213], v[132:133], off offset:512
	global_load_dwordx4 v[214:217], v[132:133], off offset:528
	v_lshlrev_b64 v[128:129], 11, v[128:129]
	v_lshl_add_u64 v[128:129], v[146:147], 0, v[128:129]
	s_and_b64 vcc, exec, s[42:43]
	s_waitcnt vmcnt(0) lgkmcnt(0)
	s_nop 1
	v_mov_b64_e32 v[140:141], v[202:203]
	v_mov_b64_e32 v[142:143], v[204:205]
	v_pk_fma_f32 v[126:127], v[126:127], 0.5, v[142:143] op_sel_hi:[1,0,1]
	v_pk_fma_f32 v[124:125], v[124:125], 0.5, v[140:141] op_sel_hi:[1,0,1]
	s_nop 1
	v_mov_b64_e32 v[140:141], v[206:207]
	v_mov_b64_e32 v[142:143], v[208:209]
	s_waitcnt lgkmcnt(0)
	v_pk_fma_f32 v[122:123], v[122:123], 0.5, v[142:143] op_sel_hi:[1,0,1]
	v_pk_fma_f32 v[120:121], v[120:121], 0.5, v[140:141] op_sel_hi:[1,0,1]
	global_store_dwordx4 v[130:131], v[124:127], off
	global_store_dwordx4 v[130:131], v[120:123], off offset:16
	s_cbranch_vccnz .LBB0_326
	v_pk_mul_f32 v[134:135], v[126:127], v[126:127]
	v_pk_mul_f32 v[140:141], v[124:125], v[124:125]
	v_pk_mul_f32 v[126:127], v[66:67], v[126:127]
	v_pk_mov_b32 v[142:143], v[140:141], v[134:135] op_sel:[1,0]
	v_mov_b32_e32 v141, v135
	v_pk_add_f32 v[134:135], v[142:143], v[140:141]
	v_pk_mul_f32 v[140:141], v[122:123], v[122:123]
	v_pk_mul_f32 v[142:143], v[120:121], v[120:121]
	v_mov_b32_e32 v152, v140
	v_mov_b32_e32 v153, v142
	v_mov_b32_e32 v142, v141
	v_pk_add_f32 v[140:141], v[152:153], v[142:143]
	v_add_f32_e32 v134, v134, v135
	v_add_f32_e32 v134, v134, v141
	v_add_f32_e32 v134, v140, v134
	v_pk_mul_f32 v[124:125], v[64:65], v[124:125]
	v_pk_mul_f32 v[140:141], v[58:59], v[122:123]
	v_pk_mul_f32 v[122:123], v[56:57], v[120:121]
	v_cvt_pk_bf16_f32 v120, v124, v125
	v_cvt_pk_bf16_f32 v121, v126, v127
	v_cvt_pk_bf16_f32 v122, v122, v123
	v_cvt_pk_bf16_f32 v123, v140, v141
	global_store_dwordx4 v[128:129], v[120:123], off
	s_branch .LBB0_327

; __device__ __forceinline__ unsigned cvt_pk_bf16(float lo, float hi) { f32x2 v = {lo, hi}; bf16x2_t_ b = __builtin_convertvector(v, bf16x2_t_); return __builtin_bit_cast(unsigned, b); }
; __device__ __forceinline__ float shfl_xor_l(float v, int o, int lane) { return __int_as_float(__builtin_amdgcn_ds_bpermute((lane ^ o) << 2, __float_as_int(v))); }
;     __device__ __forceinline__ void operator()(const Acc& acc, const Unit& u, int wr, int wc, int fr, int fq) const {
;     ...
;                 for (int bj = 0; bj < 2; ++bj) { f32x4* p0 = (f32x4*)(rowp + bj * HALF); const f32x4* r0 = (const f32x4*)(R + (size_t)row * DM + col0 + bj * HALF); const f32x4 o0 = r0[0] + acc[ai][bj][m][0] * alpha, o1 = r0[1] + acc[ai][bj][m][1] * alpha; p0[0] = o0; p0[1] = o1;
;                     if (gnext) { sq += (o0[0] * o0[0] + o0[1] * o0[1]) + (o0[2] * o0[2] + o0[3] * o0[3]) + (o1[0] * o1[0] + o1[1] * o1[1]) + (o1[2] * o1[2] + o1[3] * o1[3]);
;                         const f32x4 y0 = o0 * gv[bj][0], y1 = o1 * gv[bj][1];
;                         u32x4 w; w.x = cvt_pk_bf16(y0[0], y0[1]); w.y = cvt_pk_bf16(y0[2], y0[3]); w.z = cvt_pk_bf16(y1[0], y1[1]); w.w = cvt_pk_bf16(y1[2], y1[3]);
;                         *(u32x4*)(XNo + (size_t)row * DM + col0 + bj * HALF) = w; } }
;                 if (gnext) { sq += shfl_xor_l(sq, 16, lane); sq += shfl_xor_l(sq, 32, lane); if (fq == 0) part[wc * 256 + ai * HALF + wr * 64 + m * 16 + fr] = sq; }
.LBB0_327:
	s_nop 1
	v_mov_b64_e32 v[120:121], v[210:211]
	v_mov_b64_e32 v[122:123], v[212:213]
	s_and_b64 vcc, exec, s[42:43]
	s_waitcnt lgkmcnt(0)
	v_pk_fma_f32 v[118:119], v[118:119], 0.5, v[122:123] op_sel_hi:[1,0,1]
	v_pk_fma_f32 v[116:117], v[116:117], 0.5, v[120:121] op_sel_hi:[1,0,1]
	s_nop 1
	v_mov_b64_e32 v[120:121], v[214:215]
	v_mov_b64_e32 v[122:123], v[216:217]
	s_waitcnt lgkmcnt(0)
	v_pk_fma_f32 v[114:115], v[114:115], 0.5, v[122:123] op_sel_hi:[1,0,1]
	v_pk_fma_f32 v[112:113], v[112:113], 0.5, v[120:121] op_sel_hi:[1,0,1]
	global_store_dwordx4 v[130:131], v[116:119], off offset:512
	global_store_dwordx4 v[130:131], v[112:115], off offset:528
	s_cbranch_vccnz .LBB0_331
	v_mul_f32_e32 v120, v117, v117
	v_mul_f32_e32 v121, v119, v119
	v_fmac_f32_e32 v120, v116, v116
	v_fmac_f32_e32 v121, v118, v118
	v_add_f32_e32 v120, v120, v121
	v_mul_f32_e32 v121, v113, v113
	v_fmac_f32_e32 v121, v112, v112
	v_add_f32_e32 v120, v120, v121
	v_mul_f32_e32 v121, v115, v115
	v_fmac_f32_e32 v121, v114, v114
	v_add_f32_e32 v120, v121, v120
	v_add_f32_e32 v124, v134, v120
	ds_bpermute_b32 v125, v138, v124
	v_pk_mul_f32 v[122:123], v[44:45], v[112:113]
	v_pk_mul_f32 v[118:119], v[50:51], v[118:119]
	v_pk_mul_f32 v[116:117], v[48:49], v[116:117]
	v_pk_mul_f32 v[120:121], v[46:47], v[114:115]
	s_waitcnt lgkmcnt(0)
	v_add_f32_e32 v112, v124, v125
	ds_bpermute_b32 v113, v137, v112
	v_cvt_pk_bf16_f32 v114, v116, v117
	v_cvt_pk_bf16_f32 v115, v118, v119
	v_cvt_pk_bf16_f32 v116, v122, v123
	v_cvt_pk_bf16_f32 v117, v120, v121
	global_store_dwordx4 v[128:129], v[114:117], off offset:256
	s_and_saveexec_b64 s[6:7], s[44:45]
	s_cbranch_execz .LBB0_330
	s_waitcnt lgkmcnt(0)
	v_add_f32_e32 v112, v112, v113
	ds_write_b32 v136, v112 offset:64

; __device__ __forceinline__ unsigned cvt_pk_bf16(float lo, float hi) { f32x2 v = {lo, hi}; bf16x2_t_ b = __builtin_convertvector(v, bf16x2_t_); return __builtin_bit_cast(unsigned, b); }
;     __device__ __forceinline__ void operator()(const Acc& acc, const Unit& u, int wr, int wc, int fr, int fq) const {
;     ...
;             for (int m = 0; m < 4; ++m) { const int row = row0 + ai * HALF + m * 16; float* rowp = X + (size_t)row * DM + col0; float sq = 0.f;
; #pragma unroll
;                 for (int bj = 0; bj < 2; ++bj) { f32x4* p0 = (f32x4*)(rowp + bj * HALF); const f32x4* r0 = (const f32x4*)(R + (size_t)row * DM + col0 + bj * HALF); const f32x4 o0 = r0[0] + acc[ai][bj][m][0] * alpha, o1 = r0[1] + acc[ai][bj][m][1] * alpha; p0[0] = o0; p0[1] = o1;
;                     if (gnext) { sq += (o0[0] * o0[0] + o0[1] * o0[1]) + (o0[2] * o0[2] + o0[3] * o0[3]) + (o1[0] * o1[0] + o1[1] * o1[1]) + (o1[2] * o1[2] + o1[3] * o1[3]);
;                         const f32x4 y0 = o0 * gv[bj][0], y1 = o1 * gv[bj][1];
;                         u32x4 w; w.x = cvt_pk_bf16(y0[0], y0[1]); w.y = cvt_pk_bf16(y0[2], y0[3]); w.z = cvt_pk_bf16(y1[0], y1[1]); w.w = cvt_pk_bf16(y1[2], y1[3]);
;                         *(u32x4*)(XNo + (size_t)row * DM + col0 + bj * HALF) = w; } }
.LBB0_331:
	s_nop 0
	v_or_b32_e32 v112, 32, v144
	s_waitcnt lgkmcnt(0)
	v_ashrrev_i32_e32 v113, 31, v112
	v_lshlrev_b64 v[116:117], 12, v[112:113]
	v_lshl_add_u64 v[114:115], v[148:149], 0, v[116:117]
	v_lshl_add_u64 v[116:117], v[150:151], 0, v[116:117]
	global_load_dwordx4 v[202:205], v[116:117], off
	global_load_dwordx4 v[206:209], v[116:117], off offset:16
	global_load_dwordx4 v[210:213], v[116:117], off offset:512
	global_load_dwordx4 v[214:217], v[116:117], off offset:528
	v_lshlrev_b64 v[112:113], 11, v[112:113]
	v_lshl_add_u64 v[112:113], v[146:147], 0, v[112:113]
	s_and_b64 vcc, exec, s[42:43]
	s_waitcnt vmcnt(0) lgkmcnt(0)
	s_nop 1
	v_mov_b64_e32 v[118:119], v[202:203]
	v_mov_b64_e32 v[120:121], v[204:205]
	v_pk_fma_f32 v[110:111], v[110:111], 0.5, v[120:121] op_sel_hi:[1,0,1]
	v_pk_fma_f32 v[108:109], v[108:109], 0.5, v[118:119] op_sel_hi:[1,0,1]
	s_nop 1
	v_mov_b64_e32 v[118:119], v[206:207]
	v_mov_b64_e32 v[120:121], v[208:209]
	s_waitcnt lgkmcnt(0)
	v_pk_fma_f32 v[106:107], v[106:107], 0.5, v[120:121] op_sel_hi:[1,0,1]
	v_pk_fma_f32 v[104:105], v[104:105], 0.5, v[118:119] op_sel_hi:[1,0,1]
	global_store_dwordx4 v[114:115], v[108:111], off
	global_store_dwordx4 v[114:115], v[104:107], off offset:16
	s_cbranch_vccnz .LBB0_333
	v_pk_mul_f32 v[118:119], v[110:111], v[110:111]
	v_pk_mul_f32 v[120:121], v[108:109], v[108:109]
	v_pk_mul_f32 v[110:111], v[66:67], v[110:111]
	v_pk_mov_b32 v[122:123], v[120:121], v[118:119] op_sel:[1,0]
	v_mov_b32_e32 v121, v119
	v_pk_add_f32 v[118:119], v[122:123], v[120:121]
	v_pk_mul_f32 v[120:121], v[106:107], v[106:107]
	v_pk_mul_f32 v[122:123], v[104:105], v[104:105]
	v_mov_b32_e32 v124, v120
	v_mov_b32_e32 v125, v122
	v_mov_b32_e32 v122, v121
	v_pk_add_f32 v[120:121], v[124:125], v[122:123]
	v_add_f32_e32 v118, v118, v119
	v_add_f32_e32 v118, v118, v121
	v_add_f32_e32 v118, v120, v118
	v_pk_mul_f32 v[108:109], v[64:65], v[108:109]
	v_pk_mul_f32 v[120:121], v[58:59], v[106:107]
	v_pk_mul_f32 v[106:107], v[56:57], v[104:105]
	v_cvt_pk_bf16_f32 v104, v108, v109
	v_cvt_pk_bf16_f32 v105, v110, v111
	v_cvt_pk_bf16_f32 v106, v106, v107
	v_cvt_pk_bf16_f32 v107, v120, v121
	global_store_dwordx4 v[112:113], v[104:107], off
	s_branch .LBB0_334

; __device__ __forceinline__ unsigned cvt_pk_bf16(float lo, float hi) { f32x2 v = {lo, hi}; bf16x2_t_ b = __builtin_convertvector(v, bf16x2_t_); return __builtin_bit_cast(unsigned, b); }
; __device__ __forceinline__ float shfl_xor_l(float v, int o, int lane) { return __int_as_float(__builtin_amdgcn_ds_bpermute((lane ^ o) << 2, __float_as_int(v))); }
;     __device__ __forceinline__ void operator()(const Acc& acc, const Unit& u, int wr, int wc, int fr, int fq) const {
;     ...
;                 for (int bj = 0; bj < 2; ++bj) { f32x4* p0 = (f32x4*)(rowp + bj * HALF); const f32x4* r0 = (const f32x4*)(R + (size_t)row * DM + col0 + bj * HALF); const f32x4 o0 = r0[0] + acc[ai][bj][m][0] * alpha, o1 = r0[1] + acc[ai][bj][m][1] * alpha; p0[0] = o0; p0[1] = o1;
;                     if (gnext) { sq += (o0[0] * o0[0] + o0[1] * o0[1]) + (o0[2] * o0[2] + o0[3] * o0[3]) + (o1[0] * o1[0] + o1[1] * o1[1]) + (o1[2] * o1[2] + o1[3] * o1[3]);
;                         const f32x4 y0 = o0 * gv[bj][0], y1 = o1 * gv[bj][1];
;                         u32x4 w; w.x = cvt_pk_bf16(y0[0], y0[1]); w.y = cvt_pk_bf16(y0[2], y0[3]); w.z = cvt_pk_bf16(y1[0], y1[1]); w.w = cvt_pk_bf16(y1[2], y1[3]);
;                         *(u32x4*)(XNo + (size_t)row * DM + col0 + bj * HALF) = w; } }
;                 if (gnext) { sq += shfl_xor_l(sq, 16, lane); sq += shfl_xor_l(sq, 32, lane); if (fq == 0) part[wc * 256 + ai * HALF + wr * 64 + m * 16 + fr] = sq; }
.LBB0_334:
	s_nop 1
	v_mov_b64_e32 v[104:105], v[210:211]
	v_mov_b64_e32 v[106:107], v[212:213]
	s_and_b64 vcc, exec, s[42:43]
	s_waitcnt lgkmcnt(0)
	v_pk_fma_f32 v[102:103], v[102:103], 0.5, v[106:107] op_sel_hi:[1,0,1]
	v_pk_fma_f32 v[100:101], v[100:101], 0.5, v[104:105] op_sel_hi:[1,0,1]
	s_nop 1
	v_mov_b64_e32 v[104:105], v[214:215]
	v_mov_b64_e32 v[106:107], v[216:217]
	s_waitcnt lgkmcnt(0)
	v_pk_fma_f32 v[98:99], v[98:99], 0.5, v[106:107] op_sel_hi:[1,0,1]
	v_pk_fma_f32 v[96:97], v[96:97], 0.5, v[104:105] op_sel_hi:[1,0,1]
	global_store_dwordx4 v[114:115], v[100:103], off offset:512
	global_store_dwordx4 v[114:115], v[96:99], off offset:528
	s_cbranch_vccnz .LBB0_338
	v_mul_f32_e32 v104, v101, v101
	v_mul_f32_e32 v105, v103, v103
	v_fmac_f32_e32 v104, v100, v100
	v_fmac_f32_e32 v105, v102, v102
	v_add_f32_e32 v104, v104, v105
	v_mul_f32_e32 v105, v97, v97
	v_fmac_f32_e32 v105, v96, v96
	v_add_f32_e32 v104, v104, v105
	v_mul_f32_e32 v105, v99, v99
	v_fmac_f32_e32 v105, v98, v98
	v_add_f32_e32 v104, v105, v104
	v_add_f32_e32 v108, v118, v104
	ds_bpermute_b32 v109, v138, v108
	v_pk_mul_f32 v[106:107], v[44:45], v[96:97]
	v_pk_mul_f32 v[102:103], v[50:51], v[102:103]
	v_pk_mul_f32 v[100:101], v[48:49], v[100:101]
	v_pk_mul_f32 v[104:105], v[46:47], v[98:99]
	s_waitcnt lgkmcnt(0)
	v_add_f32_e32 v96, v108, v109
	ds_bpermute_b32 v97, v137, v96
	v_cvt_pk_bf16_f32 v98, v100, v101
	v_cvt_pk_bf16_f32 v99, v102, v103
	v_cvt_pk_bf16_f32 v100, v106, v107
	v_cvt_pk_bf16_f32 v101, v104, v105
	global_store_dwordx4 v[112:113], v[98:101], off offset:256
	s_and_saveexec_b64 s[6:7], s[44:45]
	s_cbranch_execz .LBB0_337
	s_waitcnt lgkmcnt(0)
	v_add_f32_e32 v96, v96, v97
	ds_write_b32 v136, v96 offset:128

; __device__ __forceinline__ unsigned cvt_pk_bf16(float lo, float hi) { f32x2 v = {lo, hi}; bf16x2_t_ b = __builtin_convertvector(v, bf16x2_t_); return __builtin_bit_cast(unsigned, b); }
;     __device__ __forceinline__ void operator()(const Acc& acc, const Unit& u, int wr, int wc, int fr, int fq) const {
;     ...
;             for (int m = 0; m < 4; ++m) { const int row = row0 + ai * HALF + m * 16; float* rowp = X + (size_t)row * DM + col0; float sq = 0.f;
; #pragma unroll
;                 for (int bj = 0; bj < 2; ++bj) { f32x4* p0 = (f32x4*)(rowp + bj * HALF); const f32x4* r0 = (const f32x4*)(R + (size_t)row * DM + col0 + bj * HALF); const f32x4 o0 = r0[0] + acc[ai][bj][m][0] * alpha, o1 = r0[1] + acc[ai][bj][m][1] * alpha; p0[0] = o0; p0[1] = o1;
;                     if (gnext) { sq += (o0[0] * o0[0] + o0[1] * o0[1]) + (o0[2] * o0[2] + o0[3] * o0[3]) + (o1[0] * o1[0] + o1[1] * o1[1]) + (o1[2] * o1[2] + o1[3] * o1[3]);
;                         const f32x4 y0 = o0 * gv[bj][0], y1 = o1 * gv[bj][1];
;                         u32x4 w; w.x = cvt_pk_bf16(y0[0], y0[1]); w.y = cvt_pk_bf16(y0[2], y0[3]); w.z = cvt_pk_bf16(y1[0], y1[1]); w.w = cvt_pk_bf16(y1[2], y1[3]);
;                         *(u32x4*)(XNo + (size_t)row * DM + col0 + bj * HALF) = w; } }
.LBB0_338:
	s_nop 0
	v_or_b32_e32 v96, 48, v144
	s_waitcnt lgkmcnt(0)
	v_ashrrev_i32_e32 v97, 31, v96
	v_lshlrev_b64 v[100:101], 12, v[96:97]
	v_lshl_add_u64 v[98:99], v[148:149], 0, v[100:101]
	v_lshl_add_u64 v[100:101], v[150:151], 0, v[100:101]
	global_load_dwordx4 v[202:205], v[100:101], off
	global_load_dwordx4 v[206:209], v[100:101], off offset:16
	global_load_dwordx4 v[210:213], v[100:101], off offset:512
	global_load_dwordx4 v[214:217], v[100:101], off offset:528
	v_lshlrev_b64 v[96:97], 11, v[96:97]
	v_lshl_add_u64 v[96:97], v[146:147], 0, v[96:97]
	s_and_b64 vcc, exec, s[42:43]
	s_waitcnt vmcnt(0) lgkmcnt(0)
	s_nop 1
	v_mov_b64_e32 v[102:103], v[202:203]
	v_mov_b64_e32 v[104:105], v[204:205]
	v_pk_fma_f32 v[94:95], v[94:95], 0.5, v[104:105] op_sel_hi:[1,0,1]
	v_pk_fma_f32 v[92:93], v[92:93], 0.5, v[102:103] op_sel_hi:[1,0,1]
	s_nop 1
	v_mov_b64_e32 v[102:103], v[206:207]
	v_mov_b64_e32 v[104:105], v[208:209]
	s_waitcnt lgkmcnt(0)
	v_pk_fma_f32 v[90:91], v[90:91], 0.5, v[104:105] op_sel_hi:[1,0,1]
	v_pk_fma_f32 v[88:89], v[88:89], 0.5, v[102:103] op_sel_hi:[1,0,1]
	global_store_dwordx4 v[98:99], v[92:95], off
	global_store_dwordx4 v[98:99], v[88:91], off offset:16
	s_cbranch_vccnz .LBB0_340
	v_pk_mul_f32 v[102:103], v[94:95], v[94:95]
	v_pk_mul_f32 v[104:105], v[92:93], v[92:93]
	v_pk_mul_f32 v[94:95], v[66:67], v[94:95]
	v_pk_mov_b32 v[106:107], v[104:105], v[102:103] op_sel:[1,0]
	v_mov_b32_e32 v105, v103
	v_pk_add_f32 v[102:103], v[106:107], v[104:105]
	v_pk_mul_f32 v[104:105], v[90:91], v[90:91]
	v_pk_mul_f32 v[106:107], v[88:89], v[88:89]
	v_mov_b32_e32 v108, v104
	v_mov_b32_e32 v109, v106
	v_mov_b32_e32 v106, v105
	v_pk_add_f32 v[104:105], v[108:109], v[106:107]
	v_add_f32_e32 v102, v102, v103
	v_add_f32_e32 v102, v102, v105
	v_add_f32_e32 v102, v104, v102
	v_pk_mul_f32 v[92:93], v[64:65], v[92:93]
	v_pk_mul_f32 v[104:105], v[58:59], v[90:91]
	v_pk_mul_f32 v[90:91], v[56:57], v[88:89]
	v_cvt_pk_bf16_f32 v88, v92, v93
	v_cvt_pk_bf16_f32 v89, v94, v95
	v_cvt_pk_bf16_f32 v90, v90, v91
	v_cvt_pk_bf16_f32 v91, v104, v105
	global_store_dwordx4 v[96:97], v[88:91], off
	s_branch .LBB0_341

; __device__ __forceinline__ unsigned cvt_pk_bf16(float lo, float hi) { f32x2 v = {lo, hi}; bf16x2_t_ b = __builtin_convertvector(v, bf16x2_t_); return __builtin_bit_cast(unsigned, b); }
; __device__ __forceinline__ float shfl_xor_l(float v, int o, int lane) { return __int_as_float(__builtin_amdgcn_ds_bpermute((lane ^ o) << 2, __float_as_int(v))); }
;     __device__ __forceinline__ void operator()(const Acc& acc, const Unit& u, int wr, int wc, int fr, int fq) const {
;     ...
;                 for (int bj = 0; bj < 2; ++bj) { f32x4* p0 = (f32x4*)(rowp + bj * HALF); const f32x4* r0 = (const f32x4*)(R + (size_t)row * DM + col0 + bj * HALF); const f32x4 o0 = r0[0] + acc[ai][bj][m][0] * alpha, o1 = r0[1] + acc[ai][bj][m][1] * alpha; p0[0] = o0; p0[1] = o1;
;                     if (gnext) { sq += (o0[0] * o0[0] + o0[1] * o0[1]) + (o0[2] * o0[2] + o0[3] * o0[3]) + (o1[0] * o1[0] + o1[1] * o1[1]) + (o1[2] * o1[2] + o1[3] * o1[3]);
;                         const f32x4 y0 = o0 * gv[bj][0], y1 = o1 * gv[bj][1];
;                         u32x4 w; w.x = cvt_pk_bf16(y0[0], y0[1]); w.y = cvt_pk_bf16(y0[2], y0[3]); w.z = cvt_pk_bf16(y1[0], y1[1]); w.w = cvt_pk_bf16(y1[2], y1[3]);
;                         *(u32x4*)(XNo + (size_t)row * DM + col0 + bj * HALF) = w; } }
;                 if (gnext) { sq += shfl_xor_l(sq, 16, lane); sq += shfl_xor_l(sq, 32, lane); if (fq == 0) part[wc * 256 + ai * HALF + wr * 64 + m * 16 + fr] = sq; }
.LBB0_341:
	s_nop 1
	v_mov_b64_e32 v[88:89], v[210:211]
	v_mov_b64_e32 v[90:91], v[212:213]
	s_and_b64 vcc, exec, s[42:43]
	s_waitcnt lgkmcnt(0)
	v_pk_fma_f32 v[86:87], v[86:87], 0.5, v[90:91] op_sel_hi:[1,0,1]
	v_pk_fma_f32 v[84:85], v[84:85], 0.5, v[88:89] op_sel_hi:[1,0,1]
	s_nop 1
	v_mov_b64_e32 v[88:89], v[214:215]
	v_mov_b64_e32 v[90:91], v[216:217]
	s_waitcnt lgkmcnt(0)
	v_pk_fma_f32 v[82:83], v[82:83], 0.5, v[90:91] op_sel_hi:[1,0,1]
	v_pk_fma_f32 v[80:81], v[80:81], 0.5, v[88:89] op_sel_hi:[1,0,1]
	global_store_dwordx4 v[98:99], v[84:87], off offset:512
	global_store_dwordx4 v[98:99], v[80:83], off offset:528
	s_cbranch_vccnz .LBB0_345
	v_mul_f32_e32 v88, v85, v85
	v_mul_f32_e32 v89, v87, v87
	v_fmac_f32_e32 v88, v84, v84
	v_fmac_f32_e32 v89, v86, v86
	v_add_f32_e32 v88, v88, v89
	v_mul_f32_e32 v89, v81, v81
	v_fmac_f32_e32 v89, v80, v80
	v_add_f32_e32 v88, v88, v89
	v_mul_f32_e32 v89, v83, v83
	v_fmac_f32_e32 v89, v82, v82
	v_add_f32_e32 v88, v89, v88
	v_add_f32_e32 v92, v102, v88
	ds_bpermute_b32 v93, v138, v92
	v_pk_mul_f32 v[90:91], v[44:45], v[80:81]
	v_pk_mul_f32 v[86:87], v[50:51], v[86:87]
	v_pk_mul_f32 v[84:85], v[48:49], v[84:85]
	v_pk_mul_f32 v[88:89], v[46:47], v[82:83]
	s_waitcnt lgkmcnt(0)
	v_add_f32_e32 v80, v92, v93
	ds_bpermute_b32 v81, v137, v80
	v_cvt_pk_bf16_f32 v82, v84, v85
	v_cvt_pk_bf16_f32 v83, v86, v87
	v_cvt_pk_bf16_f32 v84, v90, v91
	v_cvt_pk_bf16_f32 v85, v88, v89
	global_store_dwordx4 v[96:97], v[82:85], off offset:256
	s_and_saveexec_b64 s[6:7], s[44:45]
	s_cbranch_execz .LBB0_344
	s_waitcnt lgkmcnt(0)
	v_add_f32_e32 v80, v80, v81
	ds_write_b32 v136, v80 offset:192

; __device__ __forceinline__ unsigned cvt_pk_bf16(float lo, float hi) { f32x2 v = {lo, hi}; bf16x2_t_ b = __builtin_convertvector(v, bf16x2_t_); return __builtin_bit_cast(unsigned, b); }
;     __device__ __forceinline__ void operator()(const Acc& acc, const Unit& u, int wr, int wc, int fr, int fq) const {
;     ...
;             for (int m = 0; m < 4; ++m) { const int row = row0 + ai * HALF + m * 16; float* rowp = X + (size_t)row * DM + col0; float sq = 0.f;
; #pragma unroll
;                 for (int bj = 0; bj < 2; ++bj) { f32x4* p0 = (f32x4*)(rowp + bj * HALF); const f32x4* r0 = (const f32x4*)(R + (size_t)row * DM + col0 + bj * HALF); const f32x4 o0 = r0[0] + acc[ai][bj][m][0] * alpha, o1 = r0[1] + acc[ai][bj][m][1] * alpha; p0[0] = o0; p0[1] = o1;
;                     if (gnext) { sq += (o0[0] * o0[0] + o0[1] * o0[1]) + (o0[2] * o0[2] + o0[3] * o0[3]) + (o1[0] * o1[0] + o1[1] * o1[1]) + (o1[2] * o1[2] + o1[3] * o1[3]);
;                         const f32x4 y0 = o0 * gv[bj][0], y1 = o1 * gv[bj][1];
;                         u32x4 w; w.x = cvt_pk_bf16(y0[0], y0[1]); w.y = cvt_pk_bf16(y0[2], y0[3]); w.z = cvt_pk_bf16(y1[0], y1[1]); w.w = cvt_pk_bf16(y1[2], y1[3]);
;                         *(u32x4*)(XNo + (size_t)row * DM + col0 + bj * HALF) = w; } }
.LBB0_345:
	s_nop 0
	v_add_u32_e32 v80, 0x80, v144
	s_waitcnt lgkmcnt(0)
	v_ashrrev_i32_e32 v81, 31, v80
	v_lshlrev_b64 v[84:85], 12, v[80:81]
	v_lshl_add_u64 v[82:83], v[148:149], 0, v[84:85]
	v_lshl_add_u64 v[84:85], v[150:151], 0, v[84:85]
	global_load_dwordx4 v[202:205], v[84:85], off
	global_load_dwordx4 v[206:209], v[84:85], off offset:16
	global_load_dwordx4 v[210:213], v[84:85], off offset:512
	global_load_dwordx4 v[214:217], v[84:85], off offset:528
	v_lshlrev_b64 v[80:81], 11, v[80:81]
	v_lshl_add_u64 v[80:81], v[146:147], 0, v[80:81]
	s_and_b64 vcc, exec, s[42:43]
	s_waitcnt vmcnt(0) lgkmcnt(0)
	s_nop 1
	v_mov_b64_e32 v[86:87], v[202:203]
	v_mov_b64_e32 v[88:89], v[204:205]
	v_pk_fma_f32 v[78:79], v[78:79], 0.5, v[88:89] op_sel_hi:[1,0,1]
	v_pk_fma_f32 v[76:77], v[76:77], 0.5, v[86:87] op_sel_hi:[1,0,1]
	s_nop 1
	v_mov_b64_e32 v[86:87], v[206:207]
	v_mov_b64_e32 v[88:89], v[208:209]
	s_waitcnt lgkmcnt(0)
	v_pk_fma_f32 v[74:75], v[74:75], 0.5, v[88:89] op_sel_hi:[1,0,1]
	v_pk_fma_f32 v[72:73], v[72:73], 0.5, v[86:87] op_sel_hi:[1,0,1]
	global_store_dwordx4 v[82:83], v[76:79], off
	global_store_dwordx4 v[82:83], v[72:75], off offset:16
	s_cbranch_vccnz .LBB0_347
	v_pk_mul_f32 v[86:87], v[78:79], v[78:79]
	v_pk_mul_f32 v[88:89], v[76:77], v[76:77]
	v_pk_mul_f32 v[78:79], v[66:67], v[78:79]
	v_pk_mov_b32 v[90:91], v[88:89], v[86:87] op_sel:[1,0]
	v_mov_b32_e32 v89, v87
	v_pk_add_f32 v[86:87], v[90:91], v[88:89]
	v_pk_mul_f32 v[88:89], v[74:75], v[74:75]
	v_pk_mul_f32 v[90:91], v[72:73], v[72:73]
	v_mov_b32_e32 v92, v88
	v_mov_b32_e32 v93, v90
	v_mov_b32_e32 v90, v89
	v_pk_add_f32 v[88:89], v[92:93], v[90:91]
	v_add_f32_e32 v86, v86, v87
	v_add_f32_e32 v86, v86, v89
	v_add_f32_e32 v86, v88, v86
	v_pk_mul_f32 v[76:77], v[64:65], v[76:77]
	v_pk_mul_f32 v[88:89], v[58:59], v[74:75]
	v_pk_mul_f32 v[74:75], v[56:57], v[72:73]
	v_cvt_pk_bf16_f32 v72, v76, v77
	v_cvt_pk_bf16_f32 v73, v78, v79
	v_cvt_pk_bf16_f32 v74, v74, v75
	v_cvt_pk_bf16_f32 v75, v88, v89
	global_store_dwordx4 v[80:81], v[72:75], off
	s_branch .LBB0_348

; __device__ __forceinline__ unsigned cvt_pk_bf16(float lo, float hi) { f32x2 v = {lo, hi}; bf16x2_t_ b = __builtin_convertvector(v, bf16x2_t_); return __builtin_bit_cast(unsigned, b); }
; __device__ __forceinline__ float shfl_xor_l(float v, int o, int lane) { return __int_as_float(__builtin_amdgcn_ds_bpermute((lane ^ o) << 2, __float_as_int(v))); }
;     __device__ __forceinline__ void operator()(const Acc& acc, const Unit& u, int wr, int wc, int fr, int fq) const {
;     ...
;                 for (int bj = 0; bj < 2; ++bj) { f32x4* p0 = (f32x4*)(rowp + bj * HALF); const f32x4* r0 = (const f32x4*)(R + (size_t)row * DM + col0 + bj * HALF); const f32x4 o0 = r0[0] + acc[ai][bj][m][0] * alpha, o1 = r0[1] + acc[ai][bj][m][1] * alpha; p0[0] = o0; p0[1] = o1;
;                     if (gnext) { sq += (o0[0] * o0[0] + o0[1] * o0[1]) + (o0[2] * o0[2] + o0[3] * o0[3]) + (o1[0] * o1[0] + o1[1] * o1[1]) + (o1[2] * o1[2] + o1[3] * o1[3]);
;                         const f32x4 y0 = o0 * gv[bj][0], y1 = o1 * gv[bj][1];
;                         u32x4 w; w.x = cvt_pk_bf16(y0[0], y0[1]); w.y = cvt_pk_bf16(y0[2], y0[3]); w.z = cvt_pk_bf16(y1[0], y1[1]); w.w = cvt_pk_bf16(y1[2], y1[3]);
;                         *(u32x4*)(XNo + (size_t)row * DM + col0 + bj * HALF) = w; } }
;                 if (gnext) { sq += shfl_xor_l(sq, 16, lane); sq += shfl_xor_l(sq, 32, lane); if (fq == 0) part[wc * 256 + ai * HALF + wr * 64 + m * 16 + fr] = sq; }
.LBB0_348:
	s_nop 1
	v_mov_b64_e32 v[72:73], v[210:211]
	v_mov_b64_e32 v[74:75], v[212:213]
	s_and_b64 vcc, exec, s[42:43]
	s_waitcnt lgkmcnt(0)
	v_pk_fma_f32 v[70:71], v[70:71], 0.5, v[74:75] op_sel_hi:[1,0,1]
	v_pk_fma_f32 v[68:69], v[68:69], 0.5, v[72:73] op_sel_hi:[1,0,1]
	s_nop 1
	v_mov_b64_e32 v[72:73], v[214:215]
	v_mov_b64_e32 v[74:75], v[216:217]
	s_waitcnt lgkmcnt(0)
	v_pk_fma_f32 v[62:63], v[62:63], 0.5, v[74:75] op_sel_hi:[1,0,1]
	v_pk_fma_f32 v[60:61], v[60:61], 0.5, v[72:73] op_sel_hi:[1,0,1]
	global_store_dwordx4 v[82:83], v[68:71], off offset:512
	global_store_dwordx4 v[82:83], v[60:63], off offset:528
	s_cbranch_vccnz .LBB0_352
	v_mul_f32_e32 v72, v69, v69
	v_mul_f32_e32 v73, v71, v71
	v_fmac_f32_e32 v72, v68, v68
	v_fmac_f32_e32 v73, v70, v70
	v_add_f32_e32 v72, v72, v73
	v_mul_f32_e32 v73, v61, v61
	v_fmac_f32_e32 v73, v60, v60
	v_add_f32_e32 v72, v72, v73
	v_mul_f32_e32 v73, v63, v63
	v_fmac_f32_e32 v73, v62, v62
	v_add_f32_e32 v72, v73, v72
	v_add_f32_e32 v74, v86, v72
	ds_bpermute_b32 v75, v138, v74
	v_pk_mul_f32 v[72:73], v[44:45], v[60:61]
	v_pk_mul_f32 v[70:71], v[50:51], v[70:71]
	v_pk_mul_f32 v[68:69], v[48:49], v[68:69]
	v_pk_mul_f32 v[62:63], v[46:47], v[62:63]
	s_waitcnt lgkmcnt(0)
	v_add_f32_e32 v60, v74, v75
	ds_bpermute_b32 v61, v137, v60
	v_cvt_pk_bf16_f32 v68, v68, v69
	v_cvt_pk_bf16_f32 v69, v70, v71
	v_cvt_pk_bf16_f32 v70, v72, v73
	v_cvt_pk_bf16_f32 v71, v62, v63
	global_store_dwordx4 v[80:81], v[68:71], off offset:256
	s_and_saveexec_b64 s[6:7], s[44:45]
	s_cbranch_execz .LBB0_351
	s_waitcnt lgkmcnt(0)
	v_add_f32_e32 v60, v60, v61
	ds_write_b32 v136, v60 offset:512

; __device__ __forceinline__ unsigned cvt_pk_bf16(float lo, float hi) { f32x2 v = {lo, hi}; bf16x2_t_ b = __builtin_convertvector(v, bf16x2_t_); return __builtin_bit_cast(unsigned, b); }
;     __device__ __forceinline__ void operator()(const Acc& acc, const Unit& u, int wr, int wc, int fr, int fq) const {
;     ...
;             for (int m = 0; m < 4; ++m) { const int row = row0 + ai * HALF + m * 16; float* rowp = X + (size_t)row * DM + col0; float sq = 0.f;
; #pragma unroll
;                 for (int bj = 0; bj < 2; ++bj) { f32x4* p0 = (f32x4*)(rowp + bj * HALF); const f32x4* r0 = (const f32x4*)(R + (size_t)row * DM + col0 + bj * HALF); const f32x4 o0 = r0[0] + acc[ai][bj][m][0] * alpha, o1 = r0[1] + acc[ai][bj][m][1] * alpha; p0[0] = o0; p0[1] = o1;
;                     if (gnext) { sq += (o0[0] * o0[0] + o0[1] * o0[1]) + (o0[2] * o0[2] + o0[3] * o0[3]) + (o1[0] * o1[0] + o1[1] * o1[1]) + (o1[2] * o1[2] + o1[3] * o1[3]);
;                         const f32x4 y0 = o0 * gv[bj][0], y1 = o1 * gv[bj][1];
;                         u32x4 w; w.x = cvt_pk_bf16(y0[0], y0[1]); w.y = cvt_pk_bf16(y0[2], y0[3]); w.z = cvt_pk_bf16(y1[0], y1[1]); w.w = cvt_pk_bf16(y1[2], y1[3]);
;                         *(u32x4*)(XNo + (size_t)row * DM + col0 + bj * HALF) = w; } }
.LBB0_352:
	s_nop 0
	v_add_u32_e32 v60, 0x90, v144
	s_waitcnt lgkmcnt(0)
	v_ashrrev_i32_e32 v61, 31, v60
	v_lshlrev_b64 v[68:69], 12, v[60:61]
	v_lshl_add_u64 v[62:63], v[148:149], 0, v[68:69]
	v_lshl_add_u64 v[68:69], v[150:151], 0, v[68:69]
	global_load_dwordx4 v[202:205], v[68:69], off
	global_load_dwordx4 v[206:209], v[68:69], off offset:16
	global_load_dwordx4 v[210:213], v[68:69], off offset:512
	global_load_dwordx4 v[214:217], v[68:69], off offset:528
	v_lshlrev_b64 v[60:61], 11, v[60:61]
	v_lshl_add_u64 v[60:61], v[146:147], 0, v[60:61]
	s_and_b64 vcc, exec, s[42:43]
	s_waitcnt vmcnt(0) lgkmcnt(0)
	s_nop 1
	v_mov_b64_e32 v[70:71], v[202:203]
	v_mov_b64_e32 v[72:73], v[204:205]
	v_pk_fma_f32 v[54:55], v[54:55], 0.5, v[72:73] op_sel_hi:[1,0,1]
	v_pk_fma_f32 v[52:53], v[52:53], 0.5, v[70:71] op_sel_hi:[1,0,1]
	s_nop 1
	v_mov_b64_e32 v[70:71], v[206:207]
	v_mov_b64_e32 v[72:73], v[208:209]
	s_waitcnt lgkmcnt(0)
	v_pk_fma_f32 v[42:43], v[42:43], 0.5, v[72:73] op_sel_hi:[1,0,1]
	v_pk_fma_f32 v[40:41], v[40:41], 0.5, v[70:71] op_sel_hi:[1,0,1]
	global_store_dwordx4 v[62:63], v[52:55], off
	global_store_dwordx4 v[62:63], v[40:43], off offset:16
	s_cbranch_vccnz .LBB0_354
	v_pk_mul_f32 v[70:71], v[54:55], v[54:55]
	v_pk_mul_f32 v[72:73], v[52:53], v[52:53]
	v_pk_mul_f32 v[54:55], v[66:67], v[54:55]
	v_pk_mov_b32 v[74:75], v[72:73], v[70:71] op_sel:[1,0]
	v_mov_b32_e32 v73, v71
	v_pk_add_f32 v[70:71], v[74:75], v[72:73]
	v_pk_mul_f32 v[72:73], v[42:43], v[42:43]
	v_pk_mul_f32 v[74:75], v[40:41], v[40:41]
	v_mov_b32_e32 v76, v72
	v_mov_b32_e32 v77, v74
	v_mov_b32_e32 v74, v73
	v_pk_add_f32 v[72:73], v[76:77], v[74:75]
	v_add_f32_e32 v70, v70, v71
	v_add_f32_e32 v70, v70, v73
	v_add_f32_e32 v70, v72, v70
	v_pk_mul_f32 v[52:53], v[64:65], v[52:53]
	v_pk_mul_f32 v[72:73], v[58:59], v[42:43]
	v_pk_mul_f32 v[42:43], v[56:57], v[40:41]
	v_cvt_pk_bf16_f32 v40, v52, v53
	v_cvt_pk_bf16_f32 v41, v54, v55
	v_cvt_pk_bf16_f32 v42, v42, v43
	v_cvt_pk_bf16_f32 v43, v72, v73
	global_store_dwordx4 v[60:61], v[40:43], off
	s_branch .LBB0_355

; __device__ __forceinline__ unsigned cvt_pk_bf16(float lo, float hi) { f32x2 v = {lo, hi}; bf16x2_t_ b = __builtin_convertvector(v, bf16x2_t_); return __builtin_bit_cast(unsigned, b); }
; __device__ __forceinline__ float shfl_xor_l(float v, int o, int lane) { return __int_as_float(__builtin_amdgcn_ds_bpermute((lane ^ o) << 2, __float_as_int(v))); }
;     __device__ __forceinline__ void operator()(const Acc& acc, const Unit& u, int wr, int wc, int fr, int fq) const {
;     ...
;                 for (int bj = 0; bj < 2; ++bj) { f32x4* p0 = (f32x4*)(rowp + bj * HALF); const f32x4* r0 = (const f32x4*)(R + (size_t)row * DM + col0 + bj * HALF); const f32x4 o0 = r0[0] + acc[ai][bj][m][0] * alpha, o1 = r0[1] + acc[ai][bj][m][1] * alpha; p0[0] = o0; p0[1] = o1;
;                     if (gnext) { sq += (o0[0] * o0[0] + o0[1] * o0[1]) + (o0[2] * o0[2] + o0[3] * o0[3]) + (o1[0] * o1[0] + o1[1] * o1[1]) + (o1[2] * o1[2] + o1[3] * o1[3]);
;                         const f32x4 y0 = o0 * gv[bj][0], y1 = o1 * gv[bj][1];
;                         u32x4 w; w.x = cvt_pk_bf16(y0[0], y0[1]); w.y = cvt_pk_bf16(y0[2], y0[3]); w.z = cvt_pk_bf16(y1[0], y1[1]); w.w = cvt_pk_bf16(y1[2], y1[3]);
;                         *(u32x4*)(XNo + (size_t)row * DM + col0 + bj * HALF) = w; } }
;                 if (gnext) { sq += shfl_xor_l(sq, 16, lane); sq += shfl_xor_l(sq, 32, lane); if (fq == 0) part[wc * 256 + ai * HALF + wr * 64 + m * 16 + fr] = sq; }
.LBB0_355:
	s_nop 1
	v_mov_b64_e32 v[40:41], v[210:211]
	v_mov_b64_e32 v[42:43], v[212:213]
	s_and_b64 vcc, exec, s[42:43]
	s_waitcnt lgkmcnt(0)
	v_pk_fma_f32 v[38:39], v[38:39], 0.5, v[42:43] op_sel_hi:[1,0,1]
	v_pk_fma_f32 v[36:37], v[36:37], 0.5, v[40:41] op_sel_hi:[1,0,1]
	s_nop 1
	v_mov_b64_e32 v[40:41], v[214:215]
	v_mov_b64_e32 v[42:43], v[216:217]
	s_waitcnt lgkmcnt(0)
	v_pk_fma_f32 v[34:35], v[34:35], 0.5, v[42:43] op_sel_hi:[1,0,1]
	v_pk_fma_f32 v[32:33], v[32:33], 0.5, v[40:41] op_sel_hi:[1,0,1]
	global_store_dwordx4 v[62:63], v[36:39], off offset:512
	global_store_dwordx4 v[62:63], v[32:35], off offset:528
	s_cbranch_vccnz .LBB0_359
	v_mul_f32_e32 v40, v37, v37
	v_mul_f32_e32 v41, v39, v39
	v_fmac_f32_e32 v40, v36, v36
	v_fmac_f32_e32 v41, v38, v38
	v_add_f32_e32 v40, v40, v41
	v_mul_f32_e32 v41, v33, v33
	v_fmac_f32_e32 v41, v32, v32
	v_add_f32_e32 v40, v40, v41
	v_mul_f32_e32 v41, v35, v35
	v_fmac_f32_e32 v41, v34, v34
	v_add_f32_e32 v40, v41, v40
	v_add_f32_e32 v52, v70, v40
	ds_bpermute_b32 v53, v138, v52
	v_pk_mul_f32 v[42:43], v[44:45], v[32:33]
	v_pk_mul_f32 v[38:39], v[50:51], v[38:39]
	v_pk_mul_f32 v[36:37], v[48:49], v[36:37]
	v_pk_mul_f32 v[40:41], v[46:47], v[34:35]
	s_waitcnt lgkmcnt(0)
	v_add_f32_e32 v32, v52, v53
	ds_bpermute_b32 v33, v137, v32
	v_cvt_pk_bf16_f32 v34, v36, v37
	v_cvt_pk_bf16_f32 v35, v38, v39
	v_cvt_pk_bf16_f32 v36, v42, v43
	v_cvt_pk_bf16_f32 v37, v40, v41
	global_store_dwordx4 v[60:61], v[34:37], off offset:256
	s_and_saveexec_b64 s[6:7], s[44:45]
	s_cbranch_execz .LBB0_358
	s_waitcnt lgkmcnt(0)
	v_add_f32_e32 v32, v32, v33
	ds_write_b32 v136, v32 offset:576

; __device__ __forceinline__ unsigned cvt_pk_bf16(float lo, float hi) { f32x2 v = {lo, hi}; bf16x2_t_ b = __builtin_convertvector(v, bf16x2_t_); return __builtin_bit_cast(unsigned, b); }
;     __device__ __forceinline__ void operator()(const Acc& acc, const Unit& u, int wr, int wc, int fr, int fq) const {
;     ...
;             for (int m = 0; m < 4; ++m) { const int row = row0 + ai * HALF + m * 16; float* rowp = X + (size_t)row * DM + col0; float sq = 0.f;
; #pragma unroll
;                 for (int bj = 0; bj < 2; ++bj) { f32x4* p0 = (f32x4*)(rowp + bj * HALF); const f32x4* r0 = (const f32x4*)(R + (size_t)row * DM + col0 + bj * HALF); const f32x4 o0 = r0[0] + acc[ai][bj][m][0] * alpha, o1 = r0[1] + acc[ai][bj][m][1] * alpha; p0[0] = o0; p0[1] = o1;
;                     if (gnext) { sq += (o0[0] * o0[0] + o0[1] * o0[1]) + (o0[2] * o0[2] + o0[3] * o0[3]) + (o1[0] * o1[0] + o1[1] * o1[1]) + (o1[2] * o1[2] + o1[3] * o1[3]);
;                         const f32x4 y0 = o0 * gv[bj][0], y1 = o1 * gv[bj][1];
;                         u32x4 w; w.x = cvt_pk_bf16(y0[0], y0[1]); w.y = cvt_pk_bf16(y0[2], y0[3]); w.z = cvt_pk_bf16(y1[0], y1[1]); w.w = cvt_pk_bf16(y1[2], y1[3]);
;                         *(u32x4*)(XNo + (size_t)row * DM + col0 + bj * HALF) = w; } }
.LBB0_359:
	s_nop 0
	v_add_u32_e32 v32, 0xa0, v144
	s_waitcnt lgkmcnt(0)
	v_ashrrev_i32_e32 v33, 31, v32
	v_lshlrev_b64 v[36:37], 12, v[32:33]
	v_lshl_add_u64 v[34:35], v[148:149], 0, v[36:37]
	v_lshl_add_u64 v[36:37], v[150:151], 0, v[36:37]
	global_load_dwordx4 v[202:205], v[36:37], off
	global_load_dwordx4 v[206:209], v[36:37], off offset:16
	global_load_dwordx4 v[210:213], v[36:37], off offset:512
	global_load_dwordx4 v[214:217], v[36:37], off offset:528
	v_lshlrev_b64 v[32:33], 11, v[32:33]
	v_lshl_add_u64 v[32:33], v[146:147], 0, v[32:33]
	s_and_b64 vcc, exec, s[42:43]
	s_waitcnt vmcnt(0) lgkmcnt(0)
	s_nop 1
	v_mov_b64_e32 v[38:39], v[202:203]
	v_mov_b64_e32 v[40:41], v[204:205]
	v_pk_fma_f32 v[30:31], v[30:31], 0.5, v[40:41] op_sel_hi:[1,0,1]
	v_pk_fma_f32 v[28:29], v[28:29], 0.5, v[38:39] op_sel_hi:[1,0,1]
	s_nop 1
	v_mov_b64_e32 v[38:39], v[206:207]
	v_mov_b64_e32 v[40:41], v[208:209]
	s_waitcnt lgkmcnt(0)
	v_pk_fma_f32 v[26:27], v[26:27], 0.5, v[40:41] op_sel_hi:[1,0,1]
	v_pk_fma_f32 v[24:25], v[24:25], 0.5, v[38:39] op_sel_hi:[1,0,1]
	global_store_dwordx4 v[34:35], v[28:31], off
	global_store_dwordx4 v[34:35], v[24:27], off offset:16
	s_cbranch_vccnz .LBB0_361
	v_pk_mul_f32 v[38:39], v[30:31], v[30:31]
	v_pk_mul_f32 v[40:41], v[28:29], v[28:29]
	v_pk_mul_f32 v[30:31], v[66:67], v[30:31]
	v_pk_mov_b32 v[42:43], v[40:41], v[38:39] op_sel:[1,0]
	v_mov_b32_e32 v41, v39
	v_pk_add_f32 v[38:39], v[42:43], v[40:41]
	v_pk_mul_f32 v[40:41], v[26:27], v[26:27]
	v_pk_mul_f32 v[42:43], v[24:25], v[24:25]
	v_mov_b32_e32 v52, v40
	v_mov_b32_e32 v53, v42
	v_mov_b32_e32 v42, v41
	v_pk_add_f32 v[40:41], v[52:53], v[42:43]
	v_add_f32_e32 v38, v38, v39
	v_add_f32_e32 v38, v38, v41
	v_add_f32_e32 v38, v40, v38
	v_pk_mul_f32 v[28:29], v[64:65], v[28:29]
	v_pk_mul_f32 v[40:41], v[58:59], v[26:27]
	v_pk_mul_f32 v[26:27], v[56:57], v[24:25]
	v_cvt_pk_bf16_f32 v24, v28, v29
	v_cvt_pk_bf16_f32 v25, v30, v31
	v_cvt_pk_bf16_f32 v26, v26, v27
	v_cvt_pk_bf16_f32 v27, v40, v41
	global_store_dwordx4 v[32:33], v[24:27], off
	s_branch .LBB0_362

; __device__ __forceinline__ unsigned cvt_pk_bf16(float lo, float hi) { f32x2 v = {lo, hi}; bf16x2_t_ b = __builtin_convertvector(v, bf16x2_t_); return __builtin_bit_cast(unsigned, b); }
; __device__ __forceinline__ float shfl_xor_l(float v, int o, int lane) { return __int_as_float(__builtin_amdgcn_ds_bpermute((lane ^ o) << 2, __float_as_int(v))); }
;     __device__ __forceinline__ void operator()(const Acc& acc, const Unit& u, int wr, int wc, int fr, int fq) const {
;     ...
;                 for (int bj = 0; bj < 2; ++bj) { f32x4* p0 = (f32x4*)(rowp + bj * HALF); const f32x4* r0 = (const f32x4*)(R + (size_t)row * DM + col0 + bj * HALF); const f32x4 o0 = r0[0] + acc[ai][bj][m][0] * alpha, o1 = r0[1] + acc[ai][bj][m][1] * alpha; p0[0] = o0; p0[1] = o1;
;                     if (gnext) { sq += (o0[0] * o0[0] + o0[1] * o0[1]) + (o0[2] * o0[2] + o0[3] * o0[3]) + (o1[0] * o1[0] + o1[1] * o1[1]) + (o1[2] * o1[2] + o1[3] * o1[3]);
;                         const f32x4 y0 = o0 * gv[bj][0], y1 = o1 * gv[bj][1];
;                         u32x4 w; w.x = cvt_pk_bf16(y0[0], y0[1]); w.y = cvt_pk_bf16(y0[2], y0[3]); w.z = cvt_pk_bf16(y1[0], y1[1]); w.w = cvt_pk_bf16(y1[2], y1[3]);
;                         *(u32x4*)(XNo + (size_t)row * DM + col0 + bj * HALF) = w; } }
;                 if (gnext) { sq += shfl_xor_l(sq, 16, lane); sq += shfl_xor_l(sq, 32, lane); if (fq == 0) part[wc * 256 + ai * HALF + wr * 64 + m * 16 + fr] = sq; }
.LBB0_362:
	s_nop 1
	v_mov_b64_e32 v[24:25], v[210:211]
	v_mov_b64_e32 v[26:27], v[212:213]
	s_and_b64 vcc, exec, s[42:43]
	s_waitcnt lgkmcnt(0)
	v_pk_fma_f32 v[22:23], v[22:23], 0.5, v[26:27] op_sel_hi:[1,0,1]
	v_pk_fma_f32 v[20:21], v[20:21], 0.5, v[24:25] op_sel_hi:[1,0,1]
	s_nop 1
	v_mov_b64_e32 v[24:25], v[214:215]
	v_mov_b64_e32 v[26:27], v[216:217]
	s_waitcnt lgkmcnt(0)
	v_pk_fma_f32 v[18:19], v[18:19], 0.5, v[26:27] op_sel_hi:[1,0,1]
	v_pk_fma_f32 v[16:17], v[16:17], 0.5, v[24:25] op_sel_hi:[1,0,1]
	global_store_dwordx4 v[34:35], v[20:23], off offset:512
	global_store_dwordx4 v[34:35], v[16:19], off offset:528
	s_cbranch_vccnz .LBB0_366
	v_mul_f32_e32 v24, v21, v21
	v_mul_f32_e32 v25, v23, v23
	v_fmac_f32_e32 v24, v20, v20
	v_fmac_f32_e32 v25, v22, v22
	v_add_f32_e32 v24, v24, v25
	v_mul_f32_e32 v25, v17, v17
	v_fmac_f32_e32 v25, v16, v16
	v_add_f32_e32 v24, v24, v25
	v_mul_f32_e32 v25, v19, v19
	v_fmac_f32_e32 v25, v18, v18
	v_add_f32_e32 v24, v25, v24
	v_add_f32_e32 v28, v38, v24
	ds_bpermute_b32 v29, v138, v28
	v_pk_mul_f32 v[26:27], v[44:45], v[16:17]
	v_pk_mul_f32 v[22:23], v[50:51], v[22:23]
	v_pk_mul_f32 v[20:21], v[48:49], v[20:21]
	v_pk_mul_f32 v[24:25], v[46:47], v[18:19]
	s_waitcnt lgkmcnt(0)
	v_add_f32_e32 v16, v28, v29
	ds_bpermute_b32 v17, v137, v16
	v_cvt_pk_bf16_f32 v18, v20, v21
	v_cvt_pk_bf16_f32 v19, v22, v23
	v_cvt_pk_bf16_f32 v20, v26, v27
	v_cvt_pk_bf16_f32 v21, v24, v25
	global_store_dwordx4 v[32:33], v[18:21], off offset:256
	s_and_saveexec_b64 s[6:7], s[44:45]
	s_cbranch_execz .LBB0_365
	s_waitcnt lgkmcnt(0)
	v_add_f32_e32 v16, v16, v17
	ds_write_b32 v136, v16 offset:640

; __device__ __forceinline__ unsigned cvt_pk_bf16(float lo, float hi) { f32x2 v = {lo, hi}; bf16x2_t_ b = __builtin_convertvector(v, bf16x2_t_); return __builtin_bit_cast(unsigned, b); }
;     __device__ __forceinline__ void operator()(const Acc& acc, const Unit& u, int wr, int wc, int fr, int fq) const {
;     ...
;             for (int m = 0; m < 4; ++m) { const int row = row0 + ai * HALF + m * 16; float* rowp = X + (size_t)row * DM + col0; float sq = 0.f;
; #pragma unroll
;                 for (int bj = 0; bj < 2; ++bj) { f32x4* p0 = (f32x4*)(rowp + bj * HALF); const f32x4* r0 = (const f32x4*)(R + (size_t)row * DM + col0 + bj * HALF); const f32x4 o0 = r0[0] + acc[ai][bj][m][0] * alpha, o1 = r0[1] + acc[ai][bj][m][1] * alpha; p0[0] = o0; p0[1] = o1;
;                     if (gnext) { sq += (o0[0] * o0[0] + o0[1] * o0[1]) + (o0[2] * o0[2] + o0[3] * o0[3]) + (o1[0] * o1[0] + o1[1] * o1[1]) + (o1[2] * o1[2] + o1[3] * o1[3]);
;                         const f32x4 y0 = o0 * gv[bj][0], y1 = o1 * gv[bj][1];
;                         u32x4 w; w.x = cvt_pk_bf16(y0[0], y0[1]); w.y = cvt_pk_bf16(y0[2], y0[3]); w.z = cvt_pk_bf16(y1[0], y1[1]); w.w = cvt_pk_bf16(y1[2], y1[3]);
;                         *(u32x4*)(XNo + (size_t)row * DM + col0 + bj * HALF) = w; } }
.LBB0_366:
	s_nop 0
	v_add_u32_e32 v16, 0xb0, v144
	s_waitcnt lgkmcnt(0)
	v_ashrrev_i32_e32 v17, 31, v16
	v_lshlrev_b64 v[20:21], 12, v[16:17]
	v_lshl_add_u64 v[18:19], v[148:149], 0, v[20:21]
	v_lshl_add_u64 v[20:21], v[150:151], 0, v[20:21]
	global_load_dwordx4 v[202:205], v[20:21], off
	global_load_dwordx4 v[206:209], v[20:21], off offset:16
	global_load_dwordx4 v[210:213], v[20:21], off offset:512
	global_load_dwordx4 v[214:217], v[20:21], off offset:528
	v_lshlrev_b64 v[16:17], 11, v[16:17]
	v_lshl_add_u64 v[16:17], v[146:147], 0, v[16:17]
	s_and_b64 vcc, exec, s[42:43]
	s_waitcnt vmcnt(0) lgkmcnt(0)
	s_nop 1
	v_mov_b64_e32 v[22:23], v[202:203]
	v_mov_b64_e32 v[24:25], v[204:205]
	v_pk_fma_f32 v[14:15], v[14:15], 0.5, v[24:25] op_sel_hi:[1,0,1]
	v_pk_fma_f32 v[12:13], v[12:13], 0.5, v[22:23] op_sel_hi:[1,0,1]
	s_nop 1
	v_mov_b64_e32 v[22:23], v[206:207]
	v_mov_b64_e32 v[24:25], v[208:209]
	s_waitcnt lgkmcnt(0)
	v_pk_fma_f32 v[10:11], v[10:11], 0.5, v[24:25] op_sel_hi:[1,0,1]
	v_pk_fma_f32 v[8:9], v[8:9], 0.5, v[22:23] op_sel_hi:[1,0,1]
	global_store_dwordx4 v[18:19], v[12:15], off
	global_store_dwordx4 v[18:19], v[8:11], off offset:16
	s_cbranch_vccnz .LBB0_368
	v_pk_mul_f32 v[22:23], v[14:15], v[14:15]
	v_pk_mul_f32 v[24:25], v[12:13], v[12:13]
	v_pk_mul_f32 v[14:15], v[66:67], v[14:15]
	v_pk_mov_b32 v[26:27], v[24:25], v[22:23] op_sel:[1,0]
	v_mov_b32_e32 v25, v23
	v_pk_add_f32 v[22:23], v[26:27], v[24:25]
	v_pk_mul_f32 v[24:25], v[10:11], v[10:11]
	v_pk_mul_f32 v[26:27], v[8:9], v[8:9]
	v_mov_b32_e32 v28, v24
	v_mov_b32_e32 v29, v26
	v_mov_b32_e32 v26, v25
	v_pk_add_f32 v[24:25], v[28:29], v[26:27]
	v_add_f32_e32 v22, v22, v23
	v_add_f32_e32 v22, v22, v25
	v_add_f32_e32 v22, v24, v22
	v_pk_mul_f32 v[12:13], v[64:65], v[12:13]
	v_pk_mul_f32 v[24:25], v[58:59], v[10:11]
	v_pk_mul_f32 v[10:11], v[56:57], v[8:9]
	v_cvt_pk_bf16_f32 v8, v12, v13
	v_cvt_pk_bf16_f32 v9, v14, v15
	v_cvt_pk_bf16_f32 v10, v10, v11
	v_cvt_pk_bf16_f32 v11, v24, v25
	global_store_dwordx4 v[16:17], v[8:11], off
	s_branch .LBB0_369

; __device__ __forceinline__ unsigned cvt_pk_bf16(float lo, float hi) { f32x2 v = {lo, hi}; bf16x2_t_ b = __builtin_convertvector(v, bf16x2_t_); return __builtin_bit_cast(unsigned, b); }
; __device__ __forceinline__ float shfl_xor_l(float v, int o, int lane) { return __int_as_float(__builtin_amdgcn_ds_bpermute((lane ^ o) << 2, __float_as_int(v))); }
;     __device__ __forceinline__ void operator()(const Acc& acc, const Unit& u, int wr, int wc, int fr, int fq) const {
;     ...
;                 for (int bj = 0; bj < 2; ++bj) { f32x4* p0 = (f32x4*)(rowp + bj * HALF); const f32x4* r0 = (const f32x4*)(R + (size_t)row * DM + col0 + bj * HALF); const f32x4 o0 = r0[0] + acc[ai][bj][m][0] * alpha, o1 = r0[1] + acc[ai][bj][m][1] * alpha; p0[0] = o0; p0[1] = o1;
;                     if (gnext) { sq += (o0[0] * o0[0] + o0[1] * o0[1]) + (o0[2] * o0[2] + o0[3] * o0[3]) + (o1[0] * o1[0] + o1[1] * o1[1]) + (o1[2] * o1[2] + o1[3] * o1[3]);
;                         const f32x4 y0 = o0 * gv[bj][0], y1 = o1 * gv[bj][1];
;                         u32x4 w; w.x = cvt_pk_bf16(y0[0], y0[1]); w.y = cvt_pk_bf16(y0[2], y0[3]); w.z = cvt_pk_bf16(y1[0], y1[1]); w.w = cvt_pk_bf16(y1[2], y1[3]);
;                         *(u32x4*)(XNo + (size_t)row * DM + col0 + bj * HALF) = w; } }
;                 if (gnext) { sq += shfl_xor_l(sq, 16, lane); sq += shfl_xor_l(sq, 32, lane); if (fq == 0) part[wc * 256 + ai * HALF + wr * 64 + m * 16 + fr] = sq; }
.LBB0_369:
	s_nop 1
	v_mov_b64_e32 v[8:9], v[210:211]
	v_mov_b64_e32 v[10:11], v[212:213]
	s_and_b64 vcc, exec, s[42:43]
	s_waitcnt lgkmcnt(0)
	v_pk_fma_f32 v[6:7], v[6:7], 0.5, v[10:11] op_sel_hi:[1,0,1]
	v_pk_fma_f32 v[4:5], v[4:5], 0.5, v[8:9] op_sel_hi:[1,0,1]
	s_nop 1
	v_mov_b64_e32 v[8:9], v[214:215]
	v_mov_b64_e32 v[10:11], v[216:217]
	s_waitcnt lgkmcnt(0)
	v_pk_fma_f32 v[2:3], v[2:3], 0.5, v[10:11] op_sel_hi:[1,0,1]
	v_pk_fma_f32 v[0:1], v[0:1], 0.5, v[8:9] op_sel_hi:[1,0,1]
	global_store_dwordx4 v[18:19], v[4:7], off offset:512
	global_store_dwordx4 v[18:19], v[0:3], off offset:528
	s_cbranch_vccnz .LBB0_373
	v_mul_f32_e32 v8, v5, v5
	v_mul_f32_e32 v9, v7, v7
	v_fmac_f32_e32 v8, v4, v4
	v_fmac_f32_e32 v9, v6, v6
	v_add_f32_e32 v8, v8, v9
	v_mul_f32_e32 v9, v1, v1
	v_fmac_f32_e32 v9, v0, v0
	v_add_f32_e32 v8, v8, v9
	v_mul_f32_e32 v9, v3, v3
	v_fmac_f32_e32 v9, v2, v2
	v_add_f32_e32 v8, v9, v8
	v_add_f32_e32 v12, v22, v8
	ds_bpermute_b32 v13, v138, v12
	v_pk_mul_f32 v[10:11], v[44:45], v[0:1]
	v_pk_mul_f32 v[6:7], v[50:51], v[6:7]
	v_pk_mul_f32 v[4:5], v[48:49], v[4:5]
	v_pk_mul_f32 v[8:9], v[46:47], v[2:3]
	s_waitcnt lgkmcnt(0)
	v_add_f32_e32 v0, v12, v13
	ds_bpermute_b32 v1, v137, v0
	v_cvt_pk_bf16_f32 v2, v4, v5
	v_cvt_pk_bf16_f32 v3, v6, v7
	v_cvt_pk_bf16_f32 v4, v10, v11
	v_cvt_pk_bf16_f32 v5, v8, v9
	global_store_dwordx4 v[16:17], v[2:5], off offset:256
	s_and_saveexec_b64 s[6:7], s[44:45]
	s_cbranch_execz .LBB0_372
	s_waitcnt lgkmcnt(0)
	v_add_f32_e32 v0, v0, v1
	ds_write_b32 v136, v0 offset:704

; template <bool FIRST> __device__ __forceinline__ void partialSM(f32x16& p0, f32x16& p1, float& m_reg, f32x16& negm, float& alpha) {
;   const float pmax = rowmax32(p0, p1);
;   alpha = 1.f;
;   if (FIRST) { m_reg = pmax; p0 = p0 - pmax; p1 = p1 - pmax;
; #pragma unroll
;     for (int r = 0; r < 16; ++r) negm[r] = -m_reg; }
;   else if (__builtin_expect(!__all(pmax <= THR2), 0)) { const float dl = fmaxf(pmax, 0.f); m_reg += dl; p0 = p0 - dl; p1 = p1 - dl; alpha = __builtin_amdgcn_exp2f(-dl);
; #pragma unroll
;     for (int r = 0; r < 16; ++r) negm[r] = -m_reg; }
; #pragma unroll
;   for (int r = 0; r < 16; ++r) p0[r] = __builtin_amdgcn_exp2f(p0[r]);
; }
; __device__ __forceinline__ void finishSM(f32x16& p0, f32x16& p1, bf16x8& pa0, bf16x8& pa1, bf16x8& pa2, bf16x8& pa3) {
; #pragma unroll
;   for (int r = 0; r < 16; ++r) p1[r] = __builtin_amdgcn_exp2f(p1[r]);
;     ...
;   PK4(p0, 0, pa0); PK4(p0, 8, pa1); PK4(p1, 0, pa2); PK4(p1, 8, pa3);
;     ...
; }
; template <int DKB> __device__ __forceinline__ void qkt(f32x16& p0, f32x16& p1, const char* Ks, const bf16x8* qr, const f32x16& negm, int r32, int hi) {
; #pragma unroll
;   for (int d0 = 0; d0 < DKB; ++d0) { int cb = (d0 * 16 + hi * 8) * 2;
;     bf16x8 b0 = *reinterpret_cast<const bf16x8*>(Ks + KSWZ(r32, cb));
;     bf16x8 b1 = *reinterpret_cast<const bf16x8*>(Ks + KSWZ(32 + r32, cb));
;     if (d0 == 0) { p0 = __builtin_amdgcn_mfma_f32_32x32x16_bf16(b0, qr[0], negm, 0, 0, 0); p1 = __builtin_amdgcn_mfma_f32_32x32x16_bf16(b1, qr[0], negm, 0, 0, 0); }
;     else { p0 = __builtin_amdgcn_mfma_f32_32x32x16_bf16(b0, qr[d0], p0, 0, 0, 0); p1 = __builtin_amdgcn_mfma_f32_32x32x16_bf16(b1, qr[d0], p1, 0, 0, 0); } }
; }
; __device__ __forceinline__ int v_st(int k, int c) { const int kk = (k & ~0xC) | ((k & 4) << 1) | ((k & 8) >> 1); return ((kk >> 3) * 4 + (c >> 5)) * 512 + ((kk & 7) * 32 + (c & 31)) * 2; }
; __device__ __forceinline__ int v_rd_base(int lane) { return ((lane & 3) << 3) | (((lane >> 2) & 3) << 6) | (((lane >> 4) & 1) << 5) | (((lane >> 5) & 1) << 8); }
; template <int OFF> __device__ __forceinline__ s16x4 tr_read(int vb) {
;   s16x4 r; asm volatile("ds_read_b64_tr_b16 %0, %1 offset:%2" : "=&v"(r) : "v"(vb), "i"(OFF) : "memory"); return r;
; }
; template <int D0> __device__ __forceinline__ void pv_one(f32x16& od, int vb, bf16x8 pa0, bf16x8 pa1, bf16x8 pa2, bf16x8 pa3) {
.Lgqa_h2_skipexp:
	s_add_i32 s6, s54, 0x4000
	s_cmpk_lg_u32 s54, 0x8000
	s_cselect_b32 s7, s6, 0
	v_lshl_add_u64 v[160:161], v[160:161], 0, s[0:1]
	s_and_b64 vcc, exec, s[58:59]
	s_waitcnt lgkmcnt(0)
	s_barrier
	s_cbranch_vccnz .LBB0_717
.LBB0_703:
	s_mov_b32 s6, s55
	s_mov_b32 s55, s7
	s_add_i32 s7, s54, 0
	v_add_u32_e32 v52, s7, v169
	ds_read_b128 v[48:51], v52 offset:57344
	ds_read_b128 v[52:55], v52 offset:49152
	v_exp_f32_e32 v56, v80
	v_exp_f32_e32 v57, v81
	v_exp_f32_e32 v58, v82
	s_waitcnt lgkmcnt(1)
	v_mfma_f32_32x32x16_bf16 v[96:111], v[48:51], v[140:143], v[64:79]
	v_exp_f32_e32 v59, v83
	v_exp_f32_e32 v60, v84
	v_exp_f32_e32 v61, v85
	v_exp_f32_e32 v62, v86
	v_exp_f32_e32 v63, v87
	v_exp_f32_e32 v80, v88
	v_exp_f32_e32 v81, v89
	s_waitcnt lgkmcnt(0)
	v_mfma_f32_32x32x16_bf16 v[112:127], v[52:55], v[140:143], v[64:79]
	v_add_u32_e32 v52, s7, v170
	ds_read_b128 v[48:51], v52 offset:57344
	ds_read_b128 v[52:55], v52 offset:49152
	v_exp_f32_e32 v82, v90
	v_exp_f32_e32 v83, v91
	v_exp_f32_e32 v84, v92
	v_exp_f32_e32 v85, v93
	v_exp_f32_e32 v86, v94
	s_waitcnt lgkmcnt(0)
	v_mfma_f32_32x32x16_bf16 v[112:127], v[52:55], v[136:139], v[112:127]
	v_add_u32_e32 v52, s7, v171
	v_exp_f32_e32 v87, v95
	v_cvt_pk_bf16_f32 v56, v56, v57
	v_cvt_pk_bf16_f32 v57, v58, v59
	v_cvt_pk_bf16_f32 v58, v60, v61
	v_cvt_pk_bf16_f32 v59, v62, v63
	v_cvt_pk_bf16_f32 v60, v80, v81
	v_mfma_f32_32x32x16_bf16 v[96:111], v[48:51], v[136:139], v[96:111]
	ds_read_b128 v[48:51], v52 offset:57344
	ds_read_b128 v[52:55], v52 offset:49152
	v_cvt_pk_bf16_f32 v61, v82, v83
	v_cvt_pk_bf16_f32 v62, v84, v85
	v_cvt_pk_bf16_f32 v63, v86, v87
	v_permlane32_swap_b32_e32 v56, v58
	v_permlane32_swap_b32_e32 v57, v59
	s_waitcnt lgkmcnt(0)
	v_mfma_f32_32x32x16_bf16 v[112:127], v[52:55], v[132:135], v[112:127]
	v_add_u32_e32 v52, s7, v172
	v_permlane32_swap_b32_e32 v60, v62
	v_permlane32_swap_b32_e32 v61, v63
	v_mfma_f32_32x32x16_bf16 v[96:111], v[48:51], v[132:135], v[96:111]
	ds_read_b128 v[48:51], v52 offset:57344
	ds_read_b128 v[52:55], v52 offset:49152
	s_waitcnt lgkmcnt(0)
	v_mfma_f32_32x32x16_bf16 v[112:127], v[52:55], v[128:131], v[112:127]
	v_cvt_pk_bf16_f32 v52, v152, v153
	v_cvt_pk_bf16_f32 v53, v154, v155
	v_cvt_pk_bf16_f32 v54, v156, v158
	v_cvt_pk_bf16_f32 v55, v157, v159
	s_nop 0
	v_permlane32_swap_b32_e32 v52, v54
	v_permlane32_swap_b32_e32 v53, v55
	v_mfma_f32_32x32x16_bf16 v[96:111], v[48:51], v[128:131], v[96:111]
	v_cvt_pk_bf16_f32 v48, v174, v175
	v_cvt_pk_bf16_f32 v50, v188, v189
	v_cvt_pk_bf16_f32 v49, v186, v187
	v_cvt_pk_bf16_f32 v51, v190, v191
	v_permlane32_swap_b32_e32 v48, v50
	s_nop 0
	v_permlane32_swap_b32_e32 v49, v51
	s_mov_b32 s7, 0xfffa7f00
	v_add_co_u32_e32 v80, vcc, s7, v160
	s_nop 1
	v_addc_co_u32_e32 v81, vcc, -1, v161, vcc
	global_load_dwordx4 v[242:245], v[80:81], off offset:256
	global_load_dwordx4 v[238:241], v[80:81], off
	v_add_u32_e32 v174, s6, v164
	ds_read_b64_tr_b16 v[80:81], v174 offset:0
	ds_read_b64_tr_b16 v[82:83], v174 offset:0x800
	ds_read_b64_tr_b16 v[84:85], v174 offset:0x1000
	ds_read_b64_tr_b16 v[86:87], v174 offset:0x1800
	ds_read_b64_tr_b16 v[88:89], v174 offset:0x2000
	ds_read_b64_tr_b16 v[90:91], v174 offset:0x2800
	ds_read_b64_tr_b16 v[92:93], v174 offset:0x3000
	ds_read_b64_tr_b16 v[94:95], v174 offset:0x3800
	s_waitcnt lgkmcnt(0)
	s_nop 0
	v_mfma_f32_32x32x16_bf16 v[0:15], v[48:51], v[80:83], v[0:15]
	v_readlane_b32 s12, v254, 19
	v_readlane_b32 s14, v254, 21
	v_readlane_b32 s15, v254, 22
	v_readlane_b32 s13, v254, 20
	s_nop 0
	v_mov_b64_e32 v[82:83], s[14:15]
	v_mov_b64_e32 v[80:81], s[12:13]
	v_mfma_f32_32x32x16_bf16 v[0:15], v[52:55], v[84:87], v[0:15]
	ds_read_b64_tr_b16 v[84:85], v174 offset:0x200
	ds_read_b64_tr_b16 v[86:87], v174 offset:0xa00
	v_exp_f32_e32 v175, v113
	v_exp_f32_e32 v186, v114
	v_mfma_f32_32x32x16_bf16 v[0:15], v[56:59], v[88:91], v[0:15]
	ds_read_b64_tr_b16 v[88:89], v174 offset:0x1200
	ds_read_b64_tr_b16 v[90:91], v174 offset:0x1a00
	v_exp_f32_e32 v187, v115
	v_exp_f32_e32 v188, v116
	v_mfma_f32_32x32x16_bf16 v[32:47], v[48:51], v[80:83], v[32:47]
	v_exp_f32_e32 v189, v117
	v_exp_f32_e32 v190, v118
	v_exp_f32_e32 v191, v119
	v_mfma_f32_32x32x16_bf16 v[0:15], v[60:63], v[92:95], v[0:15]
	ds_read_b64_tr_b16 v[92:93], v174 offset:0x2200
	ds_read_b64_tr_b16 v[94:95], v174 offset:0x2a00
	ds_read_b64_tr_b16 v[178:179], v174 offset:0x3200
	ds_read_b64_tr_b16 v[180:181], v174 offset:0x3a00
	v_exp_f32_e32 v192, v120
	v_exp_f32_e32 v193, v121
	v_exp_f32_e32 v198, v122
	s_waitcnt lgkmcnt(0)
	v_mfma_f32_32x32x16_bf16 v[32:47], v[52:55], v[80:83], v[32:47]
	v_exp_f32_e32 v174, v112
	v_exp_f32_e32 v199, v123
	v_exp_f32_e32 v200, v124
	v_mfma_f32_32x32x16_bf16 v[16:31], v[48:51], v[84:87], v[16:31]
	v_max_f32_e32 v48, v113, v113
	v_max_f32_e32 v49, v112, v112
	v_max_f32_e32 v48, v49, v48
	v_max3_f32 v48, v48, v114, v115
	v_max3_f32 v48, v48, v116, v117
	v_max3_f32 v48, v48, v118, v119
	v_max3_f32 v48, v48, v120, v121
	v_mfma_f32_32x32x16_bf16 v[16:31], v[52:55], v[88:91], v[16:31]
	v_max3_f32 v48, v48, v122, v123
	v_max3_f32 v48, v48, v124, v125
	v_max3_f32 v48, v48, v126, v127
	v_max3_f32 v48, v48, v96, v97
	v_max3_f32 v48, v48, v98, v99
	v_max3_f32 v48, v48, v100, v101
	v_max3_f32 v48, v48, v102, v103
	v_mfma_f32_32x32x16_bf16 v[16:31], v[56:59], v[92:95], v[16:31]
	v_max3_f32 v48, v48, v104, v105
	v_max3_f32 v48, v48, v106, v107
	v_max3_f32 v48, v48, v108, v109
	v_max3_f32 v48, v48, v110, v111
	v_mov_b32_e32 v49, v48
	s_nop 1
	v_permlane32_swap_b32_e32 v48, v49
	v_mfma_f32_32x32x16_bf16 v[32:47], v[56:59], v[80:83], v[32:47]
	v_max_f32_e32 v49, v49, v49
	v_max_f32_e32 v48, v48, v48
	v_max_f32_e32 v48, v48, v49
	v_cmp_ge_f32_e32 vcc, s92, v48
	s_cmp_eq_u64 vcc, exec
	v_mfma_f32_32x32x16_bf16 v[16:31], v[60:63], v[178:181], v[16:31]
	v_exp_f32_e32 v201, v125
	v_exp_f32_e32 v202, v126
	v_exp_f32_e32 v203, v127
	v_mfma_f32_32x32x16_bf16 v[32:47], v[60:63], v[80:83], v[32:47]
	s_cbranch_scc0 .LBB0_715
	v_mov_b64_e32 v[48:49], v[64:65]
	v_mov_b32_e32 v80, 1.0
	v_mov_b64_e32 v[50:51], v[66:67]
	v_mov_b64_e32 v[52:53], v[68:69]
	v_mov_b64_e32 v[54:55], v[70:71]
	v_mov_b64_e32 v[56:57], v[72:73]
	v_mov_b64_e32 v[58:59], v[74:75]
	v_mov_b64_e32 v[60:61], v[76:77]
	v_mov_b64_e32 v[62:63], v[78:79]

; template <bool FIRST> __device__ __forceinline__ void partialSM(f32x16& p0, f32x16& p1, float& m_reg, f32x16& negm, float& alpha) {
;   const float pmax = rowmax32(p0, p1);
;   alpha = 1.f;
;   if (FIRST) { m_reg = pmax; p0 = p0 - pmax; p1 = p1 - pmax;
; #pragma unroll
;     for (int r = 0; r < 16; ++r) negm[r] = -m_reg; }
;   else if (__builtin_expect(!__all(pmax <= THR2), 0)) { const float dl = fmaxf(pmax, 0.f); m_reg += dl; p0 = p0 - dl; p1 = p1 - dl; alpha = __builtin_amdgcn_exp2f(-dl);
; #pragma unroll
;     for (int r = 0; r < 16; ++r) negm[r] = -m_reg; }
; #pragma unroll
;   for (int r = 0; r < 16; ++r) p0[r] = __builtin_amdgcn_exp2f(p0[r]);
; }
; __device__ __forceinline__ void finishSM(f32x16& p0, f32x16& p1, bf16x8& pa0, bf16x8& pa1, bf16x8& pa2, bf16x8& pa3) {
; #pragma unroll
;   for (int r = 0; r < 16; ++r) p1[r] = __builtin_amdgcn_exp2f(p1[r]);
;     ...
;   PK4(p0, 0, pa0); PK4(p0, 8, pa1); PK4(p1, 0, pa2); PK4(p1, 8, pa3);
;     ...
; }
; template <int DKB> __device__ __forceinline__ void qkt(f32x16& p0, f32x16& p1, const char* Ks, const bf16x8* qr, const f32x16& negm, int r32, int hi) {
; #pragma unroll
;   for (int d0 = 0; d0 < DKB; ++d0) { int cb = (d0 * 16 + hi * 8) * 2;
;     bf16x8 b0 = *reinterpret_cast<const bf16x8*>(Ks + KSWZ(r32, cb));
;     bf16x8 b1 = *reinterpret_cast<const bf16x8*>(Ks + KSWZ(32 + r32, cb));
;     if (d0 == 0) { p0 = __builtin_amdgcn_mfma_f32_32x32x16_bf16(b0, qr[0], negm, 0, 0, 0); p1 = __builtin_amdgcn_mfma_f32_32x32x16_bf16(b1, qr[0], negm, 0, 0, 0); }
;     else { p0 = __builtin_amdgcn_mfma_f32_32x32x16_bf16(b0, qr[d0], p0, 0, 0, 0); p1 = __builtin_amdgcn_mfma_f32_32x32x16_bf16(b1, qr[d0], p1, 0, 0, 0); } }
; }
; __device__ __forceinline__ int v_st(int k, int c) { const int kk = (k & ~0xC) | ((k & 4) << 1) | ((k & 8) >> 1); return ((kk >> 3) * 4 + (c >> 5)) * 512 + ((kk & 7) * 32 + (c & 31)) * 2; }
; __device__ __forceinline__ int v_rd_base(int lane) { return ((lane & 3) << 3) | (((lane >> 2) & 3) << 6) | (((lane >> 4) & 1) << 5) | (((lane >> 5) & 1) << 8); }
; template <int OFF> __device__ __forceinline__ s16x4 tr_read(int vb) {
;   s16x4 r; asm volatile("ds_read_b64_tr_b16 %0, %1 offset:%2" : "=&v"(r) : "v"(vb), "i"(OFF) : "memory"); return r;
; }
; template <int D0> __device__ __forceinline__ void pv_one(f32x16& od, int vb, bf16x8 pa0, bf16x8 pa1, bf16x8 pa2, bf16x8 pa3) {
.Lgqa_h1_skipexp:
	s_waitcnt lgkmcnt(0)
	s_barrier
	v_add_u32_e32 v80, s24, v169
	ds_read_b128 v[178:181], v80 offset:57344
	ds_read_b128 v[80:83], v80 offset:49152
	v_add_u32_e32 v182, s24, v170
	v_exp_f32_e32 v96, v96
	v_exp_f32_e32 v97, v97
	v_exp_f32_e32 v98, v98
	s_waitcnt lgkmcnt(0)
	v_mfma_f32_32x32x16_bf16 v[112:127], v[80:83], v[140:143], v[48:63]
	v_exp_f32_e32 v99, v99
	v_exp_f32_e32 v100, v100
	v_exp_f32_e32 v101, v101
	v_exp_f32_e32 v102, v102
	v_exp_f32_e32 v103, v103
	v_cvt_pk_bf16_f32 v96, v96, v97
	v_cvt_pk_bf16_f32 v97, v98, v99
	v_mfma_f32_32x32x16_bf16 v[80:95], v[178:181], v[140:143], v[48:63]
	ds_read_b128 v[178:181], v182 offset:57344
	ds_read_b128 v[182:185], v182 offset:49152
	v_cvt_pk_bf16_f32 v98, v100, v101
	v_cvt_pk_bf16_f32 v99, v102, v103
	s_nop 0
	v_permlane32_swap_b32_e32 v96, v98
	v_permlane32_swap_b32_e32 v97, v99
	s_waitcnt lgkmcnt(0)
	v_mfma_f32_32x32x16_bf16 v[112:127], v[182:185], v[136:139], v[112:127]
	v_add_u32_e32 v182, s24, v171
	v_mfma_f32_32x32x16_bf16 v[80:95], v[178:181], v[136:139], v[80:95]
	ds_read_b128 v[178:181], v182 offset:57344
	ds_read_b128 v[182:185], v182 offset:49152
	s_waitcnt lgkmcnt(0)
	v_mfma_f32_32x32x16_bf16 v[112:127], v[182:185], v[132:135], v[112:127]
	v_add_u32_e32 v182, s24, v172
	v_mfma_f32_32x32x16_bf16 v[80:95], v[178:181], v[132:135], v[80:95]
	ds_read_b128 v[178:181], v182 offset:57344
	ds_read_b128 v[182:185], v182 offset:49152
	s_waitcnt lgkmcnt(0)
	v_mfma_f32_32x32x16_bf16 v[112:127], v[182:185], v[128:131], v[112:127]
	v_exp_f32_e32 v182, v108
	v_exp_f32_e32 v183, v109
	v_exp_f32_e32 v184, v110
	v_exp_f32_e32 v185, v111
	v_cvt_pk_bf16_f32 v108, v192, v193
	v_cvt_pk_bf16_f32 v109, v198, v199
	v_cvt_pk_bf16_f32 v110, v200, v201
	v_mfma_f32_32x32x16_bf16 v[80:95], v[178:181], v[128:131], v[80:95]
	v_exp_f32_e32 v178, v104
	v_exp_f32_e32 v179, v105
	v_exp_f32_e32 v180, v106
	v_exp_f32_e32 v181, v107
	v_cvt_pk_bf16_f32 v104, v174, v175
	v_cvt_pk_bf16_f32 v105, v186, v187
	v_cvt_pk_bf16_f32 v106, v188, v189
	v_cvt_pk_bf16_f32 v107, v190, v191
	v_cvt_pk_bf16_f32 v111, v202, v203
	v_cvt_pk_bf16_f32 v100, v178, v179
	v_cvt_pk_bf16_f32 v101, v180, v181
	v_cvt_pk_bf16_f32 v102, v182, v183
	v_cvt_pk_bf16_f32 v103, v184, v185
	v_permlane32_swap_b32_e32 v104, v106
	v_permlane32_swap_b32_e32 v105, v107
	v_permlane32_swap_b32_e32 v108, v110
	v_permlane32_swap_b32_e32 v109, v111
	v_permlane32_swap_b32_e32 v100, v102
	v_permlane32_swap_b32_e32 v101, v103
	s_add_i32 s62, s62, 2
	s_cmp_ge_u32 s62, s49
	s_cselect_b64 s[58:59], -1, 0
	s_and_b64 vcc, exec, s[58:59]
	s_cbranch_vccnz .LBB0_711
	v_add_co_u32_e32 v148, vcc, 0xffffff00, v160
	s_nop 1
	v_addc_co_u32_e32 v149, vcc, -1, v161, vcc
	global_load_dwordx4 v[144:147], v[160:161], off
	s_nop 0
	global_load_dwordx4 v[148:151], v[148:149], off
.LBB0_711:
	v_add_u32_e32 v174, s54, v164
	ds_read_b64_tr_b16 v[178:179], v174 offset:0
	ds_read_b64_tr_b16 v[180:181], v174 offset:0x800
	ds_read_b64_tr_b16 v[182:183], v174 offset:0x1000
	ds_read_b64_tr_b16 v[184:185], v174 offset:0x1800
	ds_read_b64_tr_b16 v[230:231], v174 offset:0x2000
	ds_read_b64_tr_b16 v[232:233], v174 offset:0x2800
	ds_read_b64_tr_b16 v[234:235], v174 offset:0x3000
	ds_read_b64_tr_b16 v[236:237], v174 offset:0x3800
	s_waitcnt lgkmcnt(0)
	s_nop 0
	v_mfma_f32_32x32x16_bf16 v[0:15], v[104:107], v[178:181], v[0:15]
	v_readlane_b32 s12, v254, 19
	v_readlane_b32 s14, v254, 21
	v_readlane_b32 s15, v254, 22
	v_readlane_b32 s13, v254, 20
	s_nop 0
	v_mov_b64_e32 v[180:181], s[14:15]
	v_mov_b64_e32 v[178:179], s[12:13]
	v_mfma_f32_32x32x16_bf16 v[0:15], v[108:111], v[182:185], v[0:15]
	ds_read_b64_tr_b16 v[182:183], v174 offset:0x200
	ds_read_b64_tr_b16 v[184:185], v174 offset:0xa00
	v_exp_f32_e32 v175, v113
	v_exp_f32_e32 v186, v114
	v_mfma_f32_32x32x16_bf16 v[0:15], v[96:99], v[230:233], v[0:15]
	ds_read_b64_tr_b16 v[230:231], v174 offset:0x1200
	ds_read_b64_tr_b16 v[232:233], v174 offset:0x1a00
	v_exp_f32_e32 v187, v115
	v_exp_f32_e32 v188, v116
	v_mfma_f32_32x32x16_bf16 v[32:47], v[104:107], v[178:181], v[32:47]
	v_exp_f32_e32 v189, v117
	v_exp_f32_e32 v190, v118
	v_exp_f32_e32 v191, v119
	v_mfma_f32_32x32x16_bf16 v[0:15], v[100:103], v[234:237], v[0:15]
	ds_read_b64_tr_b16 v[234:235], v174 offset:0x2200
	ds_read_b64_tr_b16 v[236:237], v174 offset:0x2a00
	ds_read_b64_tr_b16 v[198:199], v174 offset:0x3200
	ds_read_b64_tr_b16 v[200:201], v174 offset:0x3a00
	v_exp_f32_e32 v152, v120
	v_exp_f32_e32 v153, v121
	v_exp_f32_e32 v154, v122
	s_waitcnt lgkmcnt(0)
	v_mfma_f32_32x32x16_bf16 v[32:47], v[108:111], v[178:181], v[32:47]
	v_exp_f32_e32 v174, v112
	v_exp_f32_e32 v155, v123
	v_exp_f32_e32 v156, v124
	v_mfma_f32_32x32x16_bf16 v[16:31], v[104:107], v[182:185], v[16:31]
	v_max_f32_e32 v104, v113, v113
	v_max_f32_e32 v105, v112, v112
	v_max_f32_e32 v104, v105, v104
	v_max3_f32 v104, v104, v114, v115
	v_max3_f32 v104, v104, v116, v117
	v_max3_f32 v104, v104, v118, v119
	v_max3_f32 v104, v104, v120, v121
	v_mfma_f32_32x32x16_bf16 v[16:31], v[108:111], v[230:233], v[16:31]
	v_max3_f32 v104, v104, v122, v123
	v_max3_f32 v104, v104, v124, v125
	v_max3_f32 v104, v104, v126, v127
	v_max3_f32 v104, v104, v80, v81
	v_max3_f32 v104, v104, v82, v83
	v_max3_f32 v104, v104, v84, v85
	v_max3_f32 v104, v104, v86, v87
	v_mfma_f32_32x32x16_bf16 v[16:31], v[96:99], v[234:237], v[16:31]
	v_max3_f32 v104, v104, v88, v89
	v_max3_f32 v104, v104, v90, v91
	v_max3_f32 v104, v104, v92, v93
	v_max3_f32 v104, v104, v94, v95
	v_mov_b32_e32 v105, v104
	s_nop 1
	v_permlane32_swap_b32_e32 v104, v105
	v_mfma_f32_32x32x16_bf16 v[32:47], v[96:99], v[178:181], v[32:47]
	v_max_f32_e32 v96, v105, v105
	v_max_f32_e32 v97, v104, v104
	v_max_f32_e32 v97, v97, v96
	v_cmp_ge_f32_e32 vcc, s92, v97
	v_mov_b32_e32 v96, 1.0
	s_cmp_eq_u64 vcc, exec
	v_mfma_f32_32x32x16_bf16 v[16:31], v[100:103], v[198:201], v[16:31]
	v_exp_f32_e32 v158, v125
	v_exp_f32_e32 v157, v126
	v_exp_f32_e32 v159, v127
	v_mfma_f32_32x32x16_bf16 v[32:47], v[100:103], v[178:181], v[32:47]
	s_cbranch_scc0 .LBB0_716
.LBB0_712:
	s_add_i32 s6, s55, 0x4000
	s_cmpk_lg_u32 s55, 0x8000
	s_cselect_b32 s54, s6, 0
	s_waitcnt vmcnt(2)
	v_add_u32_e32 v97, s54, v167
	s_waitcnt vmcnt(0)
	ds_write_b128 v97, v[242:245]
	v_add_u32_e32 v97, s54, v168
	v_cmp_gt_f32_e32 vcc, 1.0, v96
	ds_write_b128 v97, v[238:241] offset:49152
	s_cbranch_vccz .Lgqa_h2_skipexp
	s_and_saveexec_b64 s[6:7], s[40:41]
	s_cbranch_execz .LBB0_701
	ds_write_b32 v165, v96 offset:128
	s_branch .LBB0_701

; __device__ __forceinline__ unsigned cvt_pk_bf16(float lo, float hi) { f32x2 v = {lo, hi}; bf16x2_t_ b = __builtin_convertvector(v, bf16x2_t_); return __builtin_bit_cast(unsigned, b); }
; __device__ __forceinline__ float shfl_xor_l(float v, int o, int lane) { return __int_as_float(__builtin_amdgcn_ds_bpermute((lane ^ o) << 2, __float_as_int(v))); }
;     __device__ __forceinline__ void operator()(const Acc& acc, const Unit& u, int wr, int wc, int fr, int fq) const {
;     ...
;         const int row0 = u.pm * BM + wr * 64 + fr, col0 = u.pn * BM + wc * 32 + 8 * fq; const int lane = fr + 16 * fq;
;         f32x4 gv[2][2];
;         if (gnext) {
; #pragma unroll
;             for (int bj = 0; bj < 2; ++bj)
; #pragma unroll
;                 for (int n = 0; n < 2; ++n) gv[bj][n] = *(const f32x4*)(gnext + col0 + bj * HALF + 4 * n); }
; #pragma unroll
;         for (int ai = 0; ai < 2; ++ai)
; #pragma unroll
;             for (int m = 0; m < 4; ++m) { const int row = row0 + ai * HALF + m * 16; float* rowp = X + (size_t)row * DM + col0; float sq = 0.f;
; #pragma unroll
;                 for (int bj = 0; bj < 2; ++bj) { f32x4* p0 = (f32x4*)(rowp + bj * HALF); const f32x4* r0 = (const f32x4*)(R + (size_t)row * DM + col0 + bj * HALF); const f32x4 o0 = r0[0] + acc[ai][bj][m][0] * alpha, o1 = r0[1] + acc[ai][bj][m][1] * alpha; p0[0] = o0; p0[1] = o1;
;                     if (gnext) { sq += (o0[0] * o0[0] + o0[1] * o0[1]) + (o0[2] * o0[2] + o0[3] * o0[3]) + (o1[0] * o1[0] + o1[1] * o1[1]) + (o1[2] * o1[2] + o1[3] * o1[3]);
;                         const f32x4 y0 = o0 * gv[bj][0], y1 = o1 * gv[bj][1];
;                         u32x4 w; w.x = cvt_pk_bf16(y0[0], y0[1]); w.y = cvt_pk_bf16(y0[2], y0[3]); w.z = cvt_pk_bf16(y1[0], y1[1]); w.w = cvt_pk_bf16(y1[2], y1[3]);
;                         *(u32x4*)(XNo + (size_t)row * DM + col0 + bj * HALF) = w; } }
;                 if (gnext) { sq += shfl_xor_l(sq, 16, lane); sq += shfl_xor_l(sq, 32, lane); if (fq == 0) part[wc * 256 + ai * HALF + wr * 64 + m * 16 + fr] = sq; }
.LBB0_1004:
	s_lshl_b32 s86, s44, 8
	v_readlane_b32 s3, v254, 1
	v_and_b32_e32 v147, 15, v159
	s_add_i32 s3, s86, s3
	v_or_b32_e32 v146, s3, v147
	v_lshlrev_b32_e32 v150, 2, v159
	v_lshl_add_u32 v160, v147, 2, s9
	v_ashrrev_i32_e32 v147, 31, v146
	v_lshl_add_u64 v[148:149], v[144:145], 2, s[18:19]
	v_xor_b32_e32 v162, 64, v150
	v_xor_b32_e32 v161, 0x80, v150
	v_lshlrev_b64 v[150:151], 12, v[146:147]
	v_lshl_add_u64 v[150:151], v[148:149], 0, v[150:151]
	global_load_dwordx4 v[178:181], v[150:151], off
	global_load_dwordx4 v[182:185], v[150:151], off offset:16
	global_load_dwordx4 v[186:189], v[150:151], off offset:512
	global_load_dwordx4 v[190:193], v[150:151], off offset:528
	v_lshl_add_u64 v[144:145], v[144:145], 1, s[56:57]
	v_cmp_gt_u32_e64 s[44:45], 16, v159
	s_and_b64 vcc, exec, s[42:43]
	s_waitcnt vmcnt(0) lgkmcnt(0)
	s_nop 1
	v_mov_b64_e32 v[164:165], v[178:179]
	v_mov_b64_e32 v[166:167], v[180:181]
	v_pk_add_f32 v[142:143], v[142:143], v[166:167]
	v_pk_add_f32 v[140:141], v[140:141], v[164:165]
	s_nop 1
	v_mov_b64_e32 v[164:165], v[182:183]
	v_mov_b64_e32 v[166:167], v[184:185]
	s_waitcnt lgkmcnt(0)
	v_pk_add_f32 v[138:139], v[138:139], v[166:167]
	v_pk_add_f32 v[136:137], v[136:137], v[164:165]
	global_store_dwordx4 v[150:151], v[140:143], off
	global_store_dwordx4 v[150:151], v[136:139], off offset:16
	s_cbranch_vccnz .LBB0_1051
	v_lshlrev_b64 v[164:165], 10, v[146:147]
	v_mul_f32_e32 v147, v141, v141
	v_mul_f32_e32 v163, v143, v143
	v_fmac_f32_e32 v147, v140, v140
	v_fmac_f32_e32 v163, v142, v142
	v_add_f32_e32 v147, v147, v163
	v_mul_f32_e32 v163, v137, v137
	v_fmac_f32_e32 v163, v136, v136
	v_add_f32_e32 v147, v147, v163
	v_mul_f32_e32 v163, v139, v139
	v_fmac_f32_e32 v163, v138, v138
	v_pk_mul_f32 v[142:143], v[54:55], v[142:143]
	v_pk_mul_f32 v[140:141], v[52:53], v[140:141]
	v_pk_mul_f32 v[166:167], v[50:51], v[138:139]
	v_pk_mul_f32 v[138:139], v[48:49], v[136:137]
	v_lshl_add_u64 v[164:165], v[164:165], 1, v[144:145]
	v_cvt_pk_bf16_f32 v136, v140, v141
	v_cvt_pk_bf16_f32 v137, v142, v143
	v_cvt_pk_bf16_f32 v138, v138, v139
	v_cvt_pk_bf16_f32 v139, v166, v167
	global_store_dwordx4 v[164:165], v[136:139], off
	s_nop 1
	v_mov_b64_e32 v[136:137], v[186:187]
	v_mov_b64_e32 v[138:139], v[188:189]
	v_add_f32_e32 v147, v163, v147
	s_nop 1
	v_mov_b64_e32 v[140:141], v[190:191]
	v_mov_b64_e32 v[142:143], v[192:193]
	s_waitcnt lgkmcnt(0)
	v_pk_add_f32 v[138:139], v[134:135], v[138:139]
	v_pk_add_f32 v[136:137], v[132:133], v[136:137]
	v_mul_f32_e32 v166, v139, v139
	v_mul_f32_e32 v163, v137, v137
	v_pk_add_f32 v[140:141], v[124:125], v[140:141]
	v_fmac_f32_e32 v163, v136, v136
	v_fmac_f32_e32 v166, v138, v138
	v_add_f32_e32 v163, v163, v166
	v_mul_f32_e32 v166, v141, v141
	v_pk_add_f32 v[142:143], v[126:127], v[142:143]
	v_fmac_f32_e32 v166, v140, v140
	v_add_f32_e32 v163, v163, v166
	v_mul_f32_e32 v166, v143, v143
	v_fmac_f32_e32 v166, v142, v142
	global_store_dwordx4 v[150:151], v[136:139], off offset:512
	global_store_dwordx4 v[150:151], v[140:143], off offset:528
	v_add_f32_e32 v163, v166, v163
	v_pk_mul_f32 v[138:139], v[46:47], v[138:139]
	v_pk_mul_f32 v[136:137], v[44:45], v[136:137]
	v_pk_mul_f32 v[142:143], v[42:43], v[142:143]
	v_pk_mul_f32 v[140:141], v[40:41], v[140:141]
	v_add_f32_e32 v147, v147, v163
	v_cvt_pk_bf16_f32 v136, v136, v137
	v_cvt_pk_bf16_f32 v137, v138, v139
	v_cvt_pk_bf16_f32 v138, v140, v141
	v_cvt_pk_bf16_f32 v139, v142, v143
	global_store_dwordx4 v[164:165], v[136:139], off offset:256
	ds_bpermute_b32 v136, v162, v147
	s_waitcnt lgkmcnt(0)
	v_add_f32_e32 v136, v147, v136
	ds_bpermute_b32 v137, v161, v136
	s_and_saveexec_b64 s[6:7], s[44:45]
	s_cbranch_execz .LBB0_1007
	s_waitcnt lgkmcnt(0)
	v_add_f32_e32 v136, v136, v137
	ds_write_b32 v160, v136

; __device__ __forceinline__ unsigned cvt_pk_bf16(float lo, float hi) { f32x2 v = {lo, hi}; bf16x2_t_ b = __builtin_convertvector(v, bf16x2_t_); return __builtin_bit_cast(unsigned, b); }
; __device__ __forceinline__ float shfl_xor_l(float v, int o, int lane) { return __int_as_float(__builtin_amdgcn_ds_bpermute((lane ^ o) << 2, __float_as_int(v))); }
;     __device__ __forceinline__ void operator()(const Acc& acc, const Unit& u, int wr, int wc, int fr, int fq) const {
;     ...
;             for (int m = 0; m < 4; ++m) { const int row = row0 + ai * HALF + m * 16; float* rowp = X + (size_t)row * DM + col0; float sq = 0.f;
; #pragma unroll
;                 for (int bj = 0; bj < 2; ++bj) { f32x4* p0 = (f32x4*)(rowp + bj * HALF); const f32x4* r0 = (const f32x4*)(R + (size_t)row * DM + col0 + bj * HALF); const f32x4 o0 = r0[0] + acc[ai][bj][m][0] * alpha, o1 = r0[1] + acc[ai][bj][m][1] * alpha; p0[0] = o0; p0[1] = o1;
;                     if (gnext) { sq += (o0[0] * o0[0] + o0[1] * o0[1]) + (o0[2] * o0[2] + o0[3] * o0[3]) + (o1[0] * o1[0] + o1[1] * o1[1]) + (o1[2] * o1[2] + o1[3] * o1[3]);
;                         const f32x4 y0 = o0 * gv[bj][0], y1 = o1 * gv[bj][1];
;                         u32x4 w; w.x = cvt_pk_bf16(y0[0], y0[1]); w.y = cvt_pk_bf16(y0[2], y0[3]); w.z = cvt_pk_bf16(y1[0], y1[1]); w.w = cvt_pk_bf16(y1[2], y1[3]);
;                         *(u32x4*)(XNo + (size_t)row * DM + col0 + bj * HALF) = w; } }
;                 if (gnext) { sq += shfl_xor_l(sq, 16, lane); sq += shfl_xor_l(sq, 32, lane); if (fq == 0) part[wc * 256 + ai * HALF + wr * 64 + m * 16 + fr] = sq; }
.LBB0_1008:
	s_waitcnt lgkmcnt(0)
	s_nop 1
	v_mov_b64_e32 v[136:137], v[186:187]
	v_mov_b64_e32 v[138:139], v[188:189]
	s_waitcnt lgkmcnt(0)
	v_pk_add_f32 v[134:135], v[134:135], v[138:139]
	v_pk_add_f32 v[132:133], v[132:133], v[136:137]
	s_nop 1
	v_mov_b64_e32 v[136:137], v[190:191]
	v_mov_b64_e32 v[138:139], v[192:193]
	s_waitcnt lgkmcnt(0)
	v_pk_add_f32 v[126:127], v[126:127], v[138:139]
	v_pk_add_f32 v[124:125], v[124:125], v[136:137]
	global_store_dwordx4 v[150:151], v[132:135], off offset:512
	global_store_dwordx4 v[150:151], v[124:127], off offset:528
.LBB0_1009:
	s_nop 0
	v_or_b32_e32 v134, 16, v146
	v_ashrrev_i32_e32 v135, 31, v134
	v_lshlrev_b64 v[124:125], 12, v[134:135]
	v_lshl_add_u64 v[132:133], v[148:149], 0, v[124:125]
	global_load_dwordx4 v[178:181], v[132:133], off
	global_load_dwordx4 v[182:185], v[132:133], off offset:16
	global_load_dwordx4 v[186:189], v[132:133], off offset:512
	global_load_dwordx4 v[190:193], v[132:133], off offset:528
	s_and_b64 vcc, exec, s[42:43]
	s_waitcnt vmcnt(0) lgkmcnt(0)
	s_nop 1
	v_mov_b64_e32 v[124:125], v[178:179]
	v_mov_b64_e32 v[126:127], v[180:181]
	v_pk_add_f32 v[126:127], v[130:131], v[126:127]
	v_pk_add_f32 v[124:125], v[128:129], v[124:125]
	s_nop 1
	v_mov_b64_e32 v[128:129], v[182:183]
	v_mov_b64_e32 v[130:131], v[184:185]
	s_waitcnt lgkmcnt(0)
	v_pk_add_f32 v[122:123], v[122:123], v[130:131]
	v_pk_add_f32 v[120:121], v[120:121], v[128:129]
	global_store_dwordx4 v[132:133], v[124:127], off
	global_store_dwordx4 v[132:133], v[120:123], off offset:16
	s_cbranch_vccnz .LBB0_1052
	v_mul_f32_e32 v130, v125, v125
	v_mul_f32_e32 v131, v127, v127
	v_fmac_f32_e32 v130, v124, v124
	v_fmac_f32_e32 v131, v126, v126
	v_add_f32_e32 v130, v130, v131
	v_mul_f32_e32 v131, v121, v121
	v_fmac_f32_e32 v131, v120, v120
	v_add_f32_e32 v130, v130, v131
	v_mul_f32_e32 v131, v123, v123
	v_fmac_f32_e32 v131, v122, v122
	v_lshlrev_b64 v[128:129], 10, v[134:135]
	v_add_f32_e32 v134, v131, v130
	v_pk_mul_f32 v[126:127], v[54:55], v[126:127]
	v_pk_mul_f32 v[124:125], v[52:53], v[124:125]
	v_pk_mul_f32 v[130:131], v[50:51], v[122:123]
	v_pk_mul_f32 v[122:123], v[48:49], v[120:121]
	v_lshl_add_u64 v[128:129], v[128:129], 1, v[144:145]
	v_cvt_pk_bf16_f32 v120, v124, v125
	v_cvt_pk_bf16_f32 v121, v126, v127
	v_cvt_pk_bf16_f32 v122, v122, v123
	v_cvt_pk_bf16_f32 v123, v130, v131
	global_store_dwordx4 v[128:129], v[120:123], off
	s_nop 1
	v_mov_b64_e32 v[120:121], v[186:187]
	v_mov_b64_e32 v[122:123], v[188:189]
	s_nop 0
	s_nop 1
	v_mov_b64_e32 v[124:125], v[190:191]
	v_mov_b64_e32 v[126:127], v[192:193]
	s_waitcnt lgkmcnt(0)
	v_pk_add_f32 v[122:123], v[118:119], v[122:123]
	v_pk_add_f32 v[120:121], v[116:117], v[120:121]
	v_mul_f32_e32 v131, v123, v123
	v_mul_f32_e32 v130, v121, v121
	v_pk_add_f32 v[124:125], v[108:109], v[124:125]
	v_fmac_f32_e32 v130, v120, v120
	v_fmac_f32_e32 v131, v122, v122
	v_add_f32_e32 v130, v130, v131
	v_mul_f32_e32 v131, v125, v125
	v_pk_add_f32 v[126:127], v[110:111], v[126:127]
	v_fmac_f32_e32 v131, v124, v124
	v_add_f32_e32 v130, v130, v131
	v_mul_f32_e32 v131, v127, v127
	v_fmac_f32_e32 v131, v126, v126
	global_store_dwordx4 v[132:133], v[120:123], off offset:512
	global_store_dwordx4 v[132:133], v[124:127], off offset:528
	v_add_f32_e32 v130, v131, v130
	v_pk_mul_f32 v[122:123], v[46:47], v[122:123]
	v_pk_mul_f32 v[120:121], v[44:45], v[120:121]
	v_pk_mul_f32 v[126:127], v[42:43], v[126:127]
	v_pk_mul_f32 v[124:125], v[40:41], v[124:125]
	v_add_f32_e32 v130, v134, v130
	v_cvt_pk_bf16_f32 v120, v120, v121
	v_cvt_pk_bf16_f32 v121, v122, v123
	v_cvt_pk_bf16_f32 v122, v124, v125
	v_cvt_pk_bf16_f32 v123, v126, v127
	global_store_dwordx4 v[128:129], v[120:123], off offset:256
	ds_bpermute_b32 v120, v162, v130
	s_waitcnt lgkmcnt(0)
	v_add_f32_e32 v120, v130, v120
	ds_bpermute_b32 v121, v161, v120
	s_and_saveexec_b64 s[6:7], s[44:45]
	s_cbranch_execz .LBB0_1012
	s_waitcnt lgkmcnt(0)
	v_add_f32_e32 v120, v120, v121
	ds_write_b32 v160, v120 offset:64

; __device__ __forceinline__ unsigned cvt_pk_bf16(float lo, float hi) { f32x2 v = {lo, hi}; bf16x2_t_ b = __builtin_convertvector(v, bf16x2_t_); return __builtin_bit_cast(unsigned, b); }
; __device__ __forceinline__ float shfl_xor_l(float v, int o, int lane) { return __int_as_float(__builtin_amdgcn_ds_bpermute((lane ^ o) << 2, __float_as_int(v))); }
;     __device__ __forceinline__ void operator()(const Acc& acc, const Unit& u, int wr, int wc, int fr, int fq) const {
;     ...
;             for (int m = 0; m < 4; ++m) { const int row = row0 + ai * HALF + m * 16; float* rowp = X + (size_t)row * DM + col0; float sq = 0.f;
; #pragma unroll
;                 for (int bj = 0; bj < 2; ++bj) { f32x4* p0 = (f32x4*)(rowp + bj * HALF); const f32x4* r0 = (const f32x4*)(R + (size_t)row * DM + col0 + bj * HALF); const f32x4 o0 = r0[0] + acc[ai][bj][m][0] * alpha, o1 = r0[1] + acc[ai][bj][m][1] * alpha; p0[0] = o0; p0[1] = o1;
;                     if (gnext) { sq += (o0[0] * o0[0] + o0[1] * o0[1]) + (o0[2] * o0[2] + o0[3] * o0[3]) + (o1[0] * o1[0] + o1[1] * o1[1]) + (o1[2] * o1[2] + o1[3] * o1[3]);
;                         const f32x4 y0 = o0 * gv[bj][0], y1 = o1 * gv[bj][1];
;                         u32x4 w; w.x = cvt_pk_bf16(y0[0], y0[1]); w.y = cvt_pk_bf16(y0[2], y0[3]); w.z = cvt_pk_bf16(y1[0], y1[1]); w.w = cvt_pk_bf16(y1[2], y1[3]);
;                         *(u32x4*)(XNo + (size_t)row * DM + col0 + bj * HALF) = w; } }
;                 if (gnext) { sq += shfl_xor_l(sq, 16, lane); sq += shfl_xor_l(sq, 32, lane); if (fq == 0) part[wc * 256 + ai * HALF + wr * 64 + m * 16 + fr] = sq; }
.LBB0_1013:
	s_waitcnt lgkmcnt(0)
	s_nop 1
	v_mov_b64_e32 v[120:121], v[186:187]
	v_mov_b64_e32 v[122:123], v[188:189]
	s_waitcnt lgkmcnt(0)
	v_pk_add_f32 v[118:119], v[118:119], v[122:123]
	v_pk_add_f32 v[116:117], v[116:117], v[120:121]
	s_nop 1
	v_mov_b64_e32 v[120:121], v[190:191]
	v_mov_b64_e32 v[122:123], v[192:193]
	s_waitcnt lgkmcnt(0)
	v_pk_add_f32 v[110:111], v[110:111], v[122:123]
	v_pk_add_f32 v[108:109], v[108:109], v[120:121]
	global_store_dwordx4 v[132:133], v[116:119], off offset:512
	global_store_dwordx4 v[132:133], v[108:111], off offset:528
.LBB0_1014:
	s_nop 0
	v_or_b32_e32 v118, 32, v146
	v_ashrrev_i32_e32 v119, 31, v118
	v_lshlrev_b64 v[108:109], 12, v[118:119]
	v_lshl_add_u64 v[116:117], v[148:149], 0, v[108:109]
	global_load_dwordx4 v[178:181], v[116:117], off
	global_load_dwordx4 v[182:185], v[116:117], off offset:16
	global_load_dwordx4 v[186:189], v[116:117], off offset:512
	global_load_dwordx4 v[190:193], v[116:117], off offset:528
	s_and_b64 vcc, exec, s[42:43]
	s_waitcnt vmcnt(0) lgkmcnt(0)
	s_nop 1
	v_mov_b64_e32 v[108:109], v[178:179]
	v_mov_b64_e32 v[110:111], v[180:181]
	v_pk_add_f32 v[110:111], v[114:115], v[110:111]
	v_pk_add_f32 v[108:109], v[112:113], v[108:109]
	s_nop 1
	v_mov_b64_e32 v[112:113], v[182:183]
	v_mov_b64_e32 v[114:115], v[184:185]
	s_waitcnt lgkmcnt(0)
	v_pk_add_f32 v[106:107], v[106:107], v[114:115]
	v_pk_add_f32 v[104:105], v[104:105], v[112:113]
	global_store_dwordx4 v[116:117], v[108:111], off
	global_store_dwordx4 v[116:117], v[104:107], off offset:16
	s_cbranch_vccnz .LBB0_1053
	v_mul_f32_e32 v114, v109, v109
	v_mul_f32_e32 v115, v111, v111
	v_fmac_f32_e32 v114, v108, v108
	v_fmac_f32_e32 v115, v110, v110
	v_add_f32_e32 v114, v114, v115
	v_mul_f32_e32 v115, v105, v105
	v_fmac_f32_e32 v115, v104, v104
	v_add_f32_e32 v114, v114, v115
	v_mul_f32_e32 v115, v107, v107
	v_fmac_f32_e32 v115, v106, v106
	v_lshlrev_b64 v[112:113], 10, v[118:119]
	v_add_f32_e32 v118, v115, v114
	v_pk_mul_f32 v[110:111], v[54:55], v[110:111]
	v_pk_mul_f32 v[108:109], v[52:53], v[108:109]
	v_pk_mul_f32 v[114:115], v[50:51], v[106:107]
	v_pk_mul_f32 v[106:107], v[48:49], v[104:105]
	v_lshl_add_u64 v[112:113], v[112:113], 1, v[144:145]
	v_cvt_pk_bf16_f32 v104, v108, v109
	v_cvt_pk_bf16_f32 v105, v110, v111
	v_cvt_pk_bf16_f32 v106, v106, v107
	v_cvt_pk_bf16_f32 v107, v114, v115
	global_store_dwordx4 v[112:113], v[104:107], off
	s_nop 1
	v_mov_b64_e32 v[104:105], v[186:187]
	v_mov_b64_e32 v[106:107], v[188:189]
	s_nop 0
	s_nop 1
	v_mov_b64_e32 v[108:109], v[190:191]
	v_mov_b64_e32 v[110:111], v[192:193]
	s_waitcnt lgkmcnt(0)
	v_pk_add_f32 v[106:107], v[102:103], v[106:107]
	v_pk_add_f32 v[104:105], v[100:101], v[104:105]
	v_mul_f32_e32 v115, v107, v107
	v_mul_f32_e32 v114, v105, v105
	v_pk_add_f32 v[108:109], v[92:93], v[108:109]
	v_fmac_f32_e32 v114, v104, v104
	v_fmac_f32_e32 v115, v106, v106
	v_add_f32_e32 v114, v114, v115
	v_mul_f32_e32 v115, v109, v109
	v_pk_add_f32 v[110:111], v[94:95], v[110:111]
	v_fmac_f32_e32 v115, v108, v108
	v_add_f32_e32 v114, v114, v115
	v_mul_f32_e32 v115, v111, v111
	v_fmac_f32_e32 v115, v110, v110
	global_store_dwordx4 v[116:117], v[104:107], off offset:512
	global_store_dwordx4 v[116:117], v[108:111], off offset:528
	v_add_f32_e32 v114, v115, v114
	v_pk_mul_f32 v[106:107], v[46:47], v[106:107]
	v_pk_mul_f32 v[104:105], v[44:45], v[104:105]
	v_pk_mul_f32 v[110:111], v[42:43], v[110:111]
	v_pk_mul_f32 v[108:109], v[40:41], v[108:109]
	v_add_f32_e32 v114, v118, v114
	v_cvt_pk_bf16_f32 v104, v104, v105
	v_cvt_pk_bf16_f32 v105, v106, v107
	v_cvt_pk_bf16_f32 v106, v108, v109
	v_cvt_pk_bf16_f32 v107, v110, v111
	global_store_dwordx4 v[112:113], v[104:107], off offset:256
	ds_bpermute_b32 v104, v162, v114
	s_waitcnt lgkmcnt(0)
	v_add_f32_e32 v104, v114, v104
	ds_bpermute_b32 v105, v161, v104
	s_and_saveexec_b64 s[6:7], s[44:45]
	s_cbranch_execz .LBB0_1017
	s_waitcnt lgkmcnt(0)
	v_add_f32_e32 v104, v104, v105
	ds_write_b32 v160, v104 offset:128

; __device__ __forceinline__ unsigned cvt_pk_bf16(float lo, float hi) { f32x2 v = {lo, hi}; bf16x2_t_ b = __builtin_convertvector(v, bf16x2_t_); return __builtin_bit_cast(unsigned, b); }
; __device__ __forceinline__ float shfl_xor_l(float v, int o, int lane) { return __int_as_float(__builtin_amdgcn_ds_bpermute((lane ^ o) << 2, __float_as_int(v))); }
;     __device__ __forceinline__ void operator()(const Acc& acc, const Unit& u, int wr, int wc, int fr, int fq) const {
;     ...
;             for (int m = 0; m < 4; ++m) { const int row = row0 + ai * HALF + m * 16; float* rowp = X + (size_t)row * DM + col0; float sq = 0.f;
; #pragma unroll
;                 for (int bj = 0; bj < 2; ++bj) { f32x4* p0 = (f32x4*)(rowp + bj * HALF); const f32x4* r0 = (const f32x4*)(R + (size_t)row * DM + col0 + bj * HALF); const f32x4 o0 = r0[0] + acc[ai][bj][m][0] * alpha, o1 = r0[1] + acc[ai][bj][m][1] * alpha; p0[0] = o0; p0[1] = o1;
;                     if (gnext) { sq += (o0[0] * o0[0] + o0[1] * o0[1]) + (o0[2] * o0[2] + o0[3] * o0[3]) + (o1[0] * o1[0] + o1[1] * o1[1]) + (o1[2] * o1[2] + o1[3] * o1[3]);
;                         const f32x4 y0 = o0 * gv[bj][0], y1 = o1 * gv[bj][1];
;                         u32x4 w; w.x = cvt_pk_bf16(y0[0], y0[1]); w.y = cvt_pk_bf16(y0[2], y0[3]); w.z = cvt_pk_bf16(y1[0], y1[1]); w.w = cvt_pk_bf16(y1[2], y1[3]);
;                         *(u32x4*)(XNo + (size_t)row * DM + col0 + bj * HALF) = w; } }
;                 if (gnext) { sq += shfl_xor_l(sq, 16, lane); sq += shfl_xor_l(sq, 32, lane); if (fq == 0) part[wc * 256 + ai * HALF + wr * 64 + m * 16 + fr] = sq; }
.LBB0_1018:
	s_waitcnt lgkmcnt(0)
	s_nop 1
	v_mov_b64_e32 v[104:105], v[186:187]
	v_mov_b64_e32 v[106:107], v[188:189]
	s_waitcnt lgkmcnt(0)
	v_pk_add_f32 v[102:103], v[102:103], v[106:107]
	v_pk_add_f32 v[100:101], v[100:101], v[104:105]
	s_nop 1
	v_mov_b64_e32 v[104:105], v[190:191]
	v_mov_b64_e32 v[106:107], v[192:193]
	s_waitcnt lgkmcnt(0)
	v_pk_add_f32 v[94:95], v[94:95], v[106:107]
	v_pk_add_f32 v[92:93], v[92:93], v[104:105]
	global_store_dwordx4 v[116:117], v[100:103], off offset:512
	global_store_dwordx4 v[116:117], v[92:95], off offset:528
.LBB0_1019:
	s_nop 0
	v_or_b32_e32 v102, 48, v146
	v_ashrrev_i32_e32 v103, 31, v102
	v_lshlrev_b64 v[92:93], 12, v[102:103]
	v_lshl_add_u64 v[100:101], v[148:149], 0, v[92:93]
	global_load_dwordx4 v[178:181], v[100:101], off
	global_load_dwordx4 v[182:185], v[100:101], off offset:16
	global_load_dwordx4 v[186:189], v[100:101], off offset:512
	global_load_dwordx4 v[190:193], v[100:101], off offset:528
	s_and_b64 vcc, exec, s[42:43]
	s_waitcnt vmcnt(0) lgkmcnt(0)
	s_nop 1
	v_mov_b64_e32 v[92:93], v[178:179]
	v_mov_b64_e32 v[94:95], v[180:181]
	v_pk_add_f32 v[94:95], v[98:99], v[94:95]
	v_pk_add_f32 v[92:93], v[96:97], v[92:93]
	s_nop 1
	v_mov_b64_e32 v[96:97], v[182:183]
	v_mov_b64_e32 v[98:99], v[184:185]
	s_waitcnt lgkmcnt(0)
	v_pk_add_f32 v[90:91], v[90:91], v[98:99]
	v_pk_add_f32 v[88:89], v[88:89], v[96:97]
	global_store_dwordx4 v[100:101], v[92:95], off
	global_store_dwordx4 v[100:101], v[88:91], off offset:16
	s_cbranch_vccnz .LBB0_1054
	v_mul_f32_e32 v98, v93, v93
	v_mul_f32_e32 v99, v95, v95
	v_fmac_f32_e32 v98, v92, v92
	v_fmac_f32_e32 v99, v94, v94
	v_add_f32_e32 v98, v98, v99
	v_mul_f32_e32 v99, v89, v89
	v_fmac_f32_e32 v99, v88, v88
	v_add_f32_e32 v98, v98, v99
	v_mul_f32_e32 v99, v91, v91
	v_fmac_f32_e32 v99, v90, v90
	v_lshlrev_b64 v[96:97], 10, v[102:103]
	v_add_f32_e32 v102, v99, v98
	v_pk_mul_f32 v[94:95], v[54:55], v[94:95]
	v_pk_mul_f32 v[92:93], v[52:53], v[92:93]
	v_pk_mul_f32 v[98:99], v[50:51], v[90:91]
	v_pk_mul_f32 v[90:91], v[48:49], v[88:89]
	v_lshl_add_u64 v[96:97], v[96:97], 1, v[144:145]
	v_cvt_pk_bf16_f32 v88, v92, v93
	v_cvt_pk_bf16_f32 v89, v94, v95
	v_cvt_pk_bf16_f32 v90, v90, v91
	v_cvt_pk_bf16_f32 v91, v98, v99
	global_store_dwordx4 v[96:97], v[88:91], off
	s_nop 1
	v_mov_b64_e32 v[88:89], v[186:187]
	v_mov_b64_e32 v[90:91], v[188:189]
	s_nop 0
	s_nop 1
	v_mov_b64_e32 v[92:93], v[190:191]
	v_mov_b64_e32 v[94:95], v[192:193]
	s_waitcnt lgkmcnt(0)
	v_pk_add_f32 v[90:91], v[86:87], v[90:91]
	v_pk_add_f32 v[88:89], v[84:85], v[88:89]
	v_mul_f32_e32 v99, v91, v91
	v_mul_f32_e32 v98, v89, v89
	v_pk_add_f32 v[92:93], v[80:81], v[92:93]
	v_fmac_f32_e32 v98, v88, v88
	v_fmac_f32_e32 v99, v90, v90
	v_add_f32_e32 v98, v98, v99
	v_mul_f32_e32 v99, v93, v93
	v_pk_add_f32 v[94:95], v[82:83], v[94:95]
	v_fmac_f32_e32 v99, v92, v92
	v_add_f32_e32 v98, v98, v99
	v_mul_f32_e32 v99, v95, v95
	v_fmac_f32_e32 v99, v94, v94
	global_store_dwordx4 v[100:101], v[88:91], off offset:512
	global_store_dwordx4 v[100:101], v[92:95], off offset:528
	v_add_f32_e32 v98, v99, v98
	v_pk_mul_f32 v[90:91], v[46:47], v[90:91]
	v_pk_mul_f32 v[88:89], v[44:45], v[88:89]
	v_pk_mul_f32 v[94:95], v[42:43], v[94:95]
	v_pk_mul_f32 v[92:93], v[40:41], v[92:93]
	v_add_f32_e32 v98, v102, v98
	v_cvt_pk_bf16_f32 v88, v88, v89
	v_cvt_pk_bf16_f32 v89, v90, v91
	v_cvt_pk_bf16_f32 v90, v92, v93
	v_cvt_pk_bf16_f32 v91, v94, v95
	global_store_dwordx4 v[96:97], v[88:91], off offset:256
	ds_bpermute_b32 v88, v162, v98
	s_waitcnt lgkmcnt(0)
	v_add_f32_e32 v88, v98, v88
	ds_bpermute_b32 v89, v161, v88
	s_and_saveexec_b64 s[6:7], s[44:45]
	s_cbranch_execz .LBB0_1022
	s_waitcnt lgkmcnt(0)
	v_add_f32_e32 v88, v88, v89
	ds_write_b32 v160, v88 offset:192

; __device__ __forceinline__ unsigned cvt_pk_bf16(float lo, float hi) { f32x2 v = {lo, hi}; bf16x2_t_ b = __builtin_convertvector(v, bf16x2_t_); return __builtin_bit_cast(unsigned, b); }
; __device__ __forceinline__ float shfl_xor_l(float v, int o, int lane) { return __int_as_float(__builtin_amdgcn_ds_bpermute((lane ^ o) << 2, __float_as_int(v))); }
;     __device__ __forceinline__ void operator()(const Acc& acc, const Unit& u, int wr, int wc, int fr, int fq) const {
;     ...
;             for (int m = 0; m < 4; ++m) { const int row = row0 + ai * HALF + m * 16; float* rowp = X + (size_t)row * DM + col0; float sq = 0.f;
; #pragma unroll
;                 for (int bj = 0; bj < 2; ++bj) { f32x4* p0 = (f32x4*)(rowp + bj * HALF); const f32x4* r0 = (const f32x4*)(R + (size_t)row * DM + col0 + bj * HALF); const f32x4 o0 = r0[0] + acc[ai][bj][m][0] * alpha, o1 = r0[1] + acc[ai][bj][m][1] * alpha; p0[0] = o0; p0[1] = o1;
;                     if (gnext) { sq += (o0[0] * o0[0] + o0[1] * o0[1]) + (o0[2] * o0[2] + o0[3] * o0[3]) + (o1[0] * o1[0] + o1[1] * o1[1]) + (o1[2] * o1[2] + o1[3] * o1[3]);
;                         const f32x4 y0 = o0 * gv[bj][0], y1 = o1 * gv[bj][1];
;                         u32x4 w; w.x = cvt_pk_bf16(y0[0], y0[1]); w.y = cvt_pk_bf16(y0[2], y0[3]); w.z = cvt_pk_bf16(y1[0], y1[1]); w.w = cvt_pk_bf16(y1[2], y1[3]);
;                         *(u32x4*)(XNo + (size_t)row * DM + col0 + bj * HALF) = w; } }
;                 if (gnext) { sq += shfl_xor_l(sq, 16, lane); sq += shfl_xor_l(sq, 32, lane); if (fq == 0) part[wc * 256 + ai * HALF + wr * 64 + m * 16 + fr] = sq; }
.LBB0_1023:
	s_waitcnt lgkmcnt(0)
	s_nop 1
	v_mov_b64_e32 v[88:89], v[186:187]
	v_mov_b64_e32 v[90:91], v[188:189]
	s_waitcnt lgkmcnt(0)
	v_pk_add_f32 v[86:87], v[86:87], v[90:91]
	v_pk_add_f32 v[84:85], v[84:85], v[88:89]
	s_nop 1
	v_mov_b64_e32 v[88:89], v[190:191]
	v_mov_b64_e32 v[90:91], v[192:193]
	s_waitcnt lgkmcnt(0)
	v_pk_add_f32 v[82:83], v[82:83], v[90:91]
	v_pk_add_f32 v[80:81], v[80:81], v[88:89]
	global_store_dwordx4 v[100:101], v[84:87], off offset:512
	global_store_dwordx4 v[100:101], v[80:83], off offset:528
.LBB0_1024:
	s_nop 1
	v_add_u32_e32 v82, 0x80, v146
	v_ashrrev_i32_e32 v83, 31, v82
	v_lshlrev_b64 v[80:81], 12, v[82:83]
	v_lshl_add_u64 v[80:81], v[148:149], 0, v[80:81]
	global_load_dwordx4 v[178:181], v[80:81], off
	global_load_dwordx4 v[182:185], v[80:81], off offset:16
	global_load_dwordx4 v[186:189], v[80:81], off offset:512
	global_load_dwordx4 v[190:193], v[80:81], off offset:528
	s_and_b64 vcc, exec, s[42:43]
	s_waitcnt vmcnt(0) lgkmcnt(0)
	s_nop 1
	v_mov_b64_e32 v[84:85], v[178:179]
	v_mov_b64_e32 v[86:87], v[180:181]
	v_pk_add_f32 v[78:79], v[78:79], v[86:87]
	v_pk_add_f32 v[76:77], v[76:77], v[84:85]
	s_nop 1
	v_mov_b64_e32 v[84:85], v[182:183]
	v_mov_b64_e32 v[86:87], v[184:185]
	s_waitcnt lgkmcnt(0)
	v_pk_add_f32 v[74:75], v[74:75], v[86:87]
	v_pk_add_f32 v[72:73], v[72:73], v[84:85]
	global_store_dwordx4 v[80:81], v[76:79], off
	global_store_dwordx4 v[80:81], v[72:75], off offset:16
	s_cbranch_vccnz .LBB0_1055
	v_mul_f32_e32 v84, v77, v77
	v_mul_f32_e32 v85, v79, v79
	v_fmac_f32_e32 v84, v76, v76
	v_fmac_f32_e32 v85, v78, v78
	v_add_f32_e32 v84, v84, v85
	v_mul_f32_e32 v85, v73, v73
	v_fmac_f32_e32 v85, v72, v72
	v_add_f32_e32 v84, v84, v85
	v_mul_f32_e32 v85, v75, v75
	v_fmac_f32_e32 v85, v74, v74
	v_lshlrev_b64 v[82:83], 10, v[82:83]
	v_add_f32_e32 v86, v85, v84
	v_pk_mul_f32 v[78:79], v[54:55], v[78:79]
	v_pk_mul_f32 v[76:77], v[52:53], v[76:77]
	v_pk_mul_f32 v[84:85], v[50:51], v[74:75]
	v_pk_mul_f32 v[74:75], v[48:49], v[72:73]
	v_lshl_add_u64 v[82:83], v[82:83], 1, v[144:145]
	v_cvt_pk_bf16_f32 v72, v76, v77
	v_cvt_pk_bf16_f32 v73, v78, v79
	v_cvt_pk_bf16_f32 v74, v74, v75
	v_cvt_pk_bf16_f32 v75, v84, v85
	global_store_dwordx4 v[82:83], v[72:75], off
	s_nop 1
	v_mov_b64_e32 v[72:73], v[186:187]
	v_mov_b64_e32 v[74:75], v[188:189]
	s_nop 0
	s_nop 1
	v_mov_b64_e32 v[76:77], v[190:191]
	v_mov_b64_e32 v[78:79], v[192:193]
	s_waitcnt lgkmcnt(0)
	v_pk_add_f32 v[74:75], v[70:71], v[74:75]
	v_pk_add_f32 v[72:73], v[68:69], v[72:73]
	v_mul_f32_e32 v85, v75, v75
	v_mul_f32_e32 v84, v73, v73
	v_pk_add_f32 v[76:77], v[60:61], v[76:77]
	v_fmac_f32_e32 v84, v72, v72
	v_fmac_f32_e32 v85, v74, v74
	v_add_f32_e32 v84, v84, v85
	v_mul_f32_e32 v85, v77, v77
	v_pk_add_f32 v[78:79], v[62:63], v[78:79]
	v_fmac_f32_e32 v85, v76, v76
	v_add_f32_e32 v84, v84, v85
	v_mul_f32_e32 v85, v79, v79
	v_fmac_f32_e32 v85, v78, v78
	global_store_dwordx4 v[80:81], v[72:75], off offset:512
	global_store_dwordx4 v[80:81], v[76:79], off offset:528
	v_add_f32_e32 v84, v85, v84
	v_pk_mul_f32 v[74:75], v[46:47], v[74:75]
	v_pk_mul_f32 v[72:73], v[44:45], v[72:73]
	v_pk_mul_f32 v[78:79], v[42:43], v[78:79]
	v_pk_mul_f32 v[76:77], v[40:41], v[76:77]
	v_add_f32_e32 v84, v86, v84
	v_cvt_pk_bf16_f32 v72, v72, v73
	v_cvt_pk_bf16_f32 v73, v74, v75
	v_cvt_pk_bf16_f32 v74, v76, v77
	v_cvt_pk_bf16_f32 v75, v78, v79
	global_store_dwordx4 v[82:83], v[72:75], off offset:256
	ds_bpermute_b32 v72, v162, v84
	s_waitcnt lgkmcnt(0)
	v_add_f32_e32 v72, v84, v72
	ds_bpermute_b32 v73, v161, v72
	s_and_saveexec_b64 s[6:7], s[44:45]
	s_cbranch_execz .LBB0_1027
	s_waitcnt lgkmcnt(0)
	v_add_f32_e32 v72, v72, v73
	ds_write_b32 v160, v72 offset:512

; __device__ __forceinline__ unsigned cvt_pk_bf16(float lo, float hi) { f32x2 v = {lo, hi}; bf16x2_t_ b = __builtin_convertvector(v, bf16x2_t_); return __builtin_bit_cast(unsigned, b); }
; __device__ __forceinline__ float shfl_xor_l(float v, int o, int lane) { return __int_as_float(__builtin_amdgcn_ds_bpermute((lane ^ o) << 2, __float_as_int(v))); }
;     __device__ __forceinline__ void operator()(const Acc& acc, const Unit& u, int wr, int wc, int fr, int fq) const {
;     ...
;             for (int m = 0; m < 4; ++m) { const int row = row0 + ai * HALF + m * 16; float* rowp = X + (size_t)row * DM + col0; float sq = 0.f;
; #pragma unroll
;                 for (int bj = 0; bj < 2; ++bj) { f32x4* p0 = (f32x4*)(rowp + bj * HALF); const f32x4* r0 = (const f32x4*)(R + (size_t)row * DM + col0 + bj * HALF); const f32x4 o0 = r0[0] + acc[ai][bj][m][0] * alpha, o1 = r0[1] + acc[ai][bj][m][1] * alpha; p0[0] = o0; p0[1] = o1;
;                     if (gnext) { sq += (o0[0] * o0[0] + o0[1] * o0[1]) + (o0[2] * o0[2] + o0[3] * o0[3]) + (o1[0] * o1[0] + o1[1] * o1[1]) + (o1[2] * o1[2] + o1[3] * o1[3]);
;                         const f32x4 y0 = o0 * gv[bj][0], y1 = o1 * gv[bj][1];
;                         u32x4 w; w.x = cvt_pk_bf16(y0[0], y0[1]); w.y = cvt_pk_bf16(y0[2], y0[3]); w.z = cvt_pk_bf16(y1[0], y1[1]); w.w = cvt_pk_bf16(y1[2], y1[3]);
;                         *(u32x4*)(XNo + (size_t)row * DM + col0 + bj * HALF) = w; } }
;                 if (gnext) { sq += shfl_xor_l(sq, 16, lane); sq += shfl_xor_l(sq, 32, lane); if (fq == 0) part[wc * 256 + ai * HALF + wr * 64 + m * 16 + fr] = sq; }
.LBB0_1028:
	s_waitcnt lgkmcnt(0)
	s_nop 1
	v_mov_b64_e32 v[72:73], v[186:187]
	v_mov_b64_e32 v[74:75], v[188:189]
	s_waitcnt lgkmcnt(0)
	v_pk_add_f32 v[70:71], v[70:71], v[74:75]
	v_pk_add_f32 v[68:69], v[68:69], v[72:73]
	s_nop 1
	v_mov_b64_e32 v[72:73], v[190:191]
	v_mov_b64_e32 v[74:75], v[192:193]
	s_waitcnt lgkmcnt(0)
	v_pk_add_f32 v[62:63], v[62:63], v[74:75]
	v_pk_add_f32 v[60:61], v[60:61], v[72:73]
	global_store_dwordx4 v[80:81], v[68:71], off offset:512
	global_store_dwordx4 v[80:81], v[60:63], off offset:528
.LBB0_1029:
	s_nop 0
	v_add_u32_e32 v70, 0x90, v146
	v_ashrrev_i32_e32 v71, 31, v70
	v_lshlrev_b64 v[60:61], 12, v[70:71]
	v_lshl_add_u64 v[68:69], v[148:149], 0, v[60:61]
	global_load_dwordx4 v[178:181], v[68:69], off
	global_load_dwordx4 v[182:185], v[68:69], off offset:16
	global_load_dwordx4 v[186:189], v[68:69], off offset:512
	global_load_dwordx4 v[190:193], v[68:69], off offset:528
	s_and_b64 vcc, exec, s[42:43]
	s_waitcnt vmcnt(0) lgkmcnt(0)
	s_nop 1
	v_mov_b64_e32 v[60:61], v[178:179]
	v_mov_b64_e32 v[62:63], v[180:181]
	v_pk_add_f32 v[62:63], v[66:67], v[62:63]
	v_pk_add_f32 v[60:61], v[64:65], v[60:61]
	s_nop 1
	v_mov_b64_e32 v[64:65], v[182:183]
	v_mov_b64_e32 v[66:67], v[184:185]
	s_waitcnt lgkmcnt(0)
	v_pk_add_f32 v[58:59], v[58:59], v[66:67]
	v_pk_add_f32 v[56:57], v[56:57], v[64:65]
	global_store_dwordx4 v[68:69], v[60:63], off
	global_store_dwordx4 v[68:69], v[56:59], off offset:16
	s_cbranch_vccnz .LBB0_1056
	v_mul_f32_e32 v66, v61, v61
	v_mul_f32_e32 v67, v63, v63
	v_fmac_f32_e32 v66, v60, v60
	v_fmac_f32_e32 v67, v62, v62
	v_add_f32_e32 v66, v66, v67
	v_mul_f32_e32 v67, v57, v57
	v_fmac_f32_e32 v67, v56, v56
	v_add_f32_e32 v66, v66, v67
	v_mul_f32_e32 v67, v59, v59
	v_fmac_f32_e32 v67, v58, v58
	v_lshlrev_b64 v[64:65], 10, v[70:71]
	v_add_f32_e32 v70, v67, v66
	v_pk_mul_f32 v[62:63], v[54:55], v[62:63]
	v_pk_mul_f32 v[60:61], v[52:53], v[60:61]
	v_pk_mul_f32 v[66:67], v[50:51], v[58:59]
	v_pk_mul_f32 v[58:59], v[48:49], v[56:57]
	v_lshl_add_u64 v[64:65], v[64:65], 1, v[144:145]
	v_cvt_pk_bf16_f32 v56, v60, v61
	v_cvt_pk_bf16_f32 v57, v62, v63
	v_cvt_pk_bf16_f32 v58, v58, v59
	v_cvt_pk_bf16_f32 v59, v66, v67
	global_store_dwordx4 v[64:65], v[56:59], off
	s_nop 1
	v_mov_b64_e32 v[56:57], v[186:187]
	v_mov_b64_e32 v[58:59], v[188:189]
	s_nop 0
	s_nop 1
	v_mov_b64_e32 v[60:61], v[190:191]
	v_mov_b64_e32 v[62:63], v[192:193]
	s_waitcnt lgkmcnt(0)
	v_pk_add_f32 v[58:59], v[38:39], v[58:59]
	v_pk_add_f32 v[56:57], v[36:37], v[56:57]
	v_mul_f32_e32 v67, v59, v59
	v_mul_f32_e32 v66, v57, v57
	v_pk_add_f32 v[60:61], v[28:29], v[60:61]
	v_fmac_f32_e32 v66, v56, v56
	v_fmac_f32_e32 v67, v58, v58
	v_add_f32_e32 v66, v66, v67
	v_mul_f32_e32 v67, v61, v61
	v_pk_add_f32 v[62:63], v[30:31], v[62:63]
	v_fmac_f32_e32 v67, v60, v60
	v_add_f32_e32 v66, v66, v67
	v_mul_f32_e32 v67, v63, v63
	v_fmac_f32_e32 v67, v62, v62
	global_store_dwordx4 v[68:69], v[56:59], off offset:512
	global_store_dwordx4 v[68:69], v[60:63], off offset:528
	v_add_f32_e32 v66, v67, v66
	v_pk_mul_f32 v[58:59], v[46:47], v[58:59]
	v_pk_mul_f32 v[56:57], v[44:45], v[56:57]
	v_pk_mul_f32 v[62:63], v[42:43], v[62:63]
	v_pk_mul_f32 v[60:61], v[40:41], v[60:61]
	v_add_f32_e32 v66, v70, v66
	v_cvt_pk_bf16_f32 v56, v56, v57
	v_cvt_pk_bf16_f32 v57, v58, v59
	v_cvt_pk_bf16_f32 v58, v60, v61
	v_cvt_pk_bf16_f32 v59, v62, v63
	global_store_dwordx4 v[64:65], v[56:59], off offset:256
	ds_bpermute_b32 v56, v162, v66
	s_waitcnt lgkmcnt(0)
	v_add_f32_e32 v56, v66, v56
	ds_bpermute_b32 v57, v161, v56
	s_and_saveexec_b64 s[6:7], s[44:45]
	s_cbranch_execz .LBB0_1032
	s_waitcnt lgkmcnt(0)
	v_add_f32_e32 v56, v56, v57
	ds_write_b32 v160, v56 offset:576

; __device__ __forceinline__ unsigned cvt_pk_bf16(float lo, float hi) { f32x2 v = {lo, hi}; bf16x2_t_ b = __builtin_convertvector(v, bf16x2_t_); return __builtin_bit_cast(unsigned, b); }
; __device__ __forceinline__ float shfl_xor_l(float v, int o, int lane) { return __int_as_float(__builtin_amdgcn_ds_bpermute((lane ^ o) << 2, __float_as_int(v))); }
;     __device__ __forceinline__ void operator()(const Acc& acc, const Unit& u, int wr, int wc, int fr, int fq) const {
;     ...
;             for (int m = 0; m < 4; ++m) { const int row = row0 + ai * HALF + m * 16; float* rowp = X + (size_t)row * DM + col0; float sq = 0.f;
; #pragma unroll
;                 for (int bj = 0; bj < 2; ++bj) { f32x4* p0 = (f32x4*)(rowp + bj * HALF); const f32x4* r0 = (const f32x4*)(R + (size_t)row * DM + col0 + bj * HALF); const f32x4 o0 = r0[0] + acc[ai][bj][m][0] * alpha, o1 = r0[1] + acc[ai][bj][m][1] * alpha; p0[0] = o0; p0[1] = o1;
;                     if (gnext) { sq += (o0[0] * o0[0] + o0[1] * o0[1]) + (o0[2] * o0[2] + o0[3] * o0[3]) + (o1[0] * o1[0] + o1[1] * o1[1]) + (o1[2] * o1[2] + o1[3] * o1[3]);
;                         const f32x4 y0 = o0 * gv[bj][0], y1 = o1 * gv[bj][1];
;                         u32x4 w; w.x = cvt_pk_bf16(y0[0], y0[1]); w.y = cvt_pk_bf16(y0[2], y0[3]); w.z = cvt_pk_bf16(y1[0], y1[1]); w.w = cvt_pk_bf16(y1[2], y1[3]);
;                         *(u32x4*)(XNo + (size_t)row * DM + col0 + bj * HALF) = w; } }
;                 if (gnext) { sq += shfl_xor_l(sq, 16, lane); sq += shfl_xor_l(sq, 32, lane); if (fq == 0) part[wc * 256 + ai * HALF + wr * 64 + m * 16 + fr] = sq; }
.LBB0_1033:
	s_waitcnt lgkmcnt(0)
	s_nop 1
	v_mov_b64_e32 v[56:57], v[186:187]
	v_mov_b64_e32 v[58:59], v[188:189]
	s_waitcnt lgkmcnt(0)
	v_pk_add_f32 v[38:39], v[38:39], v[58:59]
	v_pk_add_f32 v[36:37], v[36:37], v[56:57]
	s_nop 1
	v_mov_b64_e32 v[56:57], v[190:191]
	v_mov_b64_e32 v[58:59], v[192:193]
	s_waitcnt lgkmcnt(0)
	v_pk_add_f32 v[30:31], v[30:31], v[58:59]
	v_pk_add_f32 v[28:29], v[28:29], v[56:57]
	global_store_dwordx4 v[68:69], v[36:39], off offset:512
	global_store_dwordx4 v[68:69], v[28:31], off offset:528
.LBB0_1034:
	s_nop 0
	v_add_u32_e32 v38, 0xa0, v146
	v_ashrrev_i32_e32 v39, 31, v38
	v_lshlrev_b64 v[28:29], 12, v[38:39]
	v_lshl_add_u64 v[36:37], v[148:149], 0, v[28:29]
	global_load_dwordx4 v[178:181], v[36:37], off
	global_load_dwordx4 v[182:185], v[36:37], off offset:16
	global_load_dwordx4 v[186:189], v[36:37], off offset:512
	global_load_dwordx4 v[190:193], v[36:37], off offset:528
	s_and_b64 vcc, exec, s[42:43]
	s_waitcnt vmcnt(0) lgkmcnt(0)
	s_nop 1
	v_mov_b64_e32 v[28:29], v[178:179]
	v_mov_b64_e32 v[30:31], v[180:181]
	v_pk_add_f32 v[30:31], v[34:35], v[30:31]
	v_pk_add_f32 v[28:29], v[32:33], v[28:29]
	s_nop 1
	v_mov_b64_e32 v[32:33], v[182:183]
	v_mov_b64_e32 v[34:35], v[184:185]
	s_waitcnt lgkmcnt(0)
	v_pk_add_f32 v[26:27], v[26:27], v[34:35]
	v_pk_add_f32 v[24:25], v[24:25], v[32:33]
	global_store_dwordx4 v[36:37], v[28:31], off
	global_store_dwordx4 v[36:37], v[24:27], off offset:16
	s_cbranch_vccnz .LBB0_1057
	v_mul_f32_e32 v34, v29, v29
	v_mul_f32_e32 v35, v31, v31
	v_fmac_f32_e32 v34, v28, v28
	v_fmac_f32_e32 v35, v30, v30
	v_add_f32_e32 v34, v34, v35
	v_mul_f32_e32 v35, v25, v25
	v_fmac_f32_e32 v35, v24, v24
	v_add_f32_e32 v34, v34, v35
	v_mul_f32_e32 v35, v27, v27
	v_fmac_f32_e32 v35, v26, v26
	v_lshlrev_b64 v[32:33], 10, v[38:39]
	v_add_f32_e32 v38, v35, v34
	v_pk_mul_f32 v[30:31], v[54:55], v[30:31]
	v_pk_mul_f32 v[28:29], v[52:53], v[28:29]
	v_pk_mul_f32 v[34:35], v[50:51], v[26:27]
	v_pk_mul_f32 v[26:27], v[48:49], v[24:25]
	v_lshl_add_u64 v[32:33], v[32:33], 1, v[144:145]
	v_cvt_pk_bf16_f32 v24, v28, v29
	v_cvt_pk_bf16_f32 v25, v30, v31
	v_cvt_pk_bf16_f32 v26, v26, v27
	v_cvt_pk_bf16_f32 v27, v34, v35
	global_store_dwordx4 v[32:33], v[24:27], off
	s_nop 1
	v_mov_b64_e32 v[24:25], v[186:187]
	v_mov_b64_e32 v[26:27], v[188:189]
	s_nop 0
	s_nop 1
	v_mov_b64_e32 v[28:29], v[190:191]
	v_mov_b64_e32 v[30:31], v[192:193]
	s_waitcnt lgkmcnt(0)
	v_pk_add_f32 v[26:27], v[22:23], v[26:27]
	v_pk_add_f32 v[24:25], v[20:21], v[24:25]
	v_mul_f32_e32 v35, v27, v27
	v_mul_f32_e32 v34, v25, v25
	v_pk_add_f32 v[28:29], v[12:13], v[28:29]
	v_fmac_f32_e32 v34, v24, v24
	v_fmac_f32_e32 v35, v26, v26
	v_add_f32_e32 v34, v34, v35
	v_mul_f32_e32 v35, v29, v29
	v_pk_add_f32 v[30:31], v[14:15], v[30:31]
	v_fmac_f32_e32 v35, v28, v28
	v_add_f32_e32 v34, v34, v35
	v_mul_f32_e32 v35, v31, v31
	v_fmac_f32_e32 v35, v30, v30
	global_store_dwordx4 v[36:37], v[24:27], off offset:512
	global_store_dwordx4 v[36:37], v[28:31], off offset:528
	v_add_f32_e32 v34, v35, v34
	v_pk_mul_f32 v[26:27], v[46:47], v[26:27]
	v_pk_mul_f32 v[24:25], v[44:45], v[24:25]
	v_pk_mul_f32 v[30:31], v[42:43], v[30:31]
	v_pk_mul_f32 v[28:29], v[40:41], v[28:29]
	v_add_f32_e32 v34, v38, v34
	v_cvt_pk_bf16_f32 v24, v24, v25
	v_cvt_pk_bf16_f32 v25, v26, v27
	v_cvt_pk_bf16_f32 v26, v28, v29
	v_cvt_pk_bf16_f32 v27, v30, v31
	global_store_dwordx4 v[32:33], v[24:27], off offset:256
	ds_bpermute_b32 v24, v162, v34
	s_waitcnt lgkmcnt(0)
	v_add_f32_e32 v24, v34, v24
	ds_bpermute_b32 v25, v161, v24
	s_and_saveexec_b64 s[6:7], s[44:45]
	s_cbranch_execz .LBB0_1037
	s_waitcnt lgkmcnt(0)
	v_add_f32_e32 v24, v24, v25
	ds_write_b32 v160, v24 offset:640

; __device__ __forceinline__ unsigned cvt_pk_bf16(float lo, float hi) { f32x2 v = {lo, hi}; bf16x2_t_ b = __builtin_convertvector(v, bf16x2_t_); return __builtin_bit_cast(unsigned, b); }
; __device__ __forceinline__ float shfl_xor_l(float v, int o, int lane) { return __int_as_float(__builtin_amdgcn_ds_bpermute((lane ^ o) << 2, __float_as_int(v))); }
;     __device__ __forceinline__ void operator()(const Acc& acc, const Unit& u, int wr, int wc, int fr, int fq) const {
;     ...
;             for (int m = 0; m < 4; ++m) { const int row = row0 + ai * HALF + m * 16; float* rowp = X + (size_t)row * DM + col0; float sq = 0.f;
; #pragma unroll
;                 for (int bj = 0; bj < 2; ++bj) { f32x4* p0 = (f32x4*)(rowp + bj * HALF); const f32x4* r0 = (const f32x4*)(R + (size_t)row * DM + col0 + bj * HALF); const f32x4 o0 = r0[0] + acc[ai][bj][m][0] * alpha, o1 = r0[1] + acc[ai][bj][m][1] * alpha; p0[0] = o0; p0[1] = o1;
;                     if (gnext) { sq += (o0[0] * o0[0] + o0[1] * o0[1]) + (o0[2] * o0[2] + o0[3] * o0[3]) + (o1[0] * o1[0] + o1[1] * o1[1]) + (o1[2] * o1[2] + o1[3] * o1[3]);
;                         const f32x4 y0 = o0 * gv[bj][0], y1 = o1 * gv[bj][1];
;                         u32x4 w; w.x = cvt_pk_bf16(y0[0], y0[1]); w.y = cvt_pk_bf16(y0[2], y0[3]); w.z = cvt_pk_bf16(y1[0], y1[1]); w.w = cvt_pk_bf16(y1[2], y1[3]);
;                         *(u32x4*)(XNo + (size_t)row * DM + col0 + bj * HALF) = w; } }
;                 if (gnext) { sq += shfl_xor_l(sq, 16, lane); sq += shfl_xor_l(sq, 32, lane); if (fq == 0) part[wc * 256 + ai * HALF + wr * 64 + m * 16 + fr] = sq; }
.LBB0_1038:
	s_waitcnt lgkmcnt(0)
	s_nop 1
	v_mov_b64_e32 v[24:25], v[186:187]
	v_mov_b64_e32 v[26:27], v[188:189]
	s_waitcnt lgkmcnt(0)
	v_pk_add_f32 v[22:23], v[22:23], v[26:27]
	v_pk_add_f32 v[20:21], v[20:21], v[24:25]
	s_nop 1
	v_mov_b64_e32 v[24:25], v[190:191]
	v_mov_b64_e32 v[26:27], v[192:193]
	s_waitcnt lgkmcnt(0)
	v_pk_add_f32 v[14:15], v[14:15], v[26:27]
	v_pk_add_f32 v[12:13], v[12:13], v[24:25]
	global_store_dwordx4 v[36:37], v[20:23], off offset:512
	global_store_dwordx4 v[36:37], v[12:15], off offset:528
.LBB0_1039:
	s_nop 0
	v_add_u32_e32 v22, 0xb0, v146
	v_ashrrev_i32_e32 v23, 31, v22
	v_lshlrev_b64 v[12:13], 12, v[22:23]
	v_lshl_add_u64 v[20:21], v[148:149], 0, v[12:13]
	global_load_dwordx4 v[178:181], v[20:21], off
	global_load_dwordx4 v[182:185], v[20:21], off offset:16
	global_load_dwordx4 v[186:189], v[20:21], off offset:512
	global_load_dwordx4 v[190:193], v[20:21], off offset:528
	s_and_b64 vcc, exec, s[42:43]
	s_waitcnt vmcnt(0) lgkmcnt(0)
	s_nop 1
	v_mov_b64_e32 v[12:13], v[178:179]
	v_mov_b64_e32 v[14:15], v[180:181]
	v_pk_add_f32 v[14:15], v[18:19], v[14:15]
	v_pk_add_f32 v[12:13], v[16:17], v[12:13]
	s_nop 1
	v_mov_b64_e32 v[16:17], v[182:183]
	v_mov_b64_e32 v[18:19], v[184:185]
	s_waitcnt lgkmcnt(0)
	v_pk_add_f32 v[10:11], v[10:11], v[18:19]
	v_pk_add_f32 v[8:9], v[8:9], v[16:17]
	global_store_dwordx4 v[20:21], v[12:15], off
	global_store_dwordx4 v[20:21], v[8:11], off offset:16
	s_cbranch_vccnz .LBB0_1058
	v_lshlrev_b64 v[16:17], 10, v[22:23]
	v_lshl_add_u64 v[26:27], v[16:17], 1, v[144:145]
	v_pk_mul_f32 v[18:19], v[54:55], v[14:15]
	v_pk_mul_f32 v[16:17], v[52:53], v[12:13]
	v_pk_mul_f32 v[22:23], v[50:51], v[10:11]
	v_pk_mul_f32 v[24:25], v[48:49], v[8:9]
	v_cvt_pk_bf16_f32 v16, v16, v17
	v_cvt_pk_bf16_f32 v17, v18, v19
	v_cvt_pk_bf16_f32 v18, v24, v25
	v_cvt_pk_bf16_f32 v19, v22, v23
	global_store_dwordx4 v[26:27], v[16:19], off
	s_nop 1
	v_mov_b64_e32 v[16:17], v[186:187]
	v_mov_b64_e32 v[18:19], v[188:189]
	s_nop 0
	s_nop 1
	v_mov_b64_e32 v[22:23], v[190:191]
	v_mov_b64_e32 v[24:25], v[192:193]
	v_mul_f32_e32 v13, v13, v13
	v_mul_f32_e32 v15, v15, v15
	v_mul_f32_e32 v9, v9, v9
	v_fmac_f32_e32 v13, v12, v12
	v_fmac_f32_e32 v15, v14, v14
	v_mul_f32_e32 v11, v11, v11
	v_fmac_f32_e32 v9, v8, v8
	v_add_f32_e32 v8, v13, v15
	v_fmac_f32_e32 v11, v10, v10
	v_add_f32_e32 v8, v8, v9
	v_add_f32_e32 v28, v11, v8
	s_waitcnt lgkmcnt(0)
	v_pk_add_f32 v[10:11], v[6:7], v[18:19]
	v_pk_add_f32 v[8:9], v[4:5], v[16:17]
	v_pk_add_f32 v[12:13], v[0:1], v[22:23]
	v_mul_f32_e32 v16, v9, v9
	v_mul_f32_e32 v17, v11, v11
	v_pk_add_f32 v[14:15], v[2:3], v[24:25]
	v_mul_f32_e32 v18, v13, v13
	v_fmac_f32_e32 v16, v8, v8
	v_fmac_f32_e32 v17, v10, v10
	v_mul_f32_e32 v19, v15, v15
	v_fmac_f32_e32 v18, v12, v12
	v_add_f32_e32 v16, v16, v17
	v_fmac_f32_e32 v19, v14, v14
	v_add_f32_e32 v16, v16, v18
	v_add_f32_e32 v16, v19, v16
	v_add_f32_e32 v18, v28, v16
	global_store_dwordx4 v[20:21], v[8:11], off offset:512
	global_store_dwordx4 v[20:21], v[12:15], off offset:528
	v_pk_mul_f32 v[16:17], v[46:47], v[10:11]
	ds_bpermute_b32 v11, v162, v18
	v_pk_mul_f32 v[8:9], v[44:45], v[8:9]
	v_pk_mul_f32 v[14:15], v[42:43], v[14:15]
	v_cvt_pk_bf16_f32 v10, v8, v9
	v_pk_mul_f32 v[12:13], v[40:41], v[12:13]
	s_waitcnt lgkmcnt(0)
	v_add_f32_e32 v8, v18, v11
	ds_bpermute_b32 v9, v161, v8
	v_cvt_pk_bf16_f32 v11, v16, v17
	v_cvt_pk_bf16_f32 v12, v12, v13
	v_cvt_pk_bf16_f32 v13, v14, v15
	global_store_dwordx4 v[26:27], v[10:13], off offset:256
	s_and_saveexec_b64 s[6:7], s[44:45]
	s_cbranch_execz .LBB0_1042
	s_waitcnt lgkmcnt(0)
	v_add_f32_e32 v8, v8, v9
	ds_write_b32 v160, v8 offset:704

; __device__ __forceinline__ unsigned cvt_pk_bf16(float lo, float hi) { f32x2 v = {lo, hi}; bf16x2_t_ b = __builtin_convertvector(v, bf16x2_t_); return __builtin_bit_cast(unsigned, b); }
;     __device__ __forceinline__ void operator()(const Acc& acc, const Unit& u, int wr, int wc, int fr, int fq) const {
;     ...
;                 for (int bj = 0; bj < 2; ++bj) { f32x4* p0 = (f32x4*)(rowp + bj * HALF); const f32x4* r0 = (const f32x4*)(R + (size_t)row * DM + col0 + bj * HALF); const f32x4 o0 = r0[0] + acc[ai][bj][m][0] * alpha, o1 = r0[1] + acc[ai][bj][m][1] * alpha; p0[0] = o0; p0[1] = o1;
;                     if (gnext) { sq += (o0[0] * o0[0] + o0[1] * o0[1]) + (o0[2] * o0[2] + o0[3] * o0[3]) + (o1[0] * o1[0] + o1[1] * o1[1]) + (o1[2] * o1[2] + o1[3] * o1[3]);
;                         const f32x4 y0 = o0 * gv[bj][0], y1 = o1 * gv[bj][1];
;                         u32x4 w; w.x = cvt_pk_bf16(y0[0], y0[1]); w.y = cvt_pk_bf16(y0[2], y0[3]); w.z = cvt_pk_bf16(y1[0], y1[1]); w.w = cvt_pk_bf16(y1[2], y1[3]);
;                         *(u32x4*)(XNo + (size_t)row * DM + col0 + bj * HALF) = w; } }
.LBB0_1043:
	s_waitcnt lgkmcnt(0)
	s_nop 1
	v_mov_b64_e32 v[8:9], v[186:187]
	v_mov_b64_e32 v[10:11], v[188:189]
	s_waitcnt lgkmcnt(0)
	v_pk_add_f32 v[6:7], v[6:7], v[10:11]
	v_pk_add_f32 v[4:5], v[4:5], v[8:9]
	s_nop 1
	v_mov_b64_e32 v[8:9], v[190:191]
	v_mov_b64_e32 v[10:11], v[192:193]
	s_waitcnt lgkmcnt(0)
	v_pk_add_f32 v[2:3], v[2:3], v[10:11]
	v_pk_add_f32 v[0:1], v[0:1], v[8:9]
	global_store_dwordx4 v[20:21], v[4:7], off offset:512
	global_store_dwordx4 v[20:21], v[0:3], off offset:528

; __device__ __forceinline__ unsigned cvt_pk_bf16(float lo, float hi) { f32x2 v = {lo, hi}; bf16x2_t_ b = __builtin_convertvector(v, bf16x2_t_); return __builtin_bit_cast(unsigned, b); }
; __device__ __forceinline__ float shfl_xor_l(float v, int o, int lane) { return __int_as_float(__builtin_amdgcn_ds_bpermute((lane ^ o) << 2, __float_as_int(v))); }
;     __device__ __forceinline__ void operator()(const Acc& acc, const Unit& u, int wr, int wc, int fr, int fq) const {
;     ...
;         const int row0 = u.pm * BM + wr * 64 + fr, col0 = u.pn * BM + wc * 32 + 8 * fq; const int lane = fr + 16 * fq;
;         f32x4 gv[2][2];
;         if (gnext) {
; #pragma unroll
;             for (int bj = 0; bj < 2; ++bj)
; #pragma unroll
;                 for (int n = 0; n < 2; ++n) gv[bj][n] = *(const f32x4*)(gnext + col0 + bj * HALF + 4 * n); }
; #pragma unroll
;         for (int ai = 0; ai < 2; ++ai)
; #pragma unroll
;             for (int m = 0; m < 4; ++m) { const int row = row0 + ai * HALF + m * 16; float* rowp = X + (size_t)row * DM + col0; float sq = 0.f;
; #pragma unroll
;                 for (int bj = 0; bj < 2; ++bj) { f32x4* p0 = (f32x4*)(rowp + bj * HALF); const f32x4* r0 = (const f32x4*)(R + (size_t)row * DM + col0 + bj * HALF); const f32x4 o0 = r0[0] + acc[ai][bj][m][0] * alpha, o1 = r0[1] + acc[ai][bj][m][1] * alpha; p0[0] = o0; p0[1] = o1;
;                     if (gnext) { sq += (o0[0] * o0[0] + o0[1] * o0[1]) + (o0[2] * o0[2] + o0[3] * o0[3]) + (o1[0] * o1[0] + o1[1] * o1[1]) + (o1[2] * o1[2] + o1[3] * o1[3]);
;                         const f32x4 y0 = o0 * gv[bj][0], y1 = o1 * gv[bj][1];
;                         u32x4 w; w.x = cvt_pk_bf16(y0[0], y0[1]); w.y = cvt_pk_bf16(y0[2], y0[3]); w.z = cvt_pk_bf16(y1[0], y1[1]); w.w = cvt_pk_bf16(y1[2], y1[3]);
;                         *(u32x4*)(XNo + (size_t)row * DM + col0 + bj * HALF) = w; } }
;                 if (gnext) { sq += shfl_xor_l(sq, 16, lane); sq += shfl_xor_l(sq, 32, lane); if (fq == 0) part[wc * 256 + ai * HALF + wr * 64 + m * 16 + fr] = sq; }
.LBB0_1174:
	s_lshl_b32 s56, s38, 8
	v_readlane_b32 s6, v254, 1
	v_and_b32_e32 v160, 15, v159
	s_add_i32 s6, s56, s6
	v_or_b32_e32 v146, s6, v160
	v_ashrrev_i32_e32 v147, 31, v146
	v_lshl_add_u64 v[144:145], v[148:149], 2, s[18:19]
	v_lshlrev_b64 v[150:151], 12, v[146:147]
	v_lshl_add_u64 v[150:151], v[144:145], 0, v[150:151]
	global_load_dwordx4 v[178:181], v[150:151], off
	global_load_dwordx4 v[182:185], v[150:151], off offset:16
	global_load_dwordx4 v[186:189], v[150:151], off offset:512
	global_load_dwordx4 v[190:193], v[150:151], off offset:528
	v_cmp_gt_u32_e64 s[44:45], 16, v159
	s_mov_b64 s[6:7], -1
	s_and_b64 vcc, exec, s[14:15]
	s_waitcnt vmcnt(0) lgkmcnt(0)
	s_nop 1
	v_mov_b64_e32 v[162:163], v[178:179]
	v_mov_b64_e32 v[164:165], v[180:181]
	v_pk_fma_f32 v[142:143], v[142:143], 0.5, v[164:165] op_sel_hi:[1,0,1]
	v_pk_fma_f32 v[140:141], v[140:141], 0.5, v[162:163] op_sel_hi:[1,0,1]
	s_nop 1
	v_mov_b64_e32 v[162:163], v[182:183]
	v_mov_b64_e32 v[164:165], v[184:185]
	s_waitcnt lgkmcnt(0)
	v_pk_fma_f32 v[138:139], v[138:139], 0.5, v[164:165] op_sel_hi:[1,0,1]
	v_pk_fma_f32 v[136:137], v[136:137], 0.5, v[162:163] op_sel_hi:[1,0,1]
	global_store_dwordx4 v[150:151], v[140:143], off
	global_store_dwordx4 v[150:151], v[136:139], off offset:16
	s_cbranch_vccz .LBB0_1176
	s_nop 1
	v_mov_b64_e32 v[162:163], v[186:187]
	v_mov_b64_e32 v[164:165], v[188:189]
	s_nop 1
	v_mov_b64_e32 v[166:167], v[190:191]
	v_mov_b64_e32 v[168:169], v[192:193]
	s_mov_b64 s[6:7], 0
	s_waitcnt lgkmcnt(0)
	v_pk_fma_f32 v[164:165], v[134:135], 0.5, v[164:165] op_sel_hi:[1,0,1]
	v_pk_fma_f32 v[162:163], v[132:133], 0.5, v[162:163] op_sel_hi:[1,0,1]
	v_pk_fma_f32 v[168:169], v[130:131], 0.5, v[168:169] op_sel_hi:[1,0,1]
	v_pk_fma_f32 v[166:167], v[128:129], 0.5, v[166:167] op_sel_hi:[1,0,1]
	global_store_dwordx4 v[150:151], v[162:165], off offset:512
	global_store_dwordx4 v[150:151], v[166:169], off offset:528
.LBB0_1176:
	v_lshlrev_b32_e32 v161, 2, v159
	v_lshl_add_u64 v[148:149], v[148:149], 1, s[2:3]
	v_xor_b32_e32 v162, 64, v161
	v_xor_b32_e32 v161, 0x80, v161
	s_andn2_b64 vcc, exec, s[6:7]
	v_lshl_add_u32 v160, v160, 2, s9
	s_cbranch_vccnz .LBB0_1180
	v_lshlrev_b64 v[164:165], 10, v[146:147]
	v_mul_f32_e32 v147, v141, v141
	v_mul_f32_e32 v163, v143, v143
	v_fmac_f32_e32 v147, v140, v140
	v_fmac_f32_e32 v163, v142, v142
	v_add_f32_e32 v147, v147, v163
	v_mul_f32_e32 v163, v137, v137
	v_fmac_f32_e32 v163, v136, v136
	v_add_f32_e32 v147, v147, v163
	v_mul_f32_e32 v163, v139, v139
	v_fmac_f32_e32 v163, v138, v138
	v_pk_mul_f32 v[142:143], v[54:55], v[142:143]
	v_pk_mul_f32 v[140:141], v[52:53], v[140:141]
	v_pk_mul_f32 v[166:167], v[50:51], v[138:139]
	v_pk_mul_f32 v[138:139], v[48:49], v[136:137]
	v_lshl_add_u64 v[164:165], v[164:165], 1, v[148:149]
	v_cvt_pk_bf16_f32 v136, v140, v141
	v_cvt_pk_bf16_f32 v137, v142, v143
	v_cvt_pk_bf16_f32 v138, v138, v139
	v_cvt_pk_bf16_f32 v139, v166, v167
	global_store_dwordx4 v[164:165], v[136:139], off
	s_nop 1
	v_mov_b64_e32 v[136:137], v[186:187]
	v_mov_b64_e32 v[138:139], v[188:189]
	v_add_f32_e32 v147, v163, v147
	s_waitcnt lgkmcnt(0)
	v_pk_fma_f32 v[134:135], v[134:135], 0.5, v[138:139] op_sel_hi:[1,0,1]
	v_pk_fma_f32 v[132:133], v[132:133], 0.5, v[136:137] op_sel_hi:[1,0,1]
	s_nop 1
	v_mov_b64_e32 v[136:137], v[190:191]
	v_mov_b64_e32 v[138:139], v[192:193]
	s_waitcnt lgkmcnt(0)
	v_pk_fma_f32 v[128:129], v[128:129], 0.5, v[136:137] op_sel_hi:[1,0,1]
	v_mul_f32_e32 v136, v133, v133
	v_mul_f32_e32 v137, v135, v135
	v_fmac_f32_e32 v136, v132, v132
	v_fmac_f32_e32 v137, v134, v134
	v_add_f32_e32 v136, v136, v137
	v_mul_f32_e32 v137, v129, v129
	v_pk_fma_f32 v[130:131], v[130:131], 0.5, v[138:139] op_sel_hi:[1,0,1]
	v_fmac_f32_e32 v137, v128, v128
	v_add_f32_e32 v136, v136, v137
	v_mul_f32_e32 v137, v131, v131
	v_fmac_f32_e32 v137, v130, v130
	v_add_f32_e32 v136, v137, v136
	global_store_dwordx4 v[150:151], v[132:135], off offset:512
	global_store_dwordx4 v[150:151], v[128:131], off offset:528
	v_add_f32_e32 v138, v147, v136
	v_pk_mul_f32 v[134:135], v[42:43], v[134:135]
	v_pk_mul_f32 v[132:133], v[40:41], v[132:133]
	v_pk_mul_f32 v[136:137], v[34:35], v[130:131]
	v_pk_mul_f32 v[130:131], v[32:33], v[128:129]
	v_cvt_pk_bf16_f32 v128, v132, v133
	v_cvt_pk_bf16_f32 v129, v134, v135
	v_cvt_pk_bf16_f32 v130, v130, v131
	v_cvt_pk_bf16_f32 v131, v136, v137
	global_store_dwordx4 v[164:165], v[128:131], off offset:256
	ds_bpermute_b32 v128, v162, v138
	s_waitcnt lgkmcnt(0)
	v_add_f32_e32 v128, v138, v128
	ds_bpermute_b32 v129, v161, v128
	s_and_saveexec_b64 s[6:7], s[44:45]
	s_cbranch_execz .LBB0_1179
	s_waitcnt lgkmcnt(0)
	v_add_f32_e32 v128, v128, v129
	ds_write_b32 v160, v128

; __device__ __forceinline__ unsigned cvt_pk_bf16(float lo, float hi) { f32x2 v = {lo, hi}; bf16x2_t_ b = __builtin_convertvector(v, bf16x2_t_); return __builtin_bit_cast(unsigned, b); }
; __device__ __forceinline__ float shfl_xor_l(float v, int o, int lane) { return __int_as_float(__builtin_amdgcn_ds_bpermute((lane ^ o) << 2, __float_as_int(v))); }
;     __device__ __forceinline__ void operator()(const Acc& acc, const Unit& u, int wr, int wc, int fr, int fq) const {
;     ...
;             for (int m = 0; m < 4; ++m) { const int row = row0 + ai * HALF + m * 16; float* rowp = X + (size_t)row * DM + col0; float sq = 0.f;
; #pragma unroll
;                 for (int bj = 0; bj < 2; ++bj) { f32x4* p0 = (f32x4*)(rowp + bj * HALF); const f32x4* r0 = (const f32x4*)(R + (size_t)row * DM + col0 + bj * HALF); const f32x4 o0 = r0[0] + acc[ai][bj][m][0] * alpha, o1 = r0[1] + acc[ai][bj][m][1] * alpha; p0[0] = o0; p0[1] = o1;
;                     if (gnext) { sq += (o0[0] * o0[0] + o0[1] * o0[1]) + (o0[2] * o0[2] + o0[3] * o0[3]) + (o1[0] * o1[0] + o1[1] * o1[1]) + (o1[2] * o1[2] + o1[3] * o1[3]);
;                         const f32x4 y0 = o0 * gv[bj][0], y1 = o1 * gv[bj][1];
;                         u32x4 w; w.x = cvt_pk_bf16(y0[0], y0[1]); w.y = cvt_pk_bf16(y0[2], y0[3]); w.z = cvt_pk_bf16(y1[0], y1[1]); w.w = cvt_pk_bf16(y1[2], y1[3]);
;                         *(u32x4*)(XNo + (size_t)row * DM + col0 + bj * HALF) = w; } }
;                 if (gnext) { sq += shfl_xor_l(sq, 16, lane); sq += shfl_xor_l(sq, 32, lane); if (fq == 0) part[wc * 256 + ai * HALF + wr * 64 + m * 16 + fr] = sq; }
.LBB0_1180:
	v_or_b32_e32 v130, 16, v146
	v_ashrrev_i32_e32 v131, 31, v130
	s_waitcnt lgkmcnt(0)
	v_lshlrev_b64 v[128:129], 12, v[130:131]
	v_lshl_add_u64 v[128:129], v[144:145], 0, v[128:129]
	global_load_dwordx4 v[178:181], v[128:129], off
	global_load_dwordx4 v[182:185], v[128:129], off offset:16
	global_load_dwordx4 v[186:189], v[128:129], off offset:512
	global_load_dwordx4 v[190:193], v[128:129], off offset:528
	s_mov_b64 s[6:7], -1
	s_and_b64 vcc, exec, s[14:15]
	s_waitcnt vmcnt(0) lgkmcnt(0)
	s_nop 1
	v_mov_b64_e32 v[132:133], v[178:179]
	v_mov_b64_e32 v[134:135], v[180:181]
	v_pk_fma_f32 v[126:127], v[126:127], 0.5, v[134:135] op_sel_hi:[1,0,1]
	v_pk_fma_f32 v[124:125], v[124:125], 0.5, v[132:133] op_sel_hi:[1,0,1]
	s_nop 1
	v_mov_b64_e32 v[132:133], v[182:183]
	v_mov_b64_e32 v[134:135], v[184:185]
	s_waitcnt lgkmcnt(0)
	v_pk_fma_f32 v[122:123], v[122:123], 0.5, v[134:135] op_sel_hi:[1,0,1]
	v_pk_fma_f32 v[120:121], v[120:121], 0.5, v[132:133] op_sel_hi:[1,0,1]
	global_store_dwordx4 v[128:129], v[124:127], off
	global_store_dwordx4 v[128:129], v[120:123], off offset:16
	s_cbranch_vccz .LBB0_1182
	s_nop 1
	v_mov_b64_e32 v[132:133], v[186:187]
	v_mov_b64_e32 v[134:135], v[188:189]
	s_nop 1
	v_mov_b64_e32 v[136:137], v[190:191]
	v_mov_b64_e32 v[138:139], v[192:193]
	s_mov_b64 s[6:7], 0
	s_waitcnt lgkmcnt(0)
	v_pk_fma_f32 v[134:135], v[118:119], 0.5, v[134:135] op_sel_hi:[1,0,1]
	v_pk_fma_f32 v[132:133], v[116:117], 0.5, v[132:133] op_sel_hi:[1,0,1]
	v_pk_fma_f32 v[138:139], v[114:115], 0.5, v[138:139] op_sel_hi:[1,0,1]
	v_pk_fma_f32 v[136:137], v[112:113], 0.5, v[136:137] op_sel_hi:[1,0,1]
	global_store_dwordx4 v[128:129], v[132:135], off offset:512
	global_store_dwordx4 v[128:129], v[136:139], off offset:528
.LBB0_1182:
	s_andn2_b64 vcc, exec, s[6:7]
	s_cbranch_vccnz .LBB0_1186
	v_mul_f32_e32 v132, v125, v125
	v_mul_f32_e32 v133, v127, v127
	v_fmac_f32_e32 v132, v124, v124
	v_fmac_f32_e32 v133, v126, v126
	v_add_f32_e32 v132, v132, v133
	v_mul_f32_e32 v133, v121, v121
	v_fmac_f32_e32 v133, v120, v120
	v_add_f32_e32 v132, v132, v133
	v_mul_f32_e32 v133, v123, v123
	v_fmac_f32_e32 v133, v122, v122
	v_lshlrev_b64 v[130:131], 10, v[130:131]
	v_add_f32_e32 v134, v133, v132
	v_pk_mul_f32 v[126:127], v[54:55], v[126:127]
	v_pk_mul_f32 v[124:125], v[52:53], v[124:125]
	v_pk_mul_f32 v[132:133], v[50:51], v[122:123]
	v_pk_mul_f32 v[122:123], v[48:49], v[120:121]
	v_lshl_add_u64 v[130:131], v[130:131], 1, v[148:149]
	v_cvt_pk_bf16_f32 v120, v124, v125
	v_cvt_pk_bf16_f32 v121, v126, v127
	v_cvt_pk_bf16_f32 v122, v122, v123
	v_cvt_pk_bf16_f32 v123, v132, v133
	global_store_dwordx4 v[130:131], v[120:123], off
	s_nop 1
	v_mov_b64_e32 v[120:121], v[186:187]
	v_mov_b64_e32 v[122:123], v[188:189]
	s_waitcnt lgkmcnt(0)
	v_pk_fma_f32 v[118:119], v[118:119], 0.5, v[122:123] op_sel_hi:[1,0,1]
	v_pk_fma_f32 v[116:117], v[116:117], 0.5, v[120:121] op_sel_hi:[1,0,1]
	s_nop 1
	v_mov_b64_e32 v[120:121], v[190:191]
	v_mov_b64_e32 v[122:123], v[192:193]
	s_waitcnt lgkmcnt(0)
	v_pk_fma_f32 v[112:113], v[112:113], 0.5, v[120:121] op_sel_hi:[1,0,1]
	v_mul_f32_e32 v120, v117, v117
	v_mul_f32_e32 v121, v119, v119
	v_fmac_f32_e32 v120, v116, v116
	v_fmac_f32_e32 v121, v118, v118
	v_add_f32_e32 v120, v120, v121
	v_mul_f32_e32 v121, v113, v113
	v_pk_fma_f32 v[114:115], v[114:115], 0.5, v[122:123] op_sel_hi:[1,0,1]
	v_fmac_f32_e32 v121, v112, v112
	v_add_f32_e32 v120, v120, v121
	v_mul_f32_e32 v121, v115, v115
	v_fmac_f32_e32 v121, v114, v114
	v_add_f32_e32 v120, v121, v120
	global_store_dwordx4 v[128:129], v[116:119], off offset:512
	global_store_dwordx4 v[128:129], v[112:115], off offset:528
	v_add_f32_e32 v122, v134, v120
	v_pk_mul_f32 v[118:119], v[42:43], v[118:119]
	v_pk_mul_f32 v[116:117], v[40:41], v[116:117]
	v_pk_mul_f32 v[120:121], v[34:35], v[114:115]
	v_pk_mul_f32 v[114:115], v[32:33], v[112:113]
	v_cvt_pk_bf16_f32 v112, v116, v117
	v_cvt_pk_bf16_f32 v113, v118, v119
	v_cvt_pk_bf16_f32 v114, v114, v115
	v_cvt_pk_bf16_f32 v115, v120, v121
	global_store_dwordx4 v[130:131], v[112:115], off offset:256
	ds_bpermute_b32 v112, v162, v122
	s_waitcnt lgkmcnt(0)
	v_add_f32_e32 v112, v122, v112
	ds_bpermute_b32 v113, v161, v112
	s_and_saveexec_b64 s[6:7], s[44:45]
	s_cbranch_execz .LBB0_1185
	s_waitcnt lgkmcnt(0)
	v_add_f32_e32 v112, v112, v113
	ds_write_b32 v160, v112 offset:64

; __device__ __forceinline__ unsigned cvt_pk_bf16(float lo, float hi) { f32x2 v = {lo, hi}; bf16x2_t_ b = __builtin_convertvector(v, bf16x2_t_); return __builtin_bit_cast(unsigned, b); }
; __device__ __forceinline__ float shfl_xor_l(float v, int o, int lane) { return __int_as_float(__builtin_amdgcn_ds_bpermute((lane ^ o) << 2, __float_as_int(v))); }
;     __device__ __forceinline__ void operator()(const Acc& acc, const Unit& u, int wr, int wc, int fr, int fq) const {
;     ...
;             for (int m = 0; m < 4; ++m) { const int row = row0 + ai * HALF + m * 16; float* rowp = X + (size_t)row * DM + col0; float sq = 0.f;
; #pragma unroll
;                 for (int bj = 0; bj < 2; ++bj) { f32x4* p0 = (f32x4*)(rowp + bj * HALF); const f32x4* r0 = (const f32x4*)(R + (size_t)row * DM + col0 + bj * HALF); const f32x4 o0 = r0[0] + acc[ai][bj][m][0] * alpha, o1 = r0[1] + acc[ai][bj][m][1] * alpha; p0[0] = o0; p0[1] = o1;
;                     if (gnext) { sq += (o0[0] * o0[0] + o0[1] * o0[1]) + (o0[2] * o0[2] + o0[3] * o0[3]) + (o1[0] * o1[0] + o1[1] * o1[1]) + (o1[2] * o1[2] + o1[3] * o1[3]);
;                         const f32x4 y0 = o0 * gv[bj][0], y1 = o1 * gv[bj][1];
;                         u32x4 w; w.x = cvt_pk_bf16(y0[0], y0[1]); w.y = cvt_pk_bf16(y0[2], y0[3]); w.z = cvt_pk_bf16(y1[0], y1[1]); w.w = cvt_pk_bf16(y1[2], y1[3]);
;                         *(u32x4*)(XNo + (size_t)row * DM + col0 + bj * HALF) = w; } }
;                 if (gnext) { sq += shfl_xor_l(sq, 16, lane); sq += shfl_xor_l(sq, 32, lane); if (fq == 0) part[wc * 256 + ai * HALF + wr * 64 + m * 16 + fr] = sq; }
.LBB0_1186:
	v_or_b32_e32 v114, 32, v146
	v_ashrrev_i32_e32 v115, 31, v114
	s_waitcnt lgkmcnt(0)
	v_lshlrev_b64 v[112:113], 12, v[114:115]
	v_lshl_add_u64 v[112:113], v[144:145], 0, v[112:113]
	global_load_dwordx4 v[178:181], v[112:113], off
	global_load_dwordx4 v[182:185], v[112:113], off offset:16
	global_load_dwordx4 v[186:189], v[112:113], off offset:512
	global_load_dwordx4 v[190:193], v[112:113], off offset:528
	s_mov_b64 s[6:7], -1
	s_and_b64 vcc, exec, s[14:15]
	s_waitcnt vmcnt(0) lgkmcnt(0)
	s_nop 1
	v_mov_b64_e32 v[116:117], v[178:179]
	v_mov_b64_e32 v[118:119], v[180:181]
	v_pk_fma_f32 v[110:111], v[110:111], 0.5, v[118:119] op_sel_hi:[1,0,1]
	v_pk_fma_f32 v[108:109], v[108:109], 0.5, v[116:117] op_sel_hi:[1,0,1]
	s_nop 1
	v_mov_b64_e32 v[116:117], v[182:183]
	v_mov_b64_e32 v[118:119], v[184:185]
	s_waitcnt lgkmcnt(0)
	v_pk_fma_f32 v[106:107], v[106:107], 0.5, v[118:119] op_sel_hi:[1,0,1]
	v_pk_fma_f32 v[104:105], v[104:105], 0.5, v[116:117] op_sel_hi:[1,0,1]
	global_store_dwordx4 v[112:113], v[108:111], off
	global_store_dwordx4 v[112:113], v[104:107], off offset:16
	s_cbranch_vccz .LBB0_1188
	s_nop 1
	v_mov_b64_e32 v[116:117], v[186:187]
	v_mov_b64_e32 v[118:119], v[188:189]
	s_nop 1
	v_mov_b64_e32 v[120:121], v[190:191]
	v_mov_b64_e32 v[122:123], v[192:193]
	s_mov_b64 s[6:7], 0
	s_waitcnt lgkmcnt(0)
	v_pk_fma_f32 v[118:119], v[102:103], 0.5, v[118:119] op_sel_hi:[1,0,1]
	v_pk_fma_f32 v[116:117], v[100:101], 0.5, v[116:117] op_sel_hi:[1,0,1]
	v_pk_fma_f32 v[122:123], v[98:99], 0.5, v[122:123] op_sel_hi:[1,0,1]
	v_pk_fma_f32 v[120:121], v[96:97], 0.5, v[120:121] op_sel_hi:[1,0,1]
	global_store_dwordx4 v[112:113], v[116:119], off offset:512
	global_store_dwordx4 v[112:113], v[120:123], off offset:528
.LBB0_1188:
	s_andn2_b64 vcc, exec, s[6:7]
	s_cbranch_vccnz .LBB0_1192
	v_mul_f32_e32 v116, v109, v109
	v_mul_f32_e32 v117, v111, v111
	v_fmac_f32_e32 v116, v108, v108
	v_fmac_f32_e32 v117, v110, v110
	v_add_f32_e32 v116, v116, v117
	v_mul_f32_e32 v117, v105, v105
	v_fmac_f32_e32 v117, v104, v104
	v_add_f32_e32 v116, v116, v117
	v_mul_f32_e32 v117, v107, v107
	v_fmac_f32_e32 v117, v106, v106
	v_lshlrev_b64 v[114:115], 10, v[114:115]
	v_add_f32_e32 v118, v117, v116
	v_pk_mul_f32 v[110:111], v[54:55], v[110:111]
	v_pk_mul_f32 v[108:109], v[52:53], v[108:109]
	v_pk_mul_f32 v[116:117], v[50:51], v[106:107]
	v_pk_mul_f32 v[106:107], v[48:49], v[104:105]
	v_lshl_add_u64 v[114:115], v[114:115], 1, v[148:149]
	v_cvt_pk_bf16_f32 v104, v108, v109
	v_cvt_pk_bf16_f32 v105, v110, v111
	v_cvt_pk_bf16_f32 v106, v106, v107
	v_cvt_pk_bf16_f32 v107, v116, v117
	global_store_dwordx4 v[114:115], v[104:107], off
	s_nop 1
	v_mov_b64_e32 v[104:105], v[186:187]
	v_mov_b64_e32 v[106:107], v[188:189]
	s_waitcnt lgkmcnt(0)
	v_pk_fma_f32 v[102:103], v[102:103], 0.5, v[106:107] op_sel_hi:[1,0,1]
	v_pk_fma_f32 v[100:101], v[100:101], 0.5, v[104:105] op_sel_hi:[1,0,1]
	s_nop 1
	v_mov_b64_e32 v[104:105], v[190:191]
	v_mov_b64_e32 v[106:107], v[192:193]
	s_waitcnt lgkmcnt(0)
	v_pk_fma_f32 v[96:97], v[96:97], 0.5, v[104:105] op_sel_hi:[1,0,1]
	v_mul_f32_e32 v104, v101, v101
	v_mul_f32_e32 v105, v103, v103
	v_fmac_f32_e32 v104, v100, v100
	v_fmac_f32_e32 v105, v102, v102
	v_add_f32_e32 v104, v104, v105
	v_mul_f32_e32 v105, v97, v97
	v_pk_fma_f32 v[98:99], v[98:99], 0.5, v[106:107] op_sel_hi:[1,0,1]
	v_fmac_f32_e32 v105, v96, v96
	v_add_f32_e32 v104, v104, v105
	v_mul_f32_e32 v105, v99, v99
	v_fmac_f32_e32 v105, v98, v98
	v_add_f32_e32 v104, v105, v104
	global_store_dwordx4 v[112:113], v[100:103], off offset:512
	global_store_dwordx4 v[112:113], v[96:99], off offset:528
	v_add_f32_e32 v106, v118, v104
	v_pk_mul_f32 v[102:103], v[42:43], v[102:103]
	v_pk_mul_f32 v[100:101], v[40:41], v[100:101]
	v_pk_mul_f32 v[104:105], v[34:35], v[98:99]
	v_pk_mul_f32 v[98:99], v[32:33], v[96:97]
	v_cvt_pk_bf16_f32 v96, v100, v101
	v_cvt_pk_bf16_f32 v97, v102, v103
	v_cvt_pk_bf16_f32 v98, v98, v99
	v_cvt_pk_bf16_f32 v99, v104, v105
	global_store_dwordx4 v[114:115], v[96:99], off offset:256
	ds_bpermute_b32 v96, v162, v106
	s_waitcnt lgkmcnt(0)
	v_add_f32_e32 v96, v106, v96
	ds_bpermute_b32 v97, v161, v96
	s_and_saveexec_b64 s[6:7], s[44:45]
	s_cbranch_execz .LBB0_1191
	s_waitcnt lgkmcnt(0)
	v_add_f32_e32 v96, v96, v97
	ds_write_b32 v160, v96 offset:128

; __device__ __forceinline__ unsigned cvt_pk_bf16(float lo, float hi) { f32x2 v = {lo, hi}; bf16x2_t_ b = __builtin_convertvector(v, bf16x2_t_); return __builtin_bit_cast(unsigned, b); }
; __device__ __forceinline__ float shfl_xor_l(float v, int o, int lane) { return __int_as_float(__builtin_amdgcn_ds_bpermute((lane ^ o) << 2, __float_as_int(v))); }
;     __device__ __forceinline__ void operator()(const Acc& acc, const Unit& u, int wr, int wc, int fr, int fq) const {
;     ...
;             for (int m = 0; m < 4; ++m) { const int row = row0 + ai * HALF + m * 16; float* rowp = X + (size_t)row * DM + col0; float sq = 0.f;
; #pragma unroll
;                 for (int bj = 0; bj < 2; ++bj) { f32x4* p0 = (f32x4*)(rowp + bj * HALF); const f32x4* r0 = (const f32x4*)(R + (size_t)row * DM + col0 + bj * HALF); const f32x4 o0 = r0[0] + acc[ai][bj][m][0] * alpha, o1 = r0[1] + acc[ai][bj][m][1] * alpha; p0[0] = o0; p0[1] = o1;
;                     if (gnext) { sq += (o0[0] * o0[0] + o0[1] * o0[1]) + (o0[2] * o0[2] + o0[3] * o0[3]) + (o1[0] * o1[0] + o1[1] * o1[1]) + (o1[2] * o1[2] + o1[3] * o1[3]);
;                         const f32x4 y0 = o0 * gv[bj][0], y1 = o1 * gv[bj][1];
;                         u32x4 w; w.x = cvt_pk_bf16(y0[0], y0[1]); w.y = cvt_pk_bf16(y0[2], y0[3]); w.z = cvt_pk_bf16(y1[0], y1[1]); w.w = cvt_pk_bf16(y1[2], y1[3]);
;                         *(u32x4*)(XNo + (size_t)row * DM + col0 + bj * HALF) = w; } }
;                 if (gnext) { sq += shfl_xor_l(sq, 16, lane); sq += shfl_xor_l(sq, 32, lane); if (fq == 0) part[wc * 256 + ai * HALF + wr * 64 + m * 16 + fr] = sq; }
.LBB0_1192:
	v_or_b32_e32 v98, 48, v146
	v_ashrrev_i32_e32 v99, 31, v98
	s_waitcnt lgkmcnt(0)
	v_lshlrev_b64 v[96:97], 12, v[98:99]
	v_lshl_add_u64 v[96:97], v[144:145], 0, v[96:97]
	global_load_dwordx4 v[178:181], v[96:97], off
	global_load_dwordx4 v[182:185], v[96:97], off offset:16
	global_load_dwordx4 v[186:189], v[96:97], off offset:512
	global_load_dwordx4 v[190:193], v[96:97], off offset:528
	s_mov_b64 s[6:7], -1
	s_and_b64 vcc, exec, s[14:15]
	s_waitcnt vmcnt(0) lgkmcnt(0)
	s_nop 1
	v_mov_b64_e32 v[100:101], v[178:179]
	v_mov_b64_e32 v[102:103], v[180:181]
	v_pk_fma_f32 v[94:95], v[94:95], 0.5, v[102:103] op_sel_hi:[1,0,1]
	v_pk_fma_f32 v[92:93], v[92:93], 0.5, v[100:101] op_sel_hi:[1,0,1]
	s_nop 1
	v_mov_b64_e32 v[100:101], v[182:183]
	v_mov_b64_e32 v[102:103], v[184:185]
	s_waitcnt lgkmcnt(0)
	v_pk_fma_f32 v[90:91], v[90:91], 0.5, v[102:103] op_sel_hi:[1,0,1]
	v_pk_fma_f32 v[88:89], v[88:89], 0.5, v[100:101] op_sel_hi:[1,0,1]
	global_store_dwordx4 v[96:97], v[92:95], off
	global_store_dwordx4 v[96:97], v[88:91], off offset:16
	s_cbranch_vccz .LBB0_1194
	s_nop 1
	v_mov_b64_e32 v[100:101], v[186:187]
	v_mov_b64_e32 v[102:103], v[188:189]
	s_nop 1
	v_mov_b64_e32 v[104:105], v[190:191]
	v_mov_b64_e32 v[106:107], v[192:193]
	s_mov_b64 s[6:7], 0
	s_waitcnt lgkmcnt(0)
	v_pk_fma_f32 v[102:103], v[86:87], 0.5, v[102:103] op_sel_hi:[1,0,1]
	v_pk_fma_f32 v[100:101], v[84:85], 0.5, v[100:101] op_sel_hi:[1,0,1]
	v_pk_fma_f32 v[106:107], v[82:83], 0.5, v[106:107] op_sel_hi:[1,0,1]
	v_pk_fma_f32 v[104:105], v[80:81], 0.5, v[104:105] op_sel_hi:[1,0,1]
	global_store_dwordx4 v[96:97], v[100:103], off offset:512
	global_store_dwordx4 v[96:97], v[104:107], off offset:528
.LBB0_1194:
	s_andn2_b64 vcc, exec, s[6:7]
	s_cbranch_vccnz .LBB0_1198
	v_mul_f32_e32 v100, v93, v93
	v_mul_f32_e32 v101, v95, v95
	v_fmac_f32_e32 v100, v92, v92
	v_fmac_f32_e32 v101, v94, v94
	v_add_f32_e32 v100, v100, v101
	v_mul_f32_e32 v101, v89, v89
	v_fmac_f32_e32 v101, v88, v88
	v_add_f32_e32 v100, v100, v101
	v_mul_f32_e32 v101, v91, v91
	v_fmac_f32_e32 v101, v90, v90
	v_lshlrev_b64 v[98:99], 10, v[98:99]
	v_add_f32_e32 v102, v101, v100
	v_pk_mul_f32 v[94:95], v[54:55], v[94:95]
	v_pk_mul_f32 v[92:93], v[52:53], v[92:93]
	v_pk_mul_f32 v[100:101], v[50:51], v[90:91]
	v_pk_mul_f32 v[90:91], v[48:49], v[88:89]
	v_lshl_add_u64 v[98:99], v[98:99], 1, v[148:149]
	v_cvt_pk_bf16_f32 v88, v92, v93
	v_cvt_pk_bf16_f32 v89, v94, v95
	v_cvt_pk_bf16_f32 v90, v90, v91
	v_cvt_pk_bf16_f32 v91, v100, v101
	global_store_dwordx4 v[98:99], v[88:91], off
	s_nop 1
	v_mov_b64_e32 v[88:89], v[186:187]
	v_mov_b64_e32 v[90:91], v[188:189]
	s_waitcnt lgkmcnt(0)
	v_pk_fma_f32 v[86:87], v[86:87], 0.5, v[90:91] op_sel_hi:[1,0,1]
	v_pk_fma_f32 v[84:85], v[84:85], 0.5, v[88:89] op_sel_hi:[1,0,1]
	s_nop 1
	v_mov_b64_e32 v[88:89], v[190:191]
	v_mov_b64_e32 v[90:91], v[192:193]
	s_waitcnt lgkmcnt(0)
	v_pk_fma_f32 v[80:81], v[80:81], 0.5, v[88:89] op_sel_hi:[1,0,1]
	v_mul_f32_e32 v88, v85, v85
	v_mul_f32_e32 v89, v87, v87
	v_fmac_f32_e32 v88, v84, v84
	v_fmac_f32_e32 v89, v86, v86
	v_add_f32_e32 v88, v88, v89
	v_mul_f32_e32 v89, v81, v81
	v_pk_fma_f32 v[82:83], v[82:83], 0.5, v[90:91] op_sel_hi:[1,0,1]
	v_fmac_f32_e32 v89, v80, v80
	v_add_f32_e32 v88, v88, v89
	v_mul_f32_e32 v89, v83, v83
	v_fmac_f32_e32 v89, v82, v82
	v_add_f32_e32 v88, v89, v88
	global_store_dwordx4 v[96:97], v[84:87], off offset:512
	global_store_dwordx4 v[96:97], v[80:83], off offset:528
	v_add_f32_e32 v90, v102, v88
	v_pk_mul_f32 v[86:87], v[42:43], v[86:87]
	v_pk_mul_f32 v[84:85], v[40:41], v[84:85]
	v_pk_mul_f32 v[88:89], v[34:35], v[82:83]
	v_pk_mul_f32 v[82:83], v[32:33], v[80:81]
	v_cvt_pk_bf16_f32 v80, v84, v85
	v_cvt_pk_bf16_f32 v81, v86, v87
	v_cvt_pk_bf16_f32 v82, v82, v83
	v_cvt_pk_bf16_f32 v83, v88, v89
	global_store_dwordx4 v[98:99], v[80:83], off offset:256
	ds_bpermute_b32 v80, v162, v90
	s_waitcnt lgkmcnt(0)
	v_add_f32_e32 v80, v90, v80
	ds_bpermute_b32 v81, v161, v80
	s_and_saveexec_b64 s[6:7], s[44:45]
	s_cbranch_execz .LBB0_1197
	s_waitcnt lgkmcnt(0)
	v_add_f32_e32 v80, v80, v81
	ds_write_b32 v160, v80 offset:192

; __device__ __forceinline__ unsigned cvt_pk_bf16(float lo, float hi) { f32x2 v = {lo, hi}; bf16x2_t_ b = __builtin_convertvector(v, bf16x2_t_); return __builtin_bit_cast(unsigned, b); }
; __device__ __forceinline__ float shfl_xor_l(float v, int o, int lane) { return __int_as_float(__builtin_amdgcn_ds_bpermute((lane ^ o) << 2, __float_as_int(v))); }
;     __device__ __forceinline__ void operator()(const Acc& acc, const Unit& u, int wr, int wc, int fr, int fq) const {
;     ...
;             for (int m = 0; m < 4; ++m) { const int row = row0 + ai * HALF + m * 16; float* rowp = X + (size_t)row * DM + col0; float sq = 0.f;
; #pragma unroll
;                 for (int bj = 0; bj < 2; ++bj) { f32x4* p0 = (f32x4*)(rowp + bj * HALF); const f32x4* r0 = (const f32x4*)(R + (size_t)row * DM + col0 + bj * HALF); const f32x4 o0 = r0[0] + acc[ai][bj][m][0] * alpha, o1 = r0[1] + acc[ai][bj][m][1] * alpha; p0[0] = o0; p0[1] = o1;
;                     if (gnext) { sq += (o0[0] * o0[0] + o0[1] * o0[1]) + (o0[2] * o0[2] + o0[3] * o0[3]) + (o1[0] * o1[0] + o1[1] * o1[1]) + (o1[2] * o1[2] + o1[3] * o1[3]);
;                         const f32x4 y0 = o0 * gv[bj][0], y1 = o1 * gv[bj][1];
;                         u32x4 w; w.x = cvt_pk_bf16(y0[0], y0[1]); w.y = cvt_pk_bf16(y0[2], y0[3]); w.z = cvt_pk_bf16(y1[0], y1[1]); w.w = cvt_pk_bf16(y1[2], y1[3]);
;                         *(u32x4*)(XNo + (size_t)row * DM + col0 + bj * HALF) = w; } }
;                 if (gnext) { sq += shfl_xor_l(sq, 16, lane); sq += shfl_xor_l(sq, 32, lane); if (fq == 0) part[wc * 256 + ai * HALF + wr * 64 + m * 16 + fr] = sq; }
.LBB0_1198:
	v_add_u32_e32 v82, 0x80, v146
	v_ashrrev_i32_e32 v83, 31, v82
	s_waitcnt lgkmcnt(0)
	v_lshlrev_b64 v[80:81], 12, v[82:83]
	v_lshl_add_u64 v[80:81], v[144:145], 0, v[80:81]
	global_load_dwordx4 v[178:181], v[80:81], off
	global_load_dwordx4 v[182:185], v[80:81], off offset:16
	global_load_dwordx4 v[186:189], v[80:81], off offset:512
	global_load_dwordx4 v[190:193], v[80:81], off offset:528
	s_mov_b64 s[6:7], -1
	s_and_b64 vcc, exec, s[14:15]
	s_waitcnt vmcnt(0) lgkmcnt(0)
	s_nop 1
	v_mov_b64_e32 v[84:85], v[178:179]
	v_mov_b64_e32 v[86:87], v[180:181]
	v_pk_fma_f32 v[78:79], v[78:79], 0.5, v[86:87] op_sel_hi:[1,0,1]
	v_pk_fma_f32 v[76:77], v[76:77], 0.5, v[84:85] op_sel_hi:[1,0,1]
	s_nop 1
	v_mov_b64_e32 v[84:85], v[182:183]
	v_mov_b64_e32 v[86:87], v[184:185]
	s_waitcnt lgkmcnt(0)
	v_pk_fma_f32 v[74:75], v[74:75], 0.5, v[86:87] op_sel_hi:[1,0,1]
	v_pk_fma_f32 v[72:73], v[72:73], 0.5, v[84:85] op_sel_hi:[1,0,1]
	global_store_dwordx4 v[80:81], v[76:79], off
	global_store_dwordx4 v[80:81], v[72:75], off offset:16
	s_cbranch_vccz .LBB0_1200
	s_nop 1
	v_mov_b64_e32 v[84:85], v[186:187]
	v_mov_b64_e32 v[86:87], v[188:189]
	s_nop 1
	v_mov_b64_e32 v[88:89], v[190:191]
	v_mov_b64_e32 v[90:91], v[192:193]
	s_mov_b64 s[6:7], 0
	s_waitcnt lgkmcnt(0)
	v_pk_fma_f32 v[86:87], v[70:71], 0.5, v[86:87] op_sel_hi:[1,0,1]
	v_pk_fma_f32 v[84:85], v[68:69], 0.5, v[84:85] op_sel_hi:[1,0,1]
	v_pk_fma_f32 v[90:91], v[66:67], 0.5, v[90:91] op_sel_hi:[1,0,1]
	v_pk_fma_f32 v[88:89], v[64:65], 0.5, v[88:89] op_sel_hi:[1,0,1]
	global_store_dwordx4 v[80:81], v[84:87], off offset:512
	global_store_dwordx4 v[80:81], v[88:91], off offset:528
.LBB0_1200:
	s_andn2_b64 vcc, exec, s[6:7]
	s_cbranch_vccnz .LBB0_1204
	v_mul_f32_e32 v84, v77, v77
	v_mul_f32_e32 v85, v79, v79
	v_fmac_f32_e32 v84, v76, v76
	v_fmac_f32_e32 v85, v78, v78
	v_add_f32_e32 v84, v84, v85
	v_mul_f32_e32 v85, v73, v73
	v_fmac_f32_e32 v85, v72, v72
	v_add_f32_e32 v84, v84, v85
	v_mul_f32_e32 v85, v75, v75
	v_fmac_f32_e32 v85, v74, v74
	v_lshlrev_b64 v[82:83], 10, v[82:83]
	v_add_f32_e32 v86, v85, v84
	v_pk_mul_f32 v[78:79], v[54:55], v[78:79]
	v_pk_mul_f32 v[76:77], v[52:53], v[76:77]
	v_pk_mul_f32 v[84:85], v[50:51], v[74:75]
	v_pk_mul_f32 v[74:75], v[48:49], v[72:73]
	v_lshl_add_u64 v[82:83], v[82:83], 1, v[148:149]
	v_cvt_pk_bf16_f32 v72, v76, v77
	v_cvt_pk_bf16_f32 v73, v78, v79
	v_cvt_pk_bf16_f32 v74, v74, v75
	v_cvt_pk_bf16_f32 v75, v84, v85
	global_store_dwordx4 v[82:83], v[72:75], off
	s_nop 1
	v_mov_b64_e32 v[72:73], v[186:187]
	v_mov_b64_e32 v[74:75], v[188:189]
	s_waitcnt lgkmcnt(0)
	v_pk_fma_f32 v[70:71], v[70:71], 0.5, v[74:75] op_sel_hi:[1,0,1]
	v_pk_fma_f32 v[68:69], v[68:69], 0.5, v[72:73] op_sel_hi:[1,0,1]
	s_nop 1
	v_mov_b64_e32 v[72:73], v[190:191]
	v_mov_b64_e32 v[74:75], v[192:193]
	s_waitcnt lgkmcnt(0)
	v_pk_fma_f32 v[64:65], v[64:65], 0.5, v[72:73] op_sel_hi:[1,0,1]
	v_mul_f32_e32 v72, v69, v69
	v_mul_f32_e32 v73, v71, v71
	v_fmac_f32_e32 v72, v68, v68
	v_fmac_f32_e32 v73, v70, v70
	v_add_f32_e32 v72, v72, v73
	v_mul_f32_e32 v73, v65, v65
	v_pk_fma_f32 v[66:67], v[66:67], 0.5, v[74:75] op_sel_hi:[1,0,1]
	v_fmac_f32_e32 v73, v64, v64
	v_add_f32_e32 v72, v72, v73
	v_mul_f32_e32 v73, v67, v67
	v_fmac_f32_e32 v73, v66, v66
	v_add_f32_e32 v72, v73, v72
	global_store_dwordx4 v[80:81], v[68:71], off offset:512
	global_store_dwordx4 v[80:81], v[64:67], off offset:528
	v_add_f32_e32 v74, v86, v72
	v_pk_mul_f32 v[70:71], v[42:43], v[70:71]
	v_pk_mul_f32 v[68:69], v[40:41], v[68:69]
	v_pk_mul_f32 v[72:73], v[34:35], v[66:67]
	v_pk_mul_f32 v[66:67], v[32:33], v[64:65]
	v_cvt_pk_bf16_f32 v64, v68, v69
	v_cvt_pk_bf16_f32 v65, v70, v71
	v_cvt_pk_bf16_f32 v66, v66, v67
	v_cvt_pk_bf16_f32 v67, v72, v73
	global_store_dwordx4 v[82:83], v[64:67], off offset:256
	ds_bpermute_b32 v64, v162, v74
	s_waitcnt lgkmcnt(0)
	v_add_f32_e32 v64, v74, v64
	ds_bpermute_b32 v65, v161, v64
	s_and_saveexec_b64 s[6:7], s[44:45]
	s_cbranch_execz .LBB0_1203
	s_waitcnt lgkmcnt(0)
	v_add_f32_e32 v64, v64, v65
	ds_write_b32 v160, v64 offset:512

; __device__ __forceinline__ unsigned cvt_pk_bf16(float lo, float hi) { f32x2 v = {lo, hi}; bf16x2_t_ b = __builtin_convertvector(v, bf16x2_t_); return __builtin_bit_cast(unsigned, b); }
; __device__ __forceinline__ float shfl_xor_l(float v, int o, int lane) { return __int_as_float(__builtin_amdgcn_ds_bpermute((lane ^ o) << 2, __float_as_int(v))); }
;     __device__ __forceinline__ void operator()(const Acc& acc, const Unit& u, int wr, int wc, int fr, int fq) const {
;     ...
;             for (int m = 0; m < 4; ++m) { const int row = row0 + ai * HALF + m * 16; float* rowp = X + (size_t)row * DM + col0; float sq = 0.f;
; #pragma unroll
;                 for (int bj = 0; bj < 2; ++bj) { f32x4* p0 = (f32x4*)(rowp + bj * HALF); const f32x4* r0 = (const f32x4*)(R + (size_t)row * DM + col0 + bj * HALF); const f32x4 o0 = r0[0] + acc[ai][bj][m][0] * alpha, o1 = r0[1] + acc[ai][bj][m][1] * alpha; p0[0] = o0; p0[1] = o1;
;                     if (gnext) { sq += (o0[0] * o0[0] + o0[1] * o0[1]) + (o0[2] * o0[2] + o0[3] * o0[3]) + (o1[0] * o1[0] + o1[1] * o1[1]) + (o1[2] * o1[2] + o1[3] * o1[3]);
;                         const f32x4 y0 = o0 * gv[bj][0], y1 = o1 * gv[bj][1];
;                         u32x4 w; w.x = cvt_pk_bf16(y0[0], y0[1]); w.y = cvt_pk_bf16(y0[2], y0[3]); w.z = cvt_pk_bf16(y1[0], y1[1]); w.w = cvt_pk_bf16(y1[2], y1[3]);
;                         *(u32x4*)(XNo + (size_t)row * DM + col0 + bj * HALF) = w; } }
;                 if (gnext) { sq += shfl_xor_l(sq, 16, lane); sq += shfl_xor_l(sq, 32, lane); if (fq == 0) part[wc * 256 + ai * HALF + wr * 64 + m * 16 + fr] = sq; }
.LBB0_1204:
	v_add_u32_e32 v66, 0x90, v146
	v_ashrrev_i32_e32 v67, 31, v66
	s_waitcnt lgkmcnt(0)
	v_lshlrev_b64 v[64:65], 12, v[66:67]
	v_lshl_add_u64 v[64:65], v[144:145], 0, v[64:65]
	global_load_dwordx4 v[178:181], v[64:65], off
	global_load_dwordx4 v[182:185], v[64:65], off offset:16
	global_load_dwordx4 v[186:189], v[64:65], off offset:512
	global_load_dwordx4 v[190:193], v[64:65], off offset:528
	s_mov_b64 s[6:7], -1
	s_and_b64 vcc, exec, s[14:15]
	s_waitcnt vmcnt(0) lgkmcnt(0)
	s_nop 1
	v_mov_b64_e32 v[68:69], v[178:179]
	v_mov_b64_e32 v[70:71], v[180:181]
	v_pk_fma_f32 v[62:63], v[62:63], 0.5, v[70:71] op_sel_hi:[1,0,1]
	v_pk_fma_f32 v[60:61], v[60:61], 0.5, v[68:69] op_sel_hi:[1,0,1]
	s_nop 1
	v_mov_b64_e32 v[68:69], v[182:183]
	v_mov_b64_e32 v[70:71], v[184:185]
	s_waitcnt lgkmcnt(0)
	v_pk_fma_f32 v[58:59], v[58:59], 0.5, v[70:71] op_sel_hi:[1,0,1]
	v_pk_fma_f32 v[56:57], v[56:57], 0.5, v[68:69] op_sel_hi:[1,0,1]
	global_store_dwordx4 v[64:65], v[60:63], off
	global_store_dwordx4 v[64:65], v[56:59], off offset:16
	s_cbranch_vccz .LBB0_1206
	s_nop 1
	v_mov_b64_e32 v[68:69], v[186:187]
	v_mov_b64_e32 v[70:71], v[188:189]
	s_nop 1
	v_mov_b64_e32 v[72:73], v[190:191]
	v_mov_b64_e32 v[74:75], v[192:193]
	s_mov_b64 s[6:7], 0
	s_waitcnt lgkmcnt(0)
	v_pk_fma_f32 v[70:71], v[46:47], 0.5, v[70:71] op_sel_hi:[1,0,1]
	v_pk_fma_f32 v[68:69], v[44:45], 0.5, v[68:69] op_sel_hi:[1,0,1]
	v_pk_fma_f32 v[74:75], v[38:39], 0.5, v[74:75] op_sel_hi:[1,0,1]
	v_pk_fma_f32 v[72:73], v[36:37], 0.5, v[72:73] op_sel_hi:[1,0,1]
	global_store_dwordx4 v[64:65], v[68:71], off offset:512
	global_store_dwordx4 v[64:65], v[72:75], off offset:528
.LBB0_1206:
	s_andn2_b64 vcc, exec, s[6:7]
	s_cbranch_vccnz .LBB0_1210
	v_mul_f32_e32 v68, v61, v61
	v_mul_f32_e32 v69, v63, v63
	v_fmac_f32_e32 v68, v60, v60
	v_fmac_f32_e32 v69, v62, v62
	v_add_f32_e32 v68, v68, v69
	v_mul_f32_e32 v69, v57, v57
	v_fmac_f32_e32 v69, v56, v56
	v_add_f32_e32 v68, v68, v69
	v_mul_f32_e32 v69, v59, v59
	v_fmac_f32_e32 v69, v58, v58
	v_lshlrev_b64 v[66:67], 10, v[66:67]
	v_add_f32_e32 v70, v69, v68
	v_pk_mul_f32 v[62:63], v[54:55], v[62:63]
	v_pk_mul_f32 v[60:61], v[52:53], v[60:61]
	v_pk_mul_f32 v[68:69], v[50:51], v[58:59]
	v_pk_mul_f32 v[58:59], v[48:49], v[56:57]
	v_lshl_add_u64 v[66:67], v[66:67], 1, v[148:149]
	v_cvt_pk_bf16_f32 v56, v60, v61
	v_cvt_pk_bf16_f32 v57, v62, v63
	v_cvt_pk_bf16_f32 v58, v58, v59
	v_cvt_pk_bf16_f32 v59, v68, v69
	global_store_dwordx4 v[66:67], v[56:59], off
	s_nop 1
	v_mov_b64_e32 v[56:57], v[186:187]
	v_mov_b64_e32 v[58:59], v[188:189]
	s_waitcnt lgkmcnt(0)
	v_pk_fma_f32 v[46:47], v[46:47], 0.5, v[58:59] op_sel_hi:[1,0,1]
	v_pk_fma_f32 v[44:45], v[44:45], 0.5, v[56:57] op_sel_hi:[1,0,1]
	s_nop 1
	v_mov_b64_e32 v[56:57], v[190:191]
	v_mov_b64_e32 v[58:59], v[192:193]
	s_waitcnt lgkmcnt(0)
	v_pk_fma_f32 v[36:37], v[36:37], 0.5, v[56:57] op_sel_hi:[1,0,1]
	v_mul_f32_e32 v56, v45, v45
	v_mul_f32_e32 v57, v47, v47
	v_fmac_f32_e32 v56, v44, v44
	v_fmac_f32_e32 v57, v46, v46
	v_add_f32_e32 v56, v56, v57
	v_mul_f32_e32 v57, v37, v37
	v_pk_fma_f32 v[38:39], v[38:39], 0.5, v[58:59] op_sel_hi:[1,0,1]
	v_fmac_f32_e32 v57, v36, v36
	v_add_f32_e32 v56, v56, v57
	v_mul_f32_e32 v57, v39, v39
	v_fmac_f32_e32 v57, v38, v38
	v_add_f32_e32 v56, v57, v56
	global_store_dwordx4 v[64:65], v[44:47], off offset:512
	global_store_dwordx4 v[64:65], v[36:39], off offset:528
	v_add_f32_e32 v58, v70, v56
	v_pk_mul_f32 v[46:47], v[42:43], v[46:47]
	v_pk_mul_f32 v[44:45], v[40:41], v[44:45]
	v_pk_mul_f32 v[56:57], v[34:35], v[38:39]
	v_pk_mul_f32 v[38:39], v[32:33], v[36:37]
	v_cvt_pk_bf16_f32 v36, v44, v45
	v_cvt_pk_bf16_f32 v37, v46, v47
	v_cvt_pk_bf16_f32 v38, v38, v39
	v_cvt_pk_bf16_f32 v39, v56, v57
	global_store_dwordx4 v[66:67], v[36:39], off offset:256
	ds_bpermute_b32 v36, v162, v58
	s_waitcnt lgkmcnt(0)
	v_add_f32_e32 v36, v58, v36
	ds_bpermute_b32 v37, v161, v36
	s_and_saveexec_b64 s[6:7], s[44:45]
	s_cbranch_execz .LBB0_1209
	s_waitcnt lgkmcnt(0)
	v_add_f32_e32 v36, v36, v37
	ds_write_b32 v160, v36 offset:576

; __device__ __forceinline__ unsigned cvt_pk_bf16(float lo, float hi) { f32x2 v = {lo, hi}; bf16x2_t_ b = __builtin_convertvector(v, bf16x2_t_); return __builtin_bit_cast(unsigned, b); }
; __device__ __forceinline__ float shfl_xor_l(float v, int o, int lane) { return __int_as_float(__builtin_amdgcn_ds_bpermute((lane ^ o) << 2, __float_as_int(v))); }
;     __device__ __forceinline__ void operator()(const Acc& acc, const Unit& u, int wr, int wc, int fr, int fq) const {
;     ...
;             for (int m = 0; m < 4; ++m) { const int row = row0 + ai * HALF + m * 16; float* rowp = X + (size_t)row * DM + col0; float sq = 0.f;
; #pragma unroll
;                 for (int bj = 0; bj < 2; ++bj) { f32x4* p0 = (f32x4*)(rowp + bj * HALF); const f32x4* r0 = (const f32x4*)(R + (size_t)row * DM + col0 + bj * HALF); const f32x4 o0 = r0[0] + acc[ai][bj][m][0] * alpha, o1 = r0[1] + acc[ai][bj][m][1] * alpha; p0[0] = o0; p0[1] = o1;
;                     if (gnext) { sq += (o0[0] * o0[0] + o0[1] * o0[1]) + (o0[2] * o0[2] + o0[3] * o0[3]) + (o1[0] * o1[0] + o1[1] * o1[1]) + (o1[2] * o1[2] + o1[3] * o1[3]);
;                         const f32x4 y0 = o0 * gv[bj][0], y1 = o1 * gv[bj][1];
;                         u32x4 w; w.x = cvt_pk_bf16(y0[0], y0[1]); w.y = cvt_pk_bf16(y0[2], y0[3]); w.z = cvt_pk_bf16(y1[0], y1[1]); w.w = cvt_pk_bf16(y1[2], y1[3]);
;                         *(u32x4*)(XNo + (size_t)row * DM + col0 + bj * HALF) = w; } }
;                 if (gnext) { sq += shfl_xor_l(sq, 16, lane); sq += shfl_xor_l(sq, 32, lane); if (fq == 0) part[wc * 256 + ai * HALF + wr * 64 + m * 16 + fr] = sq; }
.LBB0_1210:
	v_add_u32_e32 v38, 0xa0, v146
	v_ashrrev_i32_e32 v39, 31, v38
	s_waitcnt lgkmcnt(0)
	v_lshlrev_b64 v[36:37], 12, v[38:39]
	v_lshl_add_u64 v[36:37], v[144:145], 0, v[36:37]
	global_load_dwordx4 v[178:181], v[36:37], off
	global_load_dwordx4 v[182:185], v[36:37], off offset:16
	global_load_dwordx4 v[186:189], v[36:37], off offset:512
	global_load_dwordx4 v[190:193], v[36:37], off offset:528
	s_mov_b64 s[6:7], -1
	s_and_b64 vcc, exec, s[14:15]
	s_waitcnt vmcnt(0) lgkmcnt(0)
	s_nop 1
	v_mov_b64_e32 v[44:45], v[178:179]
	v_mov_b64_e32 v[46:47], v[180:181]
	v_pk_fma_f32 v[30:31], v[30:31], 0.5, v[46:47] op_sel_hi:[1,0,1]
	v_pk_fma_f32 v[28:29], v[28:29], 0.5, v[44:45] op_sel_hi:[1,0,1]
	s_nop 1
	v_mov_b64_e32 v[44:45], v[182:183]
	v_mov_b64_e32 v[46:47], v[184:185]
	s_waitcnt lgkmcnt(0)
	v_pk_fma_f32 v[26:27], v[26:27], 0.5, v[46:47] op_sel_hi:[1,0,1]
	v_pk_fma_f32 v[24:25], v[24:25], 0.5, v[44:45] op_sel_hi:[1,0,1]
	global_store_dwordx4 v[36:37], v[28:31], off
	global_store_dwordx4 v[36:37], v[24:27], off offset:16
	s_cbranch_vccz .LBB0_1212
	s_nop 1
	v_mov_b64_e32 v[44:45], v[186:187]
	v_mov_b64_e32 v[46:47], v[188:189]
	s_nop 1
	v_mov_b64_e32 v[56:57], v[190:191]
	v_mov_b64_e32 v[58:59], v[192:193]
	s_mov_b64 s[6:7], 0
	s_waitcnt lgkmcnt(0)
	v_pk_fma_f32 v[46:47], v[22:23], 0.5, v[46:47] op_sel_hi:[1,0,1]
	v_pk_fma_f32 v[44:45], v[20:21], 0.5, v[44:45] op_sel_hi:[1,0,1]
	v_pk_fma_f32 v[58:59], v[18:19], 0.5, v[58:59] op_sel_hi:[1,0,1]
	v_pk_fma_f32 v[56:57], v[16:17], 0.5, v[56:57] op_sel_hi:[1,0,1]
	global_store_dwordx4 v[36:37], v[44:47], off offset:512
	global_store_dwordx4 v[36:37], v[56:59], off offset:528
.LBB0_1212:
	s_andn2_b64 vcc, exec, s[6:7]
	s_cbranch_vccnz .LBB0_1216
	v_mul_f32_e32 v44, v29, v29
	v_mul_f32_e32 v45, v31, v31
	v_fmac_f32_e32 v44, v28, v28
	v_fmac_f32_e32 v45, v30, v30
	v_add_f32_e32 v44, v44, v45
	v_mul_f32_e32 v45, v25, v25
	v_fmac_f32_e32 v45, v24, v24
	v_add_f32_e32 v44, v44, v45
	v_mul_f32_e32 v45, v27, v27
	v_fmac_f32_e32 v45, v26, v26
	v_lshlrev_b64 v[38:39], 10, v[38:39]
	v_add_f32_e32 v46, v45, v44
	v_pk_mul_f32 v[30:31], v[54:55], v[30:31]
	v_pk_mul_f32 v[28:29], v[52:53], v[28:29]
	v_pk_mul_f32 v[44:45], v[50:51], v[26:27]
	v_pk_mul_f32 v[26:27], v[48:49], v[24:25]
	v_lshl_add_u64 v[38:39], v[38:39], 1, v[148:149]
	v_cvt_pk_bf16_f32 v24, v28, v29
	v_cvt_pk_bf16_f32 v25, v30, v31
	v_cvt_pk_bf16_f32 v26, v26, v27
	v_cvt_pk_bf16_f32 v27, v44, v45
	global_store_dwordx4 v[38:39], v[24:27], off
	s_nop 1
	v_mov_b64_e32 v[24:25], v[186:187]
	v_mov_b64_e32 v[26:27], v[188:189]
	s_waitcnt lgkmcnt(0)
	v_pk_fma_f32 v[22:23], v[22:23], 0.5, v[26:27] op_sel_hi:[1,0,1]
	v_pk_fma_f32 v[20:21], v[20:21], 0.5, v[24:25] op_sel_hi:[1,0,1]
	s_nop 1
	v_mov_b64_e32 v[24:25], v[190:191]
	v_mov_b64_e32 v[26:27], v[192:193]
	s_waitcnt lgkmcnt(0)
	v_pk_fma_f32 v[16:17], v[16:17], 0.5, v[24:25] op_sel_hi:[1,0,1]
	v_mul_f32_e32 v24, v21, v21
	v_mul_f32_e32 v25, v23, v23
	v_fmac_f32_e32 v24, v20, v20
	v_fmac_f32_e32 v25, v22, v22
	v_add_f32_e32 v24, v24, v25
	v_mul_f32_e32 v25, v17, v17
	v_pk_fma_f32 v[18:19], v[18:19], 0.5, v[26:27] op_sel_hi:[1,0,1]
	v_fmac_f32_e32 v25, v16, v16
	v_add_f32_e32 v24, v24, v25
	v_mul_f32_e32 v25, v19, v19
	v_fmac_f32_e32 v25, v18, v18
	v_add_f32_e32 v24, v25, v24
	global_store_dwordx4 v[36:37], v[20:23], off offset:512
	global_store_dwordx4 v[36:37], v[16:19], off offset:528
	v_add_f32_e32 v26, v46, v24
	v_pk_mul_f32 v[22:23], v[42:43], v[22:23]
	v_pk_mul_f32 v[20:21], v[40:41], v[20:21]
	v_pk_mul_f32 v[24:25], v[34:35], v[18:19]
	v_pk_mul_f32 v[18:19], v[32:33], v[16:17]
	v_cvt_pk_bf16_f32 v16, v20, v21
	v_cvt_pk_bf16_f32 v17, v22, v23
	v_cvt_pk_bf16_f32 v18, v18, v19
	v_cvt_pk_bf16_f32 v19, v24, v25
	global_store_dwordx4 v[38:39], v[16:19], off offset:256
	ds_bpermute_b32 v16, v162, v26
	s_waitcnt lgkmcnt(0)
	v_add_f32_e32 v16, v26, v16
	ds_bpermute_b32 v17, v161, v16
	s_and_saveexec_b64 s[6:7], s[44:45]
	s_cbranch_execz .LBB0_1215
	s_waitcnt lgkmcnt(0)
	v_add_f32_e32 v16, v16, v17
	ds_write_b32 v160, v16 offset:640

; __device__ __forceinline__ unsigned cvt_pk_bf16(float lo, float hi) { f32x2 v = {lo, hi}; bf16x2_t_ b = __builtin_convertvector(v, bf16x2_t_); return __builtin_bit_cast(unsigned, b); }
; __device__ __forceinline__ float shfl_xor_l(float v, int o, int lane) { return __int_as_float(__builtin_amdgcn_ds_bpermute((lane ^ o) << 2, __float_as_int(v))); }
;     __device__ __forceinline__ void operator()(const Acc& acc, const Unit& u, int wr, int wc, int fr, int fq) const {
;     ...
;             for (int m = 0; m < 4; ++m) { const int row = row0 + ai * HALF + m * 16; float* rowp = X + (size_t)row * DM + col0; float sq = 0.f;
; #pragma unroll
;                 for (int bj = 0; bj < 2; ++bj) { f32x4* p0 = (f32x4*)(rowp + bj * HALF); const f32x4* r0 = (const f32x4*)(R + (size_t)row * DM + col0 + bj * HALF); const f32x4 o0 = r0[0] + acc[ai][bj][m][0] * alpha, o1 = r0[1] + acc[ai][bj][m][1] * alpha; p0[0] = o0; p0[1] = o1;
;                     if (gnext) { sq += (o0[0] * o0[0] + o0[1] * o0[1]) + (o0[2] * o0[2] + o0[3] * o0[3]) + (o1[0] * o1[0] + o1[1] * o1[1]) + (o1[2] * o1[2] + o1[3] * o1[3]);
;                         const f32x4 y0 = o0 * gv[bj][0], y1 = o1 * gv[bj][1];
;                         u32x4 w; w.x = cvt_pk_bf16(y0[0], y0[1]); w.y = cvt_pk_bf16(y0[2], y0[3]); w.z = cvt_pk_bf16(y1[0], y1[1]); w.w = cvt_pk_bf16(y1[2], y1[3]);
;                         *(u32x4*)(XNo + (size_t)row * DM + col0 + bj * HALF) = w; } }
;                 if (gnext) { sq += shfl_xor_l(sq, 16, lane); sq += shfl_xor_l(sq, 32, lane); if (fq == 0) part[wc * 256 + ai * HALF + wr * 64 + m * 16 + fr] = sq; }
.LBB0_1216:
	v_add_u32_e32 v18, 0xb0, v146
	v_ashrrev_i32_e32 v19, 31, v18
	s_waitcnt lgkmcnt(0)
	v_lshlrev_b64 v[16:17], 12, v[18:19]
	v_lshl_add_u64 v[16:17], v[144:145], 0, v[16:17]
	global_load_dwordx4 v[178:181], v[16:17], off
	global_load_dwordx4 v[182:185], v[16:17], off offset:16
	global_load_dwordx4 v[186:189], v[16:17], off offset:512
	global_load_dwordx4 v[190:193], v[16:17], off offset:528
	s_mov_b64 s[6:7], -1
	s_and_b64 vcc, exec, s[14:15]
	s_waitcnt vmcnt(0) lgkmcnt(0)
	s_nop 1
	v_mov_b64_e32 v[20:21], v[178:179]
	v_mov_b64_e32 v[22:23], v[180:181]
	v_pk_fma_f32 v[14:15], v[14:15], 0.5, v[22:23] op_sel_hi:[1,0,1]
	v_pk_fma_f32 v[12:13], v[12:13], 0.5, v[20:21] op_sel_hi:[1,0,1]
	s_nop 1
	v_mov_b64_e32 v[20:21], v[182:183]
	v_mov_b64_e32 v[22:23], v[184:185]
	s_waitcnt lgkmcnt(0)
	v_pk_fma_f32 v[10:11], v[10:11], 0.5, v[22:23] op_sel_hi:[1,0,1]
	v_pk_fma_f32 v[8:9], v[8:9], 0.5, v[20:21] op_sel_hi:[1,0,1]
	global_store_dwordx4 v[16:17], v[12:15], off
	global_store_dwordx4 v[16:17], v[8:11], off offset:16
	s_cbranch_vccz .LBB0_1218
	s_nop 1
	v_mov_b64_e32 v[20:21], v[186:187]
	v_mov_b64_e32 v[22:23], v[188:189]
	s_nop 1
	v_mov_b64_e32 v[24:25], v[190:191]
	v_mov_b64_e32 v[26:27], v[192:193]
	s_mov_b64 s[6:7], 0
	s_waitcnt lgkmcnt(0)
	v_pk_fma_f32 v[22:23], v[6:7], 0.5, v[22:23] op_sel_hi:[1,0,1]
	v_pk_fma_f32 v[20:21], v[4:5], 0.5, v[20:21] op_sel_hi:[1,0,1]
	v_pk_fma_f32 v[26:27], v[2:3], 0.5, v[26:27] op_sel_hi:[1,0,1]
	v_pk_fma_f32 v[24:25], v[0:1], 0.5, v[24:25] op_sel_hi:[1,0,1]
	global_store_dwordx4 v[16:17], v[20:23], off offset:512
	global_store_dwordx4 v[16:17], v[24:27], off offset:528
.LBB0_1218:
	s_andn2_b64 vcc, exec, s[6:7]
	s_cbranch_vccnz .LBB0_1222
	v_lshlrev_b64 v[18:19], 10, v[18:19]
	v_lshl_add_u64 v[26:27], v[18:19], 1, v[148:149]
	v_pk_mul_f32 v[20:21], v[54:55], v[14:15]
	v_pk_mul_f32 v[18:19], v[52:53], v[12:13]
	v_pk_mul_f32 v[22:23], v[50:51], v[10:11]
	v_pk_mul_f32 v[24:25], v[48:49], v[8:9]
	v_cvt_pk_bf16_f32 v18, v18, v19
	v_cvt_pk_bf16_f32 v19, v20, v21
	v_cvt_pk_bf16_f32 v20, v24, v25
	v_cvt_pk_bf16_f32 v21, v22, v23
	global_store_dwordx4 v[26:27], v[18:21], off
	s_nop 1
	v_mov_b64_e32 v[18:19], v[186:187]
	v_mov_b64_e32 v[20:21], v[188:189]
	s_nop 0
	s_nop 1
	v_mov_b64_e32 v[22:23], v[190:191]
	v_mov_b64_e32 v[24:25], v[192:193]
	v_mul_f32_e32 v13, v13, v13
	v_mul_f32_e32 v15, v15, v15
	v_mul_f32_e32 v9, v9, v9
	v_fmac_f32_e32 v13, v12, v12
	v_fmac_f32_e32 v15, v14, v14
	v_mul_f32_e32 v11, v11, v11
	v_fmac_f32_e32 v9, v8, v8
	v_add_f32_e32 v8, v13, v15
	v_fmac_f32_e32 v11, v10, v10
	v_add_f32_e32 v8, v8, v9
	v_add_f32_e32 v8, v11, v8
	s_waitcnt lgkmcnt(0)
	v_pk_fma_f32 v[6:7], v[6:7], 0.5, v[20:21] op_sel_hi:[1,0,1]
	v_pk_fma_f32 v[4:5], v[4:5], 0.5, v[18:19] op_sel_hi:[1,0,1]
	v_pk_fma_f32 v[0:1], v[0:1], 0.5, v[22:23] op_sel_hi:[1,0,1]
	v_mul_f32_e32 v9, v5, v5
	v_mul_f32_e32 v10, v7, v7
	v_pk_fma_f32 v[2:3], v[2:3], 0.5, v[24:25] op_sel_hi:[1,0,1]
	v_mul_f32_e32 v11, v1, v1
	v_fmac_f32_e32 v9, v4, v4
	v_fmac_f32_e32 v10, v6, v6
	v_mul_f32_e32 v12, v3, v3
	v_fmac_f32_e32 v11, v0, v0
	v_add_f32_e32 v9, v9, v10
	v_fmac_f32_e32 v12, v2, v2
	v_add_f32_e32 v9, v9, v11
	v_add_f32_e32 v9, v12, v9
	v_add_f32_e32 v12, v8, v9
	ds_bpermute_b32 v13, v162, v12
	global_store_dwordx4 v[16:17], v[4:7], off offset:512
	global_store_dwordx4 v[16:17], v[0:3], off offset:528
	v_pk_mul_f32 v[10:11], v[32:33], v[0:1]
	v_pk_mul_f32 v[6:7], v[42:43], v[6:7]
	v_pk_mul_f32 v[4:5], v[40:41], v[4:5]
	s_waitcnt lgkmcnt(0)
	v_add_f32_e32 v0, v12, v13
	ds_bpermute_b32 v1, v161, v0
	v_pk_mul_f32 v[8:9], v[34:35], v[2:3]
	v_cvt_pk_bf16_f32 v2, v4, v5
	v_cvt_pk_bf16_f32 v3, v6, v7
	v_cvt_pk_bf16_f32 v4, v10, v11
	v_cvt_pk_bf16_f32 v5, v8, v9
	global_store_dwordx4 v[26:27], v[2:5], off offset:256
	s_and_saveexec_b64 s[6:7], s[44:45]
	s_cbranch_execz .LBB0_1221
	s_waitcnt lgkmcnt(0)
	v_add_f32_e32 v0, v0, v1
	ds_write_b32 v160, v0 offset:704
